# K-loop LDS-DMA balance 4/4/4/4: SA(0,0) stage issued at P3 head, SA(1,0) stage at the next iteration's P1 (kept in P4 for the unit's last K-iteration); waits 8/6/8/6; K=256 loop unchanged
# speedup vs baseline: 1.0159x; 1.0041x over previous
; #define PG8_STAGE(bufoff, gbase, voff) do { _Pragma("unroll") for (int _i = 0; _i < 2; ++_i) \
;         __builtin_amdgcn_global_load_lds((const unsigned*)((const char*)(gbase) + (voff)[_i]), (PG8_LAS unsigned*)(lds + (bufoff) + ldsw + _i * 8192), 16, 0, 0); } while (0)
; #define PG8_LDA(dst, b, h) do { _Pragma("unroll") for (int m = 0; m < 4; ++m) _Pragma("unroll") for (int k = 0; k < 2; ++k) dst[m][k] = *(const PG8_LAS bf16x8*)(lds + PG8_SA(b, h) + aoff + m * 2048 + k * 1024); } while (0)
; #define PG8_LDB(dst, b, h) do { _Pragma("unroll") for (int n = 0; n < 2; ++n) _Pragma("unroll") for (int k = 0; k < 2; ++k) dst[n][k] = *(const PG8_LAS bf16x8*)(lds + PG8_SB(b, h) + boff + n * 2048 + k * 1024); } while (0)
; #define PG8_WAIT_V(n) asm volatile("s_waitcnt vmcnt(" #n ")" ::: "memory")
; #define PG8_WAIT_L(n) asm volatile("s_waitcnt lgkmcnt(" #n ")" ::: "memory")
; #define PG8_BAR __builtin_amdgcn_s_barrier()
; #define PG8_SCHED __builtin_amdgcn_sched_barrier(0)
; template <class Epi, class Sched, bool ALIGN_EPI = false, bool SP2 = false, bool I8 = false>
; __device__ __forceinline__ void gemm_phase(PG8_LAS unsigned char* lds, const Gemm g, const Sched& S, const Epi& E) {
;     ...
;         const bool has_next = S.next(ui + 1, nxt);
;         const char* nA = has_next ? (const char*)g.A + (size_t)nxt.pm * tstep : cA; const char* nB = has_next ? (const char*)g.Bt + (size_t)nxt.pn * tstep : cB;
;         for (int t = 0; t < nt; t += 2) {
;             const bool last = (t == nt - 2);
;             const char* a1 = cA + (size_t)(t + 1) * kstep;
;             const char* a2 = last ? nA : cA + (size_t)(t + 2) * kstep; const char* b2 = last ? nB : cB + (size_t)(t + 2) * kstep;
;             const char* a3 = a2 + kstep; const char* b3 = b2 + kstep;
;             if (last && has_next) S.a_ready(nxt);
;             if constexpr (SP2) {
;             PG8_LDB(B0, 0, 0); PG8_LDB(B1, 0, 1); PG8_SCHED; PG8_LDA(At, 0, 0); PG8_STAGE(PG8_SA(1, 1), a1 + hstep, voffA);
;             PG8_WAIT_V(8); PG8_WAIT_L(0); PG8_BAR; PG8_MMA(0, 0, At, B0); PG8_MMA(0, 1, At, B1); PG8_BAR; PG8_SCHED;
;             PG8_LDA(At, 0, 1); PG8_STAGE(PG8_SB(0, 0), b2, voffB); PG8_STAGE(PG8_SB(0, 1), b2 + hstep, voffB); PG8_STAGE(PG8_SA(0, 0), a2, voffA);
;             PG8_WAIT_V(8); PG8_WAIT_L(0); PG8_BAR; PG8_MMA(1, 0, At, B0); PG8_MMA(1, 1, At, B1); PG8_BAR; PG8_SCHED;
.LBB0_207:
	s_ashr_i32 s19, s18, 31
	s_lshl_b64 s[22:23], s[18:19], 20
	s_add_u32 s22, s28, s22
	s_addc_u32 s23, s34, s23
	s_and_b64 s[24:25], s[6:7], exec
	s_cselect_b32 s19, s23, s27
	s_cselect_b32 s64, s22, s26
	s_ashr_i32 s17, s16, 31
	s_lshl_b64 s[24:25], s[16:17], 20
	s_add_u32 s24, s35, s24
	s_addc_u32 s25, s42, s25
	s_and_b64 s[40:41], s[6:7], exec
	s_cselect_b32 s17, s25, s37
	s_cselect_b32 s65, s24, s36
	s_add_u32 s26, s26, 0x80080
	s_addc_u32 s27, s27, 0
	s_add_u32 s72, s36, 0x100
	s_addc_u32 s73, s37, 0
	s_mov_b32 s76, -2
	s_add_u32 s36, s26, 0xfff80080
	s_addc_u32 s37, s27, -1
	s_add_i32 s50, 0, 0x10000
	s_cmp_eq_u32 s76, 28
	s_cselect_b32 s41, s19, s37
	s_cselect_b32 s40, s64, s36
	s_cselect_b32 s37, s17, s73
	s_cselect_b32 s36, s65, s72
	s_add_i32 s56, 0, 0x14000
	v_add_u32_e32 v136, s50, v175
	v_add_u32_e32 v172, s56, v175
	ds_read_b128 v[116:119], v136
	ds_read_b128 v[124:127], v136 offset:1024
	ds_read_b128 v[132:135], v136 offset:2048
	ds_read_b128 v[136:139], v136 offset:3072
	ds_read_b128 v[160:163], v172
	ds_read_b128 v[164:167], v172 offset:1024
	ds_read_b128 v[168:171], v172 offset:2048
	ds_read_b128 v[178:181], v172 offset:3072
	v_lshl_add_u64 v[172:173], s[26:27], 0, v[156:157]
	s_add_i32 m0, s44, 0xc000
	ds_read_b128 v[182:185], v177
	ds_read_b128 v[186:189], v177 offset:1024
	ds_read_b128 v[204:207], v177 offset:2048
	ds_read_b128 v[208:211], v177 offset:3072
	ds_read_b128 v[212:215], v177 offset:4096
	ds_read_b128 v[216:219], v177 offset:5120
	ds_read_b128 v[220:223], v177 offset:6144
	ds_read_b128 v[224:227], v177 offset:7168
	global_load_lds_dwordx4 v[172:173], off
	v_lshl_add_u64 v[172:173], s[26:27], 0, v[158:159]
	s_add_i32 m0, s44, 0xe000
	s_nop 0
	global_load_lds_dwordx4 v[172:173], off
	s_waitcnt vmcnt(8)
	s_waitcnt lgkmcnt(0)
	s_barrier
	s_setprio 1
	s_waitcnt lgkmcnt(0)
	v_mfma_i32_16x16x64_i8 v[144:147], v[116:119], v[182:185], 0
	v_mfma_i32_16x16x64_i8 v[144:147], v[124:127], v[186:189], v[144:147]
	v_mfma_i32_16x16x64_i8 v[112:115], v[124:127], v[208:211], 0
	v_mfma_i32_16x16x64_i8 v[112:115], v[116:119], v[204:207], v[112:115]
	v_mfma_i32_16x16x64_i8 v[96:99], v[116:119], v[212:215], 0
	v_mfma_i32_16x16x64_i8 v[96:99], v[124:127], v[216:219], v[96:99]
	v_mfma_i32_16x16x64_i8 v[80:83], v[124:127], v[224:227], 0
	v_mfma_i32_16x16x64_i8 v[80:83], v[116:119], v[220:223], v[80:83]
	v_mfma_i32_16x16x64_i8 v[76:79], v[132:135], v[220:223], 0
	v_mfma_i32_16x16x64_i8 v[76:79], v[136:139], v[224:227], v[76:79]
	v_mfma_i32_16x16x64_i8 v[92:95], v[136:139], v[216:219], 0
	v_mfma_i32_16x16x64_i8 v[92:95], v[132:135], v[212:215], v[92:95]
	v_mfma_i32_16x16x64_i8 v[108:111], v[132:135], v[204:207], 0
	v_mfma_i32_16x16x64_i8 v[108:111], v[136:139], v[208:211], v[108:111]
	v_mfma_i32_16x16x64_i8 v[140:143], v[136:139], v[186:189], 0
	v_mfma_i32_16x16x64_i8 v[140:143], v[132:135], v[182:185], v[140:143]
	v_mfma_i32_16x16x64_i8 v[128:131], v[160:163], v[182:185], 0
	v_mfma_i32_16x16x64_i8 v[128:131], v[164:167], v[186:189], v[128:131]
	v_mfma_i32_16x16x64_i8 v[104:107], v[164:167], v[208:211], 0
	v_mfma_i32_16x16x64_i8 v[104:107], v[160:163], v[204:207], v[104:107]
	v_mfma_i32_16x16x64_i8 v[88:91], v[160:163], v[212:215], 0
	v_mfma_i32_16x16x64_i8 v[88:91], v[164:167], v[216:219], v[88:91]
	v_mfma_i32_16x16x64_i8 v[72:75], v[164:167], v[224:227], 0
	v_mfma_i32_16x16x64_i8 v[72:75], v[160:163], v[220:223], v[72:75]
	v_mfma_i32_16x16x64_i8 v[68:71], v[168:171], v[220:223], 0
	v_mfma_i32_16x16x64_i8 v[68:71], v[178:181], v[224:227], v[68:71]
	v_mfma_i32_16x16x64_i8 v[84:87], v[178:181], v[216:219], 0
	v_mfma_i32_16x16x64_i8 v[84:87], v[168:171], v[212:215], v[84:87]
	v_mfma_i32_16x16x64_i8 v[100:103], v[168:171], v[204:207], 0
	v_mfma_i32_16x16x64_i8 v[100:103], v[178:181], v[208:211], v[100:103]
	v_mfma_i32_16x16x64_i8 v[120:123], v[178:181], v[186:189], 0
	v_mfma_i32_16x16x64_i8 v[120:123], v[168:171], v[182:185], v[120:123]
	s_setprio 0
	s_barrier
	s_add_i32 s50, s50, s43
	v_lshl_add_u64 v[172:173], s[36:37], 0, v[2:3]
	s_mov_b32 m0, s50
	ds_read_b128 v[182:185], v177 offset:16384
	ds_read_b128 v[186:189], v177 offset:17408
	ds_read_b128 v[204:207], v177 offset:18432
	ds_read_b128 v[208:211], v177 offset:19456
	ds_read_b128 v[212:215], v177 offset:20480
	ds_read_b128 v[216:219], v177 offset:21504
	ds_read_b128 v[220:223], v177 offset:22528
	ds_read_b128 v[224:227], v177 offset:23552
	global_load_lds_dwordx4 v[172:173], off
	s_add_i32 m0, s50, 0x2000
	s_add_u32 s50, s36, 0x80000
	v_lshl_add_u64 v[190:191], s[36:37], 0, v[148:149]
	s_addc_u32 s51, s37, 0
	s_add_i32 s56, s56, s43
	global_load_lds_dwordx4 v[190:191], off
	v_lshl_add_u64 v[228:229], s[50:51], 0, v[2:3]
	s_mov_b32 m0, s56
	v_lshl_add_u64 v[240:241], s[40:41], 0, v[150:151]
	global_load_lds_dwordx4 v[228:229], off
	v_lshl_add_u64 v[228:229], s[50:51], 0, v[148:149]
	s_add_i32 m0, s56, 0x2000
	s_nop 0
	global_load_lds_dwordx4 v[228:229], off
	v_lshl_add_u64 v[228:229], s[40:41], 0, v[152:153]
	s_waitcnt vmcnt(6)
	s_waitcnt lgkmcnt(0)
	s_barrier
; #define PG8_STAGE(bufoff, gbase, voff) do { _Pragma("unroll") for (int _i = 0; _i < 2; ++_i) \
;         __builtin_amdgcn_global_load_lds((const unsigned*)((const char*)(gbase) + (voff)[_i]), (PG8_LAS unsigned*)(lds + (bufoff) + ldsw + _i * 8192), 16, 0, 0); } while (0)
; #define PG8_LDA(dst, b, h) do { _Pragma("unroll") for (int m = 0; m < 4; ++m) _Pragma("unroll") for (int k = 0; k < 2; ++k) dst[m][k] = *(const PG8_LAS bf16x8*)(lds + PG8_SA(b, h) + aoff + m * 2048 + k * 1024); } while (0)
; #define PG8_LDB(dst, b, h) do { _Pragma("unroll") for (int n = 0; n < 2; ++n) _Pragma("unroll") for (int k = 0; k < 2; ++k) dst[n][k] = *(const PG8_LAS bf16x8*)(lds + PG8_SB(b, h) + boff + n * 2048 + k * 1024); } while (0)
; #define PG8_WAIT_V(n) asm volatile("s_waitcnt vmcnt(" #n ")" ::: "memory")
; #define PG8_WAIT_L(n) asm volatile("s_waitcnt lgkmcnt(" #n ")" ::: "memory")
; #define PG8_BAR __builtin_amdgcn_s_barrier()
; #define PG8_SCHED __builtin_amdgcn_sched_barrier(0)
; template <class Epi, class Sched, bool ALIGN_EPI = false, bool SP2 = false, bool I8 = false>
; __device__ __forceinline__ void gemm_phase(PG8_LAS unsigned char* lds, const Gemm g, const Sched& S, const Epi& E) {
;     ...
;             PG8_WAIT_V(8); PG8_WAIT_L(0); PG8_BAR; PG8_MMA(1, 0, At, B0); PG8_MMA(1, 1, At, B1); PG8_BAR; PG8_SCHED;
;             PG8_LDB(B0, 1, 0); PG8_LDB(B1, 1, 1); PG8_SCHED; PG8_LDA(At, 1, 0); PG8_STAGE(PG8_SA(0, 1), a2 + hstep, voffA);
;             PG8_WAIT_V(8); PG8_WAIT_L(0); PG8_BAR; PG8_MMA(0, 0, At, B0); PG8_MMA(0, 1, At, B1); PG8_BAR; PG8_SCHED;
;             PG8_LDA(At, 1, 1); PG8_STAGE(PG8_SB(1, 0), b3, voffB); PG8_STAGE(PG8_SB(1, 1), b3 + hstep, voffB); PG8_STAGE(PG8_SA(1, 0), a3, voffA);
;             PG8_WAIT_V(8); PG8_WAIT_L(0); PG8_BAR; PG8_MMA(1, 0, At, B0); PG8_MMA(1, 1, At, B1); PG8_BAR; PG8_SCHED;
	s_setprio 1
	s_waitcnt lgkmcnt(0)
	v_mfma_i32_16x16x64_i8 v[64:67], v[116:119], v[182:185], 0
	v_mfma_i32_16x16x64_i8 v[64:67], v[124:127], v[186:189], v[64:67]
	v_mfma_i32_16x16x64_i8 v[48:51], v[124:127], v[208:211], 0
	v_mfma_i32_16x16x64_i8 v[48:51], v[116:119], v[204:207], v[48:51]
	v_mfma_i32_16x16x64_i8 v[32:35], v[116:119], v[212:215], 0
	v_mfma_i32_16x16x64_i8 v[32:35], v[124:127], v[216:219], v[32:35]
	v_mfma_i32_16x16x64_i8 v[16:19], v[124:127], v[224:227], 0
	v_mfma_i32_16x16x64_i8 v[16:19], v[116:119], v[220:223], v[16:19]
	v_mfma_i32_16x16x64_i8 v[12:15], v[132:135], v[220:223], 0
	v_mfma_i32_16x16x64_i8 v[12:15], v[136:139], v[224:227], v[12:15]
	v_mfma_i32_16x16x64_i8 v[28:31], v[136:139], v[216:219], 0
	v_mfma_i32_16x16x64_i8 v[28:31], v[132:135], v[212:215], v[28:31]
	v_mfma_i32_16x16x64_i8 v[44:47], v[132:135], v[204:207], 0
	v_mfma_i32_16x16x64_i8 v[44:47], v[136:139], v[208:211], v[44:47]
	v_mfma_i32_16x16x64_i8 v[60:63], v[136:139], v[186:189], 0
	v_mfma_i32_16x16x64_i8 v[60:63], v[132:135], v[182:185], v[60:63]
	v_mfma_i32_16x16x64_i8 v[56:59], v[160:163], v[182:185], 0
	v_mfma_i32_16x16x64_i8 v[56:59], v[164:167], v[186:189], v[56:59]
	v_mfma_i32_16x16x64_i8 v[40:43], v[164:167], v[208:211], 0
	v_mfma_i32_16x16x64_i8 v[40:43], v[160:163], v[204:207], v[40:43]
	v_mfma_i32_16x16x64_i8 v[24:27], v[160:163], v[212:215], 0
	v_mfma_i32_16x16x64_i8 v[24:27], v[164:167], v[216:219], v[24:27]
	v_mfma_i32_16x16x64_i8 v[8:11], v[164:167], v[224:227], 0
	v_mfma_i32_16x16x64_i8 v[8:11], v[160:163], v[220:223], v[8:11]
	v_mfma_i32_16x16x64_i8 v[4:7], v[168:171], v[220:223], 0
	v_mfma_i32_16x16x64_i8 v[4:7], v[178:181], v[224:227], v[4:7]
	v_mfma_i32_16x16x64_i8 v[20:23], v[178:181], v[216:219], 0
	v_mfma_i32_16x16x64_i8 v[20:23], v[168:171], v[212:215], v[20:23]
	v_mfma_i32_16x16x64_i8 v[36:39], v[168:171], v[204:207], 0
	v_mfma_i32_16x16x64_i8 v[36:39], v[178:181], v[208:211], v[36:39]
	v_mfma_i32_16x16x64_i8 v[52:55], v[178:181], v[186:189], 0
	v_mfma_i32_16x16x64_i8 v[52:55], v[168:171], v[182:185], v[52:55]
	s_setprio 0
	s_barrier
	s_mov_b32 m0, s44
	s_nop 0
	global_load_lds_dwordx4 v[228:229], off
	s_mov_b32 m0, s45
	s_nop 0
	global_load_lds_dwordx4 v[240:241], off
	s_add_i32 s50, 0, 0x18000
	s_add_i32 s51, 0, 0x1c000
	v_add_u32_e32 v136, s50, v175
	v_add_u32_e32 v178, s51, v175
	ds_read_b128 v[116:119], v136
	ds_read_b128 v[124:127], v136 offset:1024
	ds_read_b128 v[132:135], v136 offset:2048
	ds_read_b128 v[136:139], v136 offset:3072
	ds_read_b128 v[160:163], v178
	ds_read_b128 v[164:167], v178 offset:1024
	ds_read_b128 v[168:171], v178 offset:2048
	ds_read_b128 v[178:181], v178 offset:3072
	s_add_u32 s40, s40, 0x80000
	s_addc_u32 s41, s41, 0
	s_mov_b32 m0, s46
	v_lshl_add_u64 v[242:243], s[40:41], 0, v[152:153]
	ds_read_b128 v[182:185], v177 offset:32768
	ds_read_b128 v[186:189], v177 offset:33792
	ds_read_b128 v[204:207], v177 offset:34816
	ds_read_b128 v[208:211], v177 offset:35840
	ds_read_b128 v[212:215], v177 offset:36864
	ds_read_b128 v[216:219], v177 offset:37888
	ds_read_b128 v[220:223], v177 offset:38912
	ds_read_b128 v[224:227], v177 offset:39936
	global_load_lds_dwordx4 v[242:243], off
	v_lshl_add_u64 v[242:243], s[40:41], 0, v[150:151]
	s_mov_b32 m0, s47
	s_nop 0
	global_load_lds_dwordx4 v[242:243], off
	s_waitcnt vmcnt(8)
	s_waitcnt lgkmcnt(0)
	s_barrier
	s_setprio 1
	s_waitcnt lgkmcnt(0)
	v_mfma_i32_16x16x64_i8 v[144:147], v[116:119], v[182:185], v[144:147]
	v_mfma_i32_16x16x64_i8 v[144:147], v[124:127], v[186:189], v[144:147]
	v_mfma_i32_16x16x64_i8 v[112:115], v[124:127], v[208:211], v[112:115]
	v_mfma_i32_16x16x64_i8 v[112:115], v[116:119], v[204:207], v[112:115]
	v_mfma_i32_16x16x64_i8 v[96:99], v[116:119], v[212:215], v[96:99]
	v_mfma_i32_16x16x64_i8 v[96:99], v[124:127], v[216:219], v[96:99]
	v_mfma_i32_16x16x64_i8 v[80:83], v[124:127], v[224:227], v[80:83]
	v_mfma_i32_16x16x64_i8 v[80:83], v[116:119], v[220:223], v[80:83]
	v_mfma_i32_16x16x64_i8 v[76:79], v[132:135], v[220:223], v[76:79]
	v_mfma_i32_16x16x64_i8 v[76:79], v[136:139], v[224:227], v[76:79]
	v_mfma_i32_16x16x64_i8 v[92:95], v[136:139], v[216:219], v[92:95]
	v_mfma_i32_16x16x64_i8 v[92:95], v[132:135], v[212:215], v[92:95]
	v_mfma_i32_16x16x64_i8 v[108:111], v[132:135], v[204:207], v[108:111]
	v_mfma_i32_16x16x64_i8 v[108:111], v[136:139], v[208:211], v[108:111]
	v_mfma_i32_16x16x64_i8 v[140:143], v[136:139], v[186:189], v[140:143]
	v_mfma_i32_16x16x64_i8 v[140:143], v[132:135], v[182:185], v[140:143]
	v_mfma_i32_16x16x64_i8 v[128:131], v[160:163], v[182:185], v[128:131]
	v_mfma_i32_16x16x64_i8 v[128:131], v[164:167], v[186:189], v[128:131]
	v_mfma_i32_16x16x64_i8 v[104:107], v[164:167], v[208:211], v[104:107]
	v_mfma_i32_16x16x64_i8 v[104:107], v[160:163], v[204:207], v[104:107]
	v_mfma_i32_16x16x64_i8 v[88:91], v[160:163], v[212:215], v[88:91]
	v_mfma_i32_16x16x64_i8 v[88:91], v[164:167], v[216:219], v[88:91]
	v_mfma_i32_16x16x64_i8 v[72:75], v[164:167], v[224:227], v[72:75]
	v_mfma_i32_16x16x64_i8 v[72:75], v[160:163], v[220:223], v[72:75]
	v_mfma_i32_16x16x64_i8 v[68:71], v[168:171], v[220:223], v[68:71]
	v_mfma_i32_16x16x64_i8 v[68:71], v[178:181], v[224:227], v[68:71]
	v_mfma_i32_16x16x64_i8 v[84:87], v[178:181], v[216:219], v[84:87]
	v_mfma_i32_16x16x64_i8 v[84:87], v[168:171], v[212:215], v[84:87]
	v_mfma_i32_16x16x64_i8 v[100:103], v[168:171], v[204:207], v[100:103]
	v_mfma_i32_16x16x64_i8 v[100:103], v[178:181], v[208:211], v[100:103]
	v_mfma_i32_16x16x64_i8 v[120:123], v[178:181], v[186:189], v[120:123]
	v_mfma_i32_16x16x64_i8 v[120:123], v[168:171], v[182:185], v[120:123]
	s_setprio 0
	s_barrier
	s_add_i32 s40, s50, s43
	v_lshl_add_u64 v[172:173], v[172:173], 0, s[84:85]
	s_mov_b32 m0, s40
	ds_read_b128 v[182:185], v177 offset:49152
	ds_read_b128 v[186:189], v177 offset:50176
	ds_read_b128 v[204:207], v177 offset:51200
	ds_read_b128 v[208:211], v177 offset:52224
	ds_read_b128 v[212:215], v177 offset:53248
	ds_read_b128 v[216:219], v177 offset:54272
	ds_read_b128 v[220:223], v177 offset:55296
	ds_read_b128 v[224:227], v177 offset:56320
	global_load_lds_dwordx4 v[172:173], off
	s_add_i32 m0, s40, 0x2000
	s_add_u32 s36, s36, 0x80080
	v_lshl_add_u64 v[172:173], v[190:191], 0, s[84:85]
	s_addc_u32 s37, s37, 0
	s_add_i32 s40, s51, s43
	global_load_lds_dwordx4 v[172:173], off
	v_lshl_add_u64 v[172:173], s[36:37], 0, v[2:3]
	s_mov_b32 m0, s40
	s_nop 0
	global_load_lds_dwordx4 v[172:173], off
	v_lshl_add_u64 v[172:173], s[36:37], 0, v[148:149]
	s_add_i32 m0, s40, 0x2000
	s_nop 0
	global_load_lds_dwordx4 v[172:173], off
	s_cmp_eq_u32 s76, 28
	s_cbranch_scc0 .Ldefer_208_peel
	v_lshl_add_u64 v[172:173], v[228:229], 0, s[84:85]
	s_mov_b32 m0, s52
	s_nop 0
	global_load_lds_dwordx4 v[172:173], off
	v_lshl_add_u64 v[172:173], v[240:241], 0, s[84:85]
	s_mov_b32 m0, s53
	s_nop 0
	global_load_lds_dwordx4 v[172:173], off
; #define PG8_STAGE(bufoff, gbase, voff) do { _Pragma("unroll") for (int _i = 0; _i < 2; ++_i) \
;         __builtin_amdgcn_global_load_lds((const unsigned*)((const char*)(gbase) + (voff)[_i]), (PG8_LAS unsigned*)(lds + (bufoff) + ldsw + _i * 8192), 16, 0, 0); } while (0)
; #define PG8_LDA(dst, b, h) do { _Pragma("unroll") for (int m = 0; m < 4; ++m) _Pragma("unroll") for (int k = 0; k < 2; ++k) dst[m][k] = *(const PG8_LAS bf16x8*)(lds + PG8_SA(b, h) + aoff + m * 2048 + k * 1024); } while (0)
; #define PG8_WAIT_V(n) asm volatile("s_waitcnt vmcnt(" #n ")" ::: "memory")
; #define PG8_WAIT_L(n) asm volatile("s_waitcnt lgkmcnt(" #n ")" ::: "memory")
; #define PG8_BAR __builtin_amdgcn_s_barrier()
; template <class Epi, class Sched, bool ALIGN_EPI = false, bool SP2 = false, bool I8 = false>
; __device__ __forceinline__ void gemm_phase(PG8_LAS unsigned char* lds, const Gemm g, const Sched& S, const Epi& E) {
;     ...
;         for (int t = 0; t < nt; t += 2) {
;             const bool last = (t == nt - 2);
;             const char* a1 = cA + (size_t)(t + 1) * kstep;
;             const char* a2 = last ? nA : cA + (size_t)(t + 2) * kstep; const char* b2 = last ? nB : cB + (size_t)(t + 2) * kstep;
;             const char* a3 = a2 + kstep; const char* b3 = b2 + kstep;
;             if (last && has_next) S.a_ready(nxt);
;             if constexpr (SP2) {
;             PG8_LDB(B0, 0, 0); PG8_LDB(B1, 0, 1); PG8_SCHED; PG8_LDA(At, 0, 0); PG8_STAGE(PG8_SA(1, 1), a1 + hstep, voffA);
;             PG8_WAIT_V(8); PG8_WAIT_L(0); PG8_BAR; PG8_MMA(0, 0, At, B0); PG8_MMA(0, 1, At, B1); PG8_BAR; PG8_SCHED;
;             PG8_LDA(At, 0, 1); PG8_STAGE(PG8_SB(0, 0), b2, voffB); PG8_STAGE(PG8_SB(0, 1), b2 + hstep, voffB); PG8_STAGE(PG8_SA(0, 0), a2, voffA);
;             PG8_WAIT_V(8); PG8_WAIT_L(0); PG8_BAR; PG8_MMA(1, 0, At, B0); PG8_MMA(1, 1, At, B1); PG8_BAR; PG8_SCHED;
;             PG8_LDB(B0, 1, 0); PG8_LDB(B1, 1, 1); PG8_SCHED; PG8_LDA(At, 1, 0); PG8_STAGE(PG8_SA(0, 1), a2 + hstep, voffA);
;             PG8_WAIT_V(8); PG8_WAIT_L(0); PG8_BAR; PG8_MMA(0, 0, At, B0); PG8_MMA(0, 1, At, B1); PG8_BAR; PG8_SCHED;
;             PG8_LDA(At, 1, 1); PG8_STAGE(PG8_SB(1, 0), b3, voffB); PG8_STAGE(PG8_SB(1, 1), b3 + hstep, voffB); PG8_STAGE(PG8_SA(1, 0), a3, voffA);
;             PG8_WAIT_V(8); PG8_WAIT_L(0); PG8_BAR; PG8_MMA(1, 0, At, B0); PG8_MMA(1, 1, At, B1); PG8_BAR; PG8_SCHED;
.Ldefer_208_peel:
	s_waitcnt vmcnt(6)
	s_waitcnt lgkmcnt(0)
	s_barrier
	s_setprio 1
	s_waitcnt lgkmcnt(0)
	v_mfma_i32_16x16x64_i8 v[64:67], v[116:119], v[182:185], v[64:67]
	v_mfma_i32_16x16x64_i8 v[64:67], v[124:127], v[186:189], v[64:67]
	v_mfma_i32_16x16x64_i8 v[48:51], v[124:127], v[208:211], v[48:51]
	v_mfma_i32_16x16x64_i8 v[48:51], v[116:119], v[204:207], v[48:51]
	v_mfma_i32_16x16x64_i8 v[32:35], v[116:119], v[212:215], v[32:35]
	v_mfma_i32_16x16x64_i8 v[32:35], v[124:127], v[216:219], v[32:35]
	v_mfma_i32_16x16x64_i8 v[16:19], v[124:127], v[224:227], v[16:19]
	v_mfma_i32_16x16x64_i8 v[16:19], v[116:119], v[220:223], v[16:19]
	v_mfma_i32_16x16x64_i8 v[12:15], v[132:135], v[220:223], v[12:15]
	v_mfma_i32_16x16x64_i8 v[12:15], v[136:139], v[224:227], v[12:15]
	v_mfma_i32_16x16x64_i8 v[28:31], v[136:139], v[216:219], v[28:31]
	v_mfma_i32_16x16x64_i8 v[28:31], v[132:135], v[212:215], v[28:31]
	v_mfma_i32_16x16x64_i8 v[44:47], v[132:135], v[204:207], v[44:47]
	v_mfma_i32_16x16x64_i8 v[44:47], v[136:139], v[208:211], v[44:47]
	v_mfma_i32_16x16x64_i8 v[60:63], v[136:139], v[186:189], v[60:63]
	v_mfma_i32_16x16x64_i8 v[60:63], v[132:135], v[182:185], v[60:63]
	v_mfma_i32_16x16x64_i8 v[56:59], v[160:163], v[182:185], v[56:59]
	v_mfma_i32_16x16x64_i8 v[56:59], v[164:167], v[186:189], v[56:59]
	v_mfma_i32_16x16x64_i8 v[40:43], v[164:167], v[208:211], v[40:43]
	v_mfma_i32_16x16x64_i8 v[40:43], v[160:163], v[204:207], v[40:43]
	v_mfma_i32_16x16x64_i8 v[24:27], v[160:163], v[212:215], v[24:27]
	v_mfma_i32_16x16x64_i8 v[24:27], v[164:167], v[216:219], v[24:27]
	v_mfma_i32_16x16x64_i8 v[8:11], v[164:167], v[224:227], v[8:11]
	v_mfma_i32_16x16x64_i8 v[8:11], v[160:163], v[220:223], v[8:11]
	v_mfma_i32_16x16x64_i8 v[4:7], v[168:171], v[220:223], v[4:7]
	v_mfma_i32_16x16x64_i8 v[4:7], v[178:181], v[224:227], v[4:7]
	v_mfma_i32_16x16x64_i8 v[20:23], v[178:181], v[216:219], v[20:23]
	v_mfma_i32_16x16x64_i8 v[20:23], v[168:171], v[212:215], v[20:23]
	v_mfma_i32_16x16x64_i8 v[36:39], v[168:171], v[204:207], v[36:39]
	v_mfma_i32_16x16x64_i8 v[36:39], v[178:181], v[208:211], v[36:39]
	v_mfma_i32_16x16x64_i8 v[52:55], v[178:181], v[186:189], v[52:55]
	v_mfma_i32_16x16x64_i8 v[52:55], v[168:171], v[182:185], v[52:55]
	s_setprio 0
	s_barrier
	s_add_i32 s76, s76, 2
	s_add_u32 s26, s26, 0x100
	s_addc_u32 s27, s27, 0
	s_add_u32 s72, s72, 0x100
	s_addc_u32 s73, s73, 0
	s_cmp_gt_u32 s76, 29
	s_cbranch_scc1 .Lkloop_exit_0
.LBB0_208:
	s_add_u32 s36, s26, 0xfff80080
	s_addc_u32 s37, s27, -1
	s_add_i32 s50, 0, 0x10000
	s_cmp_eq_u32 s76, 28
	s_cselect_b32 s41, s19, s37
	s_cselect_b32 s40, s64, s36
	s_cselect_b32 s37, s17, s73
	s_cselect_b32 s36, s65, s72
	s_add_i32 s56, 0, 0x14000
	v_add_u32_e32 v136, s50, v175
	v_add_u32_e32 v172, s56, v175
	ds_read_b128 v[116:119], v136
	ds_read_b128 v[124:127], v136 offset:1024
	ds_read_b128 v[132:135], v136 offset:2048
	ds_read_b128 v[136:139], v136 offset:3072
	ds_read_b128 v[160:163], v172
	ds_read_b128 v[164:167], v172 offset:1024
	ds_read_b128 v[168:171], v172 offset:2048
	ds_read_b128 v[178:181], v172 offset:3072
	v_lshl_add_u64 v[172:173], v[228:229], 0, s[84:85]
	s_mov_b32 m0, s52
	s_nop 0
	global_load_lds_dwordx4 v[172:173], off
	v_lshl_add_u64 v[172:173], v[240:241], 0, s[84:85]
	s_mov_b32 m0, s53
	s_nop 0
	global_load_lds_dwordx4 v[172:173], off
	v_lshl_add_u64 v[172:173], s[26:27], 0, v[156:157]
	s_add_i32 m0, s44, 0xc000
	ds_read_b128 v[182:185], v177
	ds_read_b128 v[186:189], v177 offset:1024
	ds_read_b128 v[204:207], v177 offset:2048
	ds_read_b128 v[208:211], v177 offset:3072
	ds_read_b128 v[212:215], v177 offset:4096
	ds_read_b128 v[216:219], v177 offset:5120
	ds_read_b128 v[220:223], v177 offset:6144
	ds_read_b128 v[224:227], v177 offset:7168
	global_load_lds_dwordx4 v[172:173], off
	v_lshl_add_u64 v[172:173], s[26:27], 0, v[158:159]
	s_add_i32 m0, s44, 0xe000
	s_nop 0
	global_load_lds_dwordx4 v[172:173], off
	s_waitcnt vmcnt(8)
	s_waitcnt lgkmcnt(0)
	s_barrier
	s_setprio 1
	s_waitcnt lgkmcnt(0)
	v_mfma_i32_16x16x64_i8 v[144:147], v[116:119], v[182:185], v[144:147]
	v_mfma_i32_16x16x64_i8 v[144:147], v[124:127], v[186:189], v[144:147]
	v_mfma_i32_16x16x64_i8 v[112:115], v[124:127], v[208:211], v[112:115]
	v_mfma_i32_16x16x64_i8 v[112:115], v[116:119], v[204:207], v[112:115]
	v_mfma_i32_16x16x64_i8 v[96:99], v[116:119], v[212:215], v[96:99]
	v_mfma_i32_16x16x64_i8 v[96:99], v[124:127], v[216:219], v[96:99]
	v_mfma_i32_16x16x64_i8 v[80:83], v[124:127], v[224:227], v[80:83]
	v_mfma_i32_16x16x64_i8 v[80:83], v[116:119], v[220:223], v[80:83]
	v_mfma_i32_16x16x64_i8 v[76:79], v[132:135], v[220:223], v[76:79]
	v_mfma_i32_16x16x64_i8 v[76:79], v[136:139], v[224:227], v[76:79]
	v_mfma_i32_16x16x64_i8 v[92:95], v[136:139], v[216:219], v[92:95]
	v_mfma_i32_16x16x64_i8 v[92:95], v[132:135], v[212:215], v[92:95]
	v_mfma_i32_16x16x64_i8 v[108:111], v[132:135], v[204:207], v[108:111]
	v_mfma_i32_16x16x64_i8 v[108:111], v[136:139], v[208:211], v[108:111]
	v_mfma_i32_16x16x64_i8 v[140:143], v[136:139], v[186:189], v[140:143]
	v_mfma_i32_16x16x64_i8 v[140:143], v[132:135], v[182:185], v[140:143]
	v_mfma_i32_16x16x64_i8 v[128:131], v[160:163], v[182:185], v[128:131]
	v_mfma_i32_16x16x64_i8 v[128:131], v[164:167], v[186:189], v[128:131]
	v_mfma_i32_16x16x64_i8 v[104:107], v[164:167], v[208:211], v[104:107]
	v_mfma_i32_16x16x64_i8 v[104:107], v[160:163], v[204:207], v[104:107]
	v_mfma_i32_16x16x64_i8 v[88:91], v[160:163], v[212:215], v[88:91]
	v_mfma_i32_16x16x64_i8 v[88:91], v[164:167], v[216:219], v[88:91]
	v_mfma_i32_16x16x64_i8 v[72:75], v[164:167], v[224:227], v[72:75]
	v_mfma_i32_16x16x64_i8 v[72:75], v[160:163], v[220:223], v[72:75]
	v_mfma_i32_16x16x64_i8 v[68:71], v[168:171], v[220:223], v[68:71]
	v_mfma_i32_16x16x64_i8 v[68:71], v[178:181], v[224:227], v[68:71]
	v_mfma_i32_16x16x64_i8 v[84:87], v[178:181], v[216:219], v[84:87]
	v_mfma_i32_16x16x64_i8 v[84:87], v[168:171], v[212:215], v[84:87]
	v_mfma_i32_16x16x64_i8 v[100:103], v[168:171], v[204:207], v[100:103]
	v_mfma_i32_16x16x64_i8 v[100:103], v[178:181], v[208:211], v[100:103]
	v_mfma_i32_16x16x64_i8 v[120:123], v[178:181], v[186:189], v[120:123]
	v_mfma_i32_16x16x64_i8 v[120:123], v[168:171], v[182:185], v[120:123]
	s_setprio 0
	s_barrier
; #define PG8_STAGE(bufoff, gbase, voff) do { _Pragma("unroll") for (int _i = 0; _i < 2; ++_i) \
;         __builtin_amdgcn_global_load_lds((const unsigned*)((const char*)(gbase) + (voff)[_i]), (PG8_LAS unsigned*)(lds + (bufoff) + ldsw + _i * 8192), 16, 0, 0); } while (0)
; #define PG8_LDA(dst, b, h) do { _Pragma("unroll") for (int m = 0; m < 4; ++m) _Pragma("unroll") for (int k = 0; k < 2; ++k) dst[m][k] = *(const PG8_LAS bf16x8*)(lds + PG8_SA(b, h) + aoff + m * 2048 + k * 1024); } while (0)
; #define PG8_LDB(dst, b, h) do { _Pragma("unroll") for (int n = 0; n < 2; ++n) _Pragma("unroll") for (int k = 0; k < 2; ++k) dst[n][k] = *(const PG8_LAS bf16x8*)(lds + PG8_SB(b, h) + boff + n * 2048 + k * 1024); } while (0)
; #define PG8_WAIT_V(n) asm volatile("s_waitcnt vmcnt(" #n ")" ::: "memory")
; #define PG8_WAIT_L(n) asm volatile("s_waitcnt lgkmcnt(" #n ")" ::: "memory")
; #define PG8_BAR __builtin_amdgcn_s_barrier()
; #define PG8_SCHED __builtin_amdgcn_sched_barrier(0)
; template <class Epi, class Sched, bool ALIGN_EPI = false, bool SP2 = false, bool I8 = false>
; __device__ __forceinline__ void gemm_phase(PG8_LAS unsigned char* lds, const Gemm g, const Sched& S, const Epi& E) {
;     ...
;             PG8_LDA(At, 0, 1); PG8_STAGE(PG8_SB(0, 0), b2, voffB); PG8_STAGE(PG8_SB(0, 1), b2 + hstep, voffB); PG8_STAGE(PG8_SA(0, 0), a2, voffA);
;             PG8_WAIT_V(8); PG8_WAIT_L(0); PG8_BAR; PG8_MMA(1, 0, At, B0); PG8_MMA(1, 1, At, B1); PG8_BAR; PG8_SCHED;
;             PG8_LDB(B0, 1, 0); PG8_LDB(B1, 1, 1); PG8_SCHED; PG8_LDA(At, 1, 0); PG8_STAGE(PG8_SA(0, 1), a2 + hstep, voffA);
;             PG8_WAIT_V(8); PG8_WAIT_L(0); PG8_BAR; PG8_MMA(0, 0, At, B0); PG8_MMA(0, 1, At, B1); PG8_BAR; PG8_SCHED;
	s_add_i32 s50, s50, s43
	v_lshl_add_u64 v[172:173], s[36:37], 0, v[2:3]
	s_mov_b32 m0, s50
	ds_read_b128 v[182:185], v177 offset:16384
	ds_read_b128 v[186:189], v177 offset:17408
	ds_read_b128 v[204:207], v177 offset:18432
	ds_read_b128 v[208:211], v177 offset:19456
	ds_read_b128 v[212:215], v177 offset:20480
	ds_read_b128 v[216:219], v177 offset:21504
	ds_read_b128 v[220:223], v177 offset:22528
	ds_read_b128 v[224:227], v177 offset:23552
	global_load_lds_dwordx4 v[172:173], off
	s_add_i32 m0, s50, 0x2000
	s_add_u32 s50, s36, 0x80000
	v_lshl_add_u64 v[190:191], s[36:37], 0, v[148:149]
	s_addc_u32 s51, s37, 0
	s_add_i32 s56, s56, s43
	global_load_lds_dwordx4 v[190:191], off
	v_lshl_add_u64 v[228:229], s[50:51], 0, v[2:3]
	s_mov_b32 m0, s56
	v_lshl_add_u64 v[240:241], s[40:41], 0, v[150:151]
	global_load_lds_dwordx4 v[228:229], off
	v_lshl_add_u64 v[228:229], s[50:51], 0, v[148:149]
	s_add_i32 m0, s56, 0x2000
	s_nop 0
	global_load_lds_dwordx4 v[228:229], off
	v_lshl_add_u64 v[228:229], s[40:41], 0, v[152:153]
	s_waitcnt vmcnt(6)
	s_waitcnt lgkmcnt(0)
	s_barrier
	s_setprio 1
	s_waitcnt lgkmcnt(0)
	v_mfma_i32_16x16x64_i8 v[64:67], v[116:119], v[182:185], v[64:67]
	v_mfma_i32_16x16x64_i8 v[64:67], v[124:127], v[186:189], v[64:67]
	v_mfma_i32_16x16x64_i8 v[48:51], v[124:127], v[208:211], v[48:51]
	v_mfma_i32_16x16x64_i8 v[48:51], v[116:119], v[204:207], v[48:51]
	v_mfma_i32_16x16x64_i8 v[32:35], v[116:119], v[212:215], v[32:35]
	v_mfma_i32_16x16x64_i8 v[32:35], v[124:127], v[216:219], v[32:35]
	v_mfma_i32_16x16x64_i8 v[16:19], v[124:127], v[224:227], v[16:19]
	v_mfma_i32_16x16x64_i8 v[16:19], v[116:119], v[220:223], v[16:19]
	v_mfma_i32_16x16x64_i8 v[12:15], v[132:135], v[220:223], v[12:15]
	v_mfma_i32_16x16x64_i8 v[12:15], v[136:139], v[224:227], v[12:15]
	v_mfma_i32_16x16x64_i8 v[28:31], v[136:139], v[216:219], v[28:31]
	v_mfma_i32_16x16x64_i8 v[28:31], v[132:135], v[212:215], v[28:31]
	v_mfma_i32_16x16x64_i8 v[44:47], v[132:135], v[204:207], v[44:47]
	v_mfma_i32_16x16x64_i8 v[44:47], v[136:139], v[208:211], v[44:47]
	v_mfma_i32_16x16x64_i8 v[60:63], v[136:139], v[186:189], v[60:63]
	v_mfma_i32_16x16x64_i8 v[60:63], v[132:135], v[182:185], v[60:63]
	v_mfma_i32_16x16x64_i8 v[56:59], v[160:163], v[182:185], v[56:59]
	v_mfma_i32_16x16x64_i8 v[56:59], v[164:167], v[186:189], v[56:59]
	v_mfma_i32_16x16x64_i8 v[40:43], v[164:167], v[208:211], v[40:43]
	v_mfma_i32_16x16x64_i8 v[40:43], v[160:163], v[204:207], v[40:43]
	v_mfma_i32_16x16x64_i8 v[24:27], v[160:163], v[212:215], v[24:27]
	v_mfma_i32_16x16x64_i8 v[24:27], v[164:167], v[216:219], v[24:27]
	v_mfma_i32_16x16x64_i8 v[8:11], v[164:167], v[224:227], v[8:11]
	v_mfma_i32_16x16x64_i8 v[8:11], v[160:163], v[220:223], v[8:11]
	v_mfma_i32_16x16x64_i8 v[4:7], v[168:171], v[220:223], v[4:7]
	v_mfma_i32_16x16x64_i8 v[4:7], v[178:181], v[224:227], v[4:7]
	v_mfma_i32_16x16x64_i8 v[20:23], v[178:181], v[216:219], v[20:23]
	v_mfma_i32_16x16x64_i8 v[20:23], v[168:171], v[212:215], v[20:23]
	v_mfma_i32_16x16x64_i8 v[36:39], v[168:171], v[204:207], v[36:39]
	v_mfma_i32_16x16x64_i8 v[36:39], v[178:181], v[208:211], v[36:39]
	v_mfma_i32_16x16x64_i8 v[52:55], v[178:181], v[186:189], v[52:55]
	v_mfma_i32_16x16x64_i8 v[52:55], v[168:171], v[182:185], v[52:55]
	s_setprio 0
	s_barrier
	s_mov_b32 m0, s44
	s_nop 0
	global_load_lds_dwordx4 v[228:229], off
	s_mov_b32 m0, s45
	s_nop 0
	global_load_lds_dwordx4 v[240:241], off
	s_add_i32 s50, 0, 0x18000
	s_add_i32 s51, 0, 0x1c000
	v_add_u32_e32 v136, s50, v175
	v_add_u32_e32 v178, s51, v175
	ds_read_b128 v[116:119], v136
	ds_read_b128 v[124:127], v136 offset:1024
	ds_read_b128 v[132:135], v136 offset:2048
	ds_read_b128 v[136:139], v136 offset:3072
	ds_read_b128 v[160:163], v178
	ds_read_b128 v[164:167], v178 offset:1024
	ds_read_b128 v[168:171], v178 offset:2048
	ds_read_b128 v[178:181], v178 offset:3072
	s_add_u32 s40, s40, 0x80000
	s_addc_u32 s41, s41, 0
	s_mov_b32 m0, s46
	v_lshl_add_u64 v[242:243], s[40:41], 0, v[152:153]
	ds_read_b128 v[182:185], v177 offset:32768
	ds_read_b128 v[186:189], v177 offset:33792
	ds_read_b128 v[204:207], v177 offset:34816
	ds_read_b128 v[208:211], v177 offset:35840
	ds_read_b128 v[212:215], v177 offset:36864
	ds_read_b128 v[216:219], v177 offset:37888
	ds_read_b128 v[220:223], v177 offset:38912
	ds_read_b128 v[224:227], v177 offset:39936
	global_load_lds_dwordx4 v[242:243], off
	v_lshl_add_u64 v[242:243], s[40:41], 0, v[150:151]
	s_mov_b32 m0, s47
	s_nop 0
	global_load_lds_dwordx4 v[242:243], off
	s_waitcnt vmcnt(8)
	s_waitcnt lgkmcnt(0)
	s_barrier
; #define PG8_STAGE(bufoff, gbase, voff) do { _Pragma("unroll") for (int _i = 0; _i < 2; ++_i) \
;         __builtin_amdgcn_global_load_lds((const unsigned*)((const char*)(gbase) + (voff)[_i]), (PG8_LAS unsigned*)(lds + (bufoff) + ldsw + _i * 8192), 16, 0, 0); } while (0)
; #define PG8_LDA(dst, b, h) do { _Pragma("unroll") for (int m = 0; m < 4; ++m) _Pragma("unroll") for (int k = 0; k < 2; ++k) dst[m][k] = *(const PG8_LAS bf16x8*)(lds + PG8_SA(b, h) + aoff + m * 2048 + k * 1024); } while (0)
; #define PG8_WAIT_V(n) asm volatile("s_waitcnt vmcnt(" #n ")" ::: "memory")
; #define PG8_WAIT_L(n) asm volatile("s_waitcnt lgkmcnt(" #n ")" ::: "memory")
; #define PG8_BAR __builtin_amdgcn_s_barrier()
; #define PG8_SCHED __builtin_amdgcn_sched_barrier(0)
; template <class Epi, class Sched, bool ALIGN_EPI = false, bool SP2 = false, bool I8 = false>
; __device__ __forceinline__ void gemm_phase(PG8_LAS unsigned char* lds, const Gemm g, const Sched& S, const Epi& E) {
;     ...
;             PG8_WAIT_V(8); PG8_WAIT_L(0); PG8_BAR; PG8_MMA(0, 0, At, B0); PG8_MMA(0, 1, At, B1); PG8_BAR; PG8_SCHED;
;             PG8_LDA(At, 1, 1); PG8_STAGE(PG8_SB(1, 0), b3, voffB); PG8_STAGE(PG8_SB(1, 1), b3 + hstep, voffB); PG8_STAGE(PG8_SA(1, 0), a3, voffA);
;             PG8_WAIT_V(8); PG8_WAIT_L(0); PG8_BAR; PG8_MMA(1, 0, At, B0); PG8_MMA(1, 1, At, B1); PG8_BAR; PG8_SCHED;
	s_setprio 1
	s_waitcnt lgkmcnt(0)
	v_mfma_i32_16x16x64_i8 v[144:147], v[116:119], v[182:185], v[144:147]
	v_mfma_i32_16x16x64_i8 v[144:147], v[124:127], v[186:189], v[144:147]
	v_mfma_i32_16x16x64_i8 v[112:115], v[124:127], v[208:211], v[112:115]
	v_mfma_i32_16x16x64_i8 v[112:115], v[116:119], v[204:207], v[112:115]
	v_mfma_i32_16x16x64_i8 v[96:99], v[116:119], v[212:215], v[96:99]
	v_mfma_i32_16x16x64_i8 v[96:99], v[124:127], v[216:219], v[96:99]
	v_mfma_i32_16x16x64_i8 v[80:83], v[124:127], v[224:227], v[80:83]
	v_mfma_i32_16x16x64_i8 v[80:83], v[116:119], v[220:223], v[80:83]
	v_mfma_i32_16x16x64_i8 v[76:79], v[132:135], v[220:223], v[76:79]
	v_mfma_i32_16x16x64_i8 v[76:79], v[136:139], v[224:227], v[76:79]
	v_mfma_i32_16x16x64_i8 v[92:95], v[136:139], v[216:219], v[92:95]
	v_mfma_i32_16x16x64_i8 v[92:95], v[132:135], v[212:215], v[92:95]
	v_mfma_i32_16x16x64_i8 v[108:111], v[132:135], v[204:207], v[108:111]
	v_mfma_i32_16x16x64_i8 v[108:111], v[136:139], v[208:211], v[108:111]
	v_mfma_i32_16x16x64_i8 v[140:143], v[136:139], v[186:189], v[140:143]
	v_mfma_i32_16x16x64_i8 v[140:143], v[132:135], v[182:185], v[140:143]
	v_mfma_i32_16x16x64_i8 v[128:131], v[160:163], v[182:185], v[128:131]
	v_mfma_i32_16x16x64_i8 v[128:131], v[164:167], v[186:189], v[128:131]
	v_mfma_i32_16x16x64_i8 v[104:107], v[164:167], v[208:211], v[104:107]
	v_mfma_i32_16x16x64_i8 v[104:107], v[160:163], v[204:207], v[104:107]
	v_mfma_i32_16x16x64_i8 v[88:91], v[160:163], v[212:215], v[88:91]
	v_mfma_i32_16x16x64_i8 v[88:91], v[164:167], v[216:219], v[88:91]
	v_mfma_i32_16x16x64_i8 v[72:75], v[164:167], v[224:227], v[72:75]
	v_mfma_i32_16x16x64_i8 v[72:75], v[160:163], v[220:223], v[72:75]
	v_mfma_i32_16x16x64_i8 v[68:71], v[168:171], v[220:223], v[68:71]
	v_mfma_i32_16x16x64_i8 v[68:71], v[178:181], v[224:227], v[68:71]
	v_mfma_i32_16x16x64_i8 v[84:87], v[178:181], v[216:219], v[84:87]
	v_mfma_i32_16x16x64_i8 v[84:87], v[168:171], v[212:215], v[84:87]
	v_mfma_i32_16x16x64_i8 v[100:103], v[168:171], v[204:207], v[100:103]
	v_mfma_i32_16x16x64_i8 v[100:103], v[178:181], v[208:211], v[100:103]
	v_mfma_i32_16x16x64_i8 v[120:123], v[178:181], v[186:189], v[120:123]
	v_mfma_i32_16x16x64_i8 v[120:123], v[168:171], v[182:185], v[120:123]
	s_setprio 0
	s_barrier
	s_add_i32 s40, s50, s43
	v_lshl_add_u64 v[172:173], v[172:173], 0, s[84:85]
	s_mov_b32 m0, s40
	ds_read_b128 v[182:185], v177 offset:49152
	ds_read_b128 v[186:189], v177 offset:50176
	ds_read_b128 v[204:207], v177 offset:51200
	ds_read_b128 v[208:211], v177 offset:52224
	ds_read_b128 v[212:215], v177 offset:53248
	ds_read_b128 v[216:219], v177 offset:54272
	ds_read_b128 v[220:223], v177 offset:55296
	ds_read_b128 v[224:227], v177 offset:56320
	global_load_lds_dwordx4 v[172:173], off
	s_add_i32 m0, s40, 0x2000
	s_add_u32 s36, s36, 0x80080
	v_lshl_add_u64 v[172:173], v[190:191], 0, s[84:85]
	s_addc_u32 s37, s37, 0
	s_add_i32 s40, s51, s43
	global_load_lds_dwordx4 v[172:173], off
	v_lshl_add_u64 v[172:173], s[36:37], 0, v[2:3]
	s_mov_b32 m0, s40
	s_nop 0
	global_load_lds_dwordx4 v[172:173], off
	v_lshl_add_u64 v[172:173], s[36:37], 0, v[148:149]
	s_add_i32 m0, s40, 0x2000
	s_nop 0
	global_load_lds_dwordx4 v[172:173], off
	s_cmp_eq_u32 s76, 28
	s_cbranch_scc0 .Ldefer_208_body
	v_lshl_add_u64 v[172:173], v[228:229], 0, s[84:85]
	s_mov_b32 m0, s52
	s_nop 0
	global_load_lds_dwordx4 v[172:173], off
	v_lshl_add_u64 v[172:173], v[240:241], 0, s[84:85]
	s_mov_b32 m0, s53
	s_nop 0
	global_load_lds_dwordx4 v[172:173], off
.Ldefer_208_body:
	s_waitcnt vmcnt(6)
	s_waitcnt lgkmcnt(0)
	s_barrier
	s_setprio 1
	s_waitcnt lgkmcnt(0)
	v_mfma_i32_16x16x64_i8 v[64:67], v[116:119], v[182:185], v[64:67]
	v_mfma_i32_16x16x64_i8 v[64:67], v[124:127], v[186:189], v[64:67]
	v_mfma_i32_16x16x64_i8 v[48:51], v[124:127], v[208:211], v[48:51]
	v_mfma_i32_16x16x64_i8 v[48:51], v[116:119], v[204:207], v[48:51]
	v_mfma_i32_16x16x64_i8 v[32:35], v[116:119], v[212:215], v[32:35]
	v_mfma_i32_16x16x64_i8 v[32:35], v[124:127], v[216:219], v[32:35]
	v_mfma_i32_16x16x64_i8 v[16:19], v[124:127], v[224:227], v[16:19]
	v_mfma_i32_16x16x64_i8 v[16:19], v[116:119], v[220:223], v[16:19]
	v_mfma_i32_16x16x64_i8 v[12:15], v[132:135], v[220:223], v[12:15]
	v_mfma_i32_16x16x64_i8 v[12:15], v[136:139], v[224:227], v[12:15]
	v_mfma_i32_16x16x64_i8 v[28:31], v[136:139], v[216:219], v[28:31]
	v_mfma_i32_16x16x64_i8 v[28:31], v[132:135], v[212:215], v[28:31]
	v_mfma_i32_16x16x64_i8 v[44:47], v[132:135], v[204:207], v[44:47]
	v_mfma_i32_16x16x64_i8 v[44:47], v[136:139], v[208:211], v[44:47]
	v_mfma_i32_16x16x64_i8 v[60:63], v[136:139], v[186:189], v[60:63]
	v_mfma_i32_16x16x64_i8 v[60:63], v[132:135], v[182:185], v[60:63]
	v_mfma_i32_16x16x64_i8 v[56:59], v[160:163], v[182:185], v[56:59]
	v_mfma_i32_16x16x64_i8 v[56:59], v[164:167], v[186:189], v[56:59]
	v_mfma_i32_16x16x64_i8 v[40:43], v[164:167], v[208:211], v[40:43]
	v_mfma_i32_16x16x64_i8 v[40:43], v[160:163], v[204:207], v[40:43]
	v_mfma_i32_16x16x64_i8 v[24:27], v[160:163], v[212:215], v[24:27]
	v_mfma_i32_16x16x64_i8 v[24:27], v[164:167], v[216:219], v[24:27]
	v_mfma_i32_16x16x64_i8 v[8:11], v[164:167], v[224:227], v[8:11]
	v_mfma_i32_16x16x64_i8 v[8:11], v[160:163], v[220:223], v[8:11]
	v_mfma_i32_16x16x64_i8 v[4:7], v[168:171], v[220:223], v[4:7]
	v_mfma_i32_16x16x64_i8 v[4:7], v[178:181], v[224:227], v[4:7]
	v_mfma_i32_16x16x64_i8 v[20:23], v[178:181], v[216:219], v[20:23]
	v_mfma_i32_16x16x64_i8 v[20:23], v[168:171], v[212:215], v[20:23]
	v_mfma_i32_16x16x64_i8 v[36:39], v[168:171], v[204:207], v[36:39]
	v_mfma_i32_16x16x64_i8 v[36:39], v[178:181], v[208:211], v[36:39]
	v_mfma_i32_16x16x64_i8 v[52:55], v[178:181], v[186:189], v[52:55]
	v_mfma_i32_16x16x64_i8 v[52:55], v[168:171], v[182:185], v[52:55]
	s_setprio 0
	s_barrier
	s_add_i32 s76, s76, 2
	s_add_u32 s26, s26, 0x100
	s_addc_u32 s27, s27, 0
	s_add_u32 s72, s72, 0x100
	s_addc_u32 s73, s73, 0
	s_cmp_gt_u32 s76, 29
	s_cbranch_scc0 .LBB0_208

; #define PG8_STAGE(bufoff, gbase, voff) do { _Pragma("unroll") for (int _i = 0; _i < 2; ++_i) \
;         __builtin_amdgcn_global_load_lds((const unsigned*)((const char*)(gbase) + (voff)[_i]), (PG8_LAS unsigned*)(lds + (bufoff) + ldsw + _i * 8192), 16, 0, 0); } while (0)
; #define PG8_LDA(dst, b, h) do { _Pragma("unroll") for (int m = 0; m < 4; ++m) _Pragma("unroll") for (int k = 0; k < 2; ++k) dst[m][k] = *(const PG8_LAS bf16x8*)(lds + PG8_SA(b, h) + aoff + m * 2048 + k * 1024); } while (0)
; #define PG8_LDB(dst, b, h) do { _Pragma("unroll") for (int n = 0; n < 2; ++n) _Pragma("unroll") for (int k = 0; k < 2; ++k) dst[n][k] = *(const PG8_LAS bf16x8*)(lds + PG8_SB(b, h) + boff + n * 2048 + k * 1024); } while (0)
; #define PG8_WAIT_V(n) asm volatile("s_waitcnt vmcnt(" #n ")" ::: "memory")
; #define PG8_WAIT_L(n) asm volatile("s_waitcnt lgkmcnt(" #n ")" ::: "memory")
; #define PG8_BAR __builtin_amdgcn_s_barrier()
; #define PG8_SCHED __builtin_amdgcn_sched_barrier(0)
; template <class Epi, class Sched, bool ALIGN_EPI = false, bool SP2 = false, bool I8 = false>
; __device__ __forceinline__ void gemm_phase(PG8_LAS unsigned char* lds, const Gemm g, const Sched& S, const Epi& E) {
;     ...
;         const bool has_next = S.next(ui + 1, nxt);
;         const char* nA = has_next ? (const char*)g.A + (size_t)nxt.pm * tstep : cA; const char* nB = has_next ? (const char*)g.Bt + (size_t)nxt.pn * tstep : cB;
;         for (int t = 0; t < nt; t += 2) {
;             const bool last = (t == nt - 2);
;             const char* a1 = cA + (size_t)(t + 1) * kstep;
;             const char* a2 = last ? nA : cA + (size_t)(t + 2) * kstep; const char* b2 = last ? nB : cB + (size_t)(t + 2) * kstep;
;             const char* a3 = a2 + kstep; const char* b3 = b2 + kstep;
;             if (last && has_next) S.a_ready(nxt);
;             if constexpr (SP2) {
;             PG8_LDB(B0, 0, 0); PG8_LDB(B1, 0, 1); PG8_SCHED; PG8_LDA(At, 0, 0); PG8_STAGE(PG8_SA(1, 1), a1 + hstep, voffA);
;             PG8_WAIT_V(8); PG8_WAIT_L(0); PG8_BAR; PG8_MMA(0, 0, At, B0); PG8_MMA(0, 1, At, B1); PG8_BAR; PG8_SCHED;
;             PG8_LDA(At, 0, 1); PG8_STAGE(PG8_SB(0, 0), b2, voffB); PG8_STAGE(PG8_SB(0, 1), b2 + hstep, voffB); PG8_STAGE(PG8_SA(0, 0), a2, voffA);
;             PG8_WAIT_V(8); PG8_WAIT_L(0); PG8_BAR; PG8_MMA(1, 0, At, B0); PG8_MMA(1, 1, At, B1); PG8_BAR; PG8_SCHED;
.LBB0_229:
	s_ashr_i32 s37, s36, 31
	s_lshl_b64 s[34:35], s[36:37], 21
	s_add_u32 s40, s42, s34
	s_addc_u32 s41, s43, s35
	s_and_b64 s[34:35], s[8:9], exec
	s_cselect_b32 s11, s41, s13
	s_cselect_b32 s34, s40, s12
	s_ashr_i32 s27, s26, 31
	s_lshl_b64 s[50:51], s[26:27], 21
	s_add_u32 s54, s44, s50
	s_addc_u32 s55, s45, s51
	s_and_b64 s[50:51], s[8:9], exec
	s_cselect_b32 s27, s55, s73
	s_cselect_b32 s35, s54, s72
	s_add_u32 s12, s12, 0x100080
	s_addc_u32 s13, s13, 0
	s_add_u32 s37, s72, 0x100
	s_addc_u32 s61, s73, 0
	s_mov_b32 s97, -2
	s_add_u32 s50, s12, 0xfff00080
	s_addc_u32 s51, s13, -1
	s_add_i32 s56, 0, 0x10000
	s_cmp_eq_u32 s97, 60
	s_cselect_b32 s77, s11, s51
	s_cselect_b32 s76, s34, s50
	s_cselect_b32 s73, s27, s61
	s_cselect_b32 s72, s35, s37
	s_add_i32 s57, 0, 0x14000
	v_add_u32_e32 v156, s56, v171
	v_add_u32_e32 v168, s57, v171
	s_waitcnt vmcnt(0)
	ds_read_b128 v[112:115], v156
	ds_read_b128 v[120:123], v156 offset:1024
	ds_read_b128 v[152:155], v156 offset:2048
	ds_read_b128 v[156:159], v156 offset:3072
	ds_read_b128 v[160:163], v168
	ds_read_b128 v[164:167], v168 offset:1024
	s_waitcnt lgkmcnt(0)
	ds_read_b128 v[176:179], v168 offset:2048
	ds_read_b128 v[180:183], v168 offset:3072
	v_lshl_add_u64 v[168:169], s[12:13], 0, v[148:149]
	s_add_i32 m0, s47, 0xc000
	ds_read_b128 v[184:187], v173
	ds_read_b128 v[188:191], v173 offset:1024
	ds_read_b128 v[204:207], v173 offset:2048
	ds_read_b128 v[208:211], v173 offset:3072
	ds_read_b128 v[212:215], v173 offset:4096
	ds_read_b128 v[216:219], v173 offset:5120
	ds_read_b128 v[220:223], v173 offset:6144
	ds_read_b128 v[224:227], v173 offset:7168
	global_load_lds_dwordx4 v[168:169], off
	v_lshl_add_u64 v[168:169], s[12:13], 0, v[150:151]
	s_add_i32 m0, s47, 0xe000
	s_nop 0
	global_load_lds_dwordx4 v[168:169], off
	s_waitcnt vmcnt(8)
	s_waitcnt lgkmcnt(0)
	s_barrier
	s_setprio 1
	s_waitcnt lgkmcnt(0)
	v_mfma_f32_16x16x32_bf16 v[136:139], v[112:115], v[184:187], 0
	v_mfma_f32_16x16x32_bf16 v[136:139], v[120:123], v[188:191], v[136:139]
	v_mfma_f32_16x16x32_bf16 v[116:119], v[120:123], v[208:211], 0
	v_mfma_f32_16x16x32_bf16 v[116:119], v[112:115], v[204:207], v[116:119]
	v_mfma_f32_16x16x32_bf16 v[96:99], v[112:115], v[212:215], 0
	v_mfma_f32_16x16x32_bf16 v[96:99], v[120:123], v[216:219], v[96:99]
	v_mfma_f32_16x16x32_bf16 v[80:83], v[120:123], v[224:227], 0
	v_mfma_f32_16x16x32_bf16 v[80:83], v[112:115], v[220:223], v[80:83]
	v_mfma_f32_16x16x32_bf16 v[76:79], v[152:155], v[220:223], 0
	v_mfma_f32_16x16x32_bf16 v[76:79], v[156:159], v[224:227], v[76:79]
	v_mfma_f32_16x16x32_bf16 v[92:95], v[156:159], v[216:219], 0
	v_mfma_f32_16x16x32_bf16 v[92:95], v[152:155], v[212:215], v[92:95]
	v_mfma_f32_16x16x32_bf16 v[108:111], v[152:155], v[204:207], 0
	v_mfma_f32_16x16x32_bf16 v[108:111], v[156:159], v[208:211], v[108:111]
	v_mfma_f32_16x16x32_bf16 v[132:135], v[156:159], v[188:191], 0
	v_mfma_f32_16x16x32_bf16 v[132:135], v[152:155], v[184:187], v[132:135]
	v_mfma_f32_16x16x32_bf16 v[128:131], v[160:163], v[184:187], 0
	v_mfma_f32_16x16x32_bf16 v[128:131], v[164:167], v[188:191], v[128:131]
	v_mfma_f32_16x16x32_bf16 v[104:107], v[164:167], v[208:211], 0
	v_mfma_f32_16x16x32_bf16 v[104:107], v[160:163], v[204:207], v[104:107]
	v_mfma_f32_16x16x32_bf16 v[88:91], v[160:163], v[212:215], 0
	v_mfma_f32_16x16x32_bf16 v[88:91], v[164:167], v[216:219], v[88:91]
	v_mfma_f32_16x16x32_bf16 v[72:75], v[164:167], v[224:227], 0
	v_mfma_f32_16x16x32_bf16 v[72:75], v[160:163], v[220:223], v[72:75]
	v_mfma_f32_16x16x32_bf16 v[68:71], v[176:179], v[220:223], 0
	v_mfma_f32_16x16x32_bf16 v[68:71], v[180:183], v[224:227], v[68:71]
	v_mfma_f32_16x16x32_bf16 v[84:87], v[180:183], v[216:219], 0
	v_mfma_f32_16x16x32_bf16 v[84:87], v[176:179], v[212:215], v[84:87]
	v_mfma_f32_16x16x32_bf16 v[100:103], v[176:179], v[204:207], 0
	v_mfma_f32_16x16x32_bf16 v[100:103], v[180:183], v[208:211], v[100:103]
	v_mfma_f32_16x16x32_bf16 v[124:127], v[180:183], v[188:191], 0
	v_mfma_f32_16x16x32_bf16 v[124:127], v[176:179], v[184:187], v[124:127]
	s_setprio 0
	s_barrier
	s_add_i32 s50, s56, s46
	v_lshl_add_u64 v[168:169], s[72:73], 0, v[2:3]
	s_mov_b32 m0, s50
	ds_read_b128 v[184:187], v173 offset:16384
	ds_read_b128 v[188:191], v173 offset:17408
	ds_read_b128 v[204:207], v173 offset:18432
	ds_read_b128 v[208:211], v173 offset:19456
	ds_read_b128 v[212:215], v173 offset:20480
	ds_read_b128 v[216:219], v173 offset:21504
	ds_read_b128 v[220:223], v173 offset:22528
	ds_read_b128 v[224:227], v173 offset:23552
	global_load_lds_dwordx4 v[168:169], off
	s_add_i32 m0, s50, 0x2000
	s_add_u32 s50, s72, 0x100000
	v_lshl_add_u64 v[228:229], s[72:73], 0, v[144:145]
	s_addc_u32 s51, s73, 0
	s_add_i32 s56, s57, s46
	global_load_lds_dwordx4 v[228:229], off
	v_lshl_add_u64 v[240:241], s[50:51], 0, v[2:3]
	s_mov_b32 m0, s56
	v_lshl_add_u64 v[242:243], s[76:77], 0, v[142:143]
	global_load_lds_dwordx4 v[240:241], off
	v_lshl_add_u64 v[240:241], s[50:51], 0, v[144:145]
	s_add_i32 m0, s56, 0x2000
	s_nop 0
	global_load_lds_dwordx4 v[240:241], off
	v_lshl_add_u64 v[240:241], s[76:77], 0, v[140:141]
	s_waitcnt vmcnt(6)
	s_waitcnt lgkmcnt(0)
	s_barrier
; #define PG8_STAGE(bufoff, gbase, voff) do { _Pragma("unroll") for (int _i = 0; _i < 2; ++_i) \
;         __builtin_amdgcn_global_load_lds((const unsigned*)((const char*)(gbase) + (voff)[_i]), (PG8_LAS unsigned*)(lds + (bufoff) + ldsw + _i * 8192), 16, 0, 0); } while (0)
; #define PG8_LDA(dst, b, h) do { _Pragma("unroll") for (int m = 0; m < 4; ++m) _Pragma("unroll") for (int k = 0; k < 2; ++k) dst[m][k] = *(const PG8_LAS bf16x8*)(lds + PG8_SA(b, h) + aoff + m * 2048 + k * 1024); } while (0)
; #define PG8_LDB(dst, b, h) do { _Pragma("unroll") for (int n = 0; n < 2; ++n) _Pragma("unroll") for (int k = 0; k < 2; ++k) dst[n][k] = *(const PG8_LAS bf16x8*)(lds + PG8_SB(b, h) + boff + n * 2048 + k * 1024); } while (0)
; #define PG8_WAIT_V(n) asm volatile("s_waitcnt vmcnt(" #n ")" ::: "memory")
; #define PG8_WAIT_L(n) asm volatile("s_waitcnt lgkmcnt(" #n ")" ::: "memory")
; #define PG8_BAR __builtin_amdgcn_s_barrier()
; #define PG8_SCHED __builtin_amdgcn_sched_barrier(0)
; template <class Epi, class Sched, bool ALIGN_EPI = false, bool SP2 = false, bool I8 = false>
; __device__ __forceinline__ void gemm_phase(PG8_LAS unsigned char* lds, const Gemm g, const Sched& S, const Epi& E) {
;     ...
;             PG8_WAIT_V(8); PG8_WAIT_L(0); PG8_BAR; PG8_MMA(1, 0, At, B0); PG8_MMA(1, 1, At, B1); PG8_BAR; PG8_SCHED;
;             PG8_LDB(B0, 1, 0); PG8_LDB(B1, 1, 1); PG8_SCHED; PG8_LDA(At, 1, 0); PG8_STAGE(PG8_SA(0, 1), a2 + hstep, voffA);
;             PG8_WAIT_V(8); PG8_WAIT_L(0); PG8_BAR; PG8_MMA(0, 0, At, B0); PG8_MMA(0, 1, At, B1); PG8_BAR; PG8_SCHED;
;             PG8_LDA(At, 1, 1); PG8_STAGE(PG8_SB(1, 0), b3, voffB); PG8_STAGE(PG8_SB(1, 1), b3 + hstep, voffB); PG8_STAGE(PG8_SA(1, 0), a3, voffA);
;             PG8_WAIT_V(8); PG8_WAIT_L(0); PG8_BAR; PG8_MMA(1, 0, At, B0); PG8_MMA(1, 1, At, B1); PG8_BAR; PG8_SCHED;
	s_setprio 1
	s_waitcnt lgkmcnt(0)
	v_mfma_f32_16x16x32_bf16 v[64:67], v[112:115], v[184:187], 0
	v_mfma_f32_16x16x32_bf16 v[64:67], v[120:123], v[188:191], v[64:67]
	v_mfma_f32_16x16x32_bf16 v[48:51], v[120:123], v[208:211], 0
	v_mfma_f32_16x16x32_bf16 v[48:51], v[112:115], v[204:207], v[48:51]
	v_mfma_f32_16x16x32_bf16 v[32:35], v[112:115], v[212:215], 0
	v_mfma_f32_16x16x32_bf16 v[32:35], v[120:123], v[216:219], v[32:35]
	v_mfma_f32_16x16x32_bf16 v[16:19], v[120:123], v[224:227], 0
	v_mfma_f32_16x16x32_bf16 v[16:19], v[112:115], v[220:223], v[16:19]
	v_mfma_f32_16x16x32_bf16 v[12:15], v[152:155], v[220:223], 0
	v_mfma_f32_16x16x32_bf16 v[12:15], v[156:159], v[224:227], v[12:15]
	v_mfma_f32_16x16x32_bf16 v[28:31], v[156:159], v[216:219], 0
	v_mfma_f32_16x16x32_bf16 v[28:31], v[152:155], v[212:215], v[28:31]
	v_mfma_f32_16x16x32_bf16 v[44:47], v[152:155], v[204:207], 0
	v_mfma_f32_16x16x32_bf16 v[44:47], v[156:159], v[208:211], v[44:47]
	v_mfma_f32_16x16x32_bf16 v[60:63], v[156:159], v[188:191], 0
	v_mfma_f32_16x16x32_bf16 v[60:63], v[152:155], v[184:187], v[60:63]
	v_mfma_f32_16x16x32_bf16 v[56:59], v[160:163], v[184:187], 0
	v_mfma_f32_16x16x32_bf16 v[56:59], v[164:167], v[188:191], v[56:59]
	v_mfma_f32_16x16x32_bf16 v[40:43], v[164:167], v[208:211], 0
	v_mfma_f32_16x16x32_bf16 v[40:43], v[160:163], v[204:207], v[40:43]
	v_mfma_f32_16x16x32_bf16 v[24:27], v[160:163], v[212:215], 0
	v_mfma_f32_16x16x32_bf16 v[24:27], v[164:167], v[216:219], v[24:27]
	v_mfma_f32_16x16x32_bf16 v[8:11], v[164:167], v[224:227], 0
	v_mfma_f32_16x16x32_bf16 v[8:11], v[160:163], v[220:223], v[8:11]
	v_mfma_f32_16x16x32_bf16 v[4:7], v[176:179], v[220:223], 0
	v_mfma_f32_16x16x32_bf16 v[4:7], v[180:183], v[224:227], v[4:7]
	v_mfma_f32_16x16x32_bf16 v[20:23], v[180:183], v[216:219], 0
	v_mfma_f32_16x16x32_bf16 v[20:23], v[176:179], v[212:215], v[20:23]
	v_mfma_f32_16x16x32_bf16 v[36:39], v[176:179], v[204:207], 0
	v_mfma_f32_16x16x32_bf16 v[36:39], v[180:183], v[208:211], v[36:39]
	v_mfma_f32_16x16x32_bf16 v[52:55], v[180:183], v[188:191], 0
	v_mfma_f32_16x16x32_bf16 v[52:55], v[176:179], v[184:187], v[52:55]
	s_setprio 0
	s_barrier
	s_mov_b32 m0, s47
	s_nop 0
	global_load_lds_dwordx4 v[240:241], off
	s_mov_b32 m0, s52
	s_nop 0
	global_load_lds_dwordx4 v[242:243], off
	s_add_i32 s56, 0, 0x18000
	s_add_i32 s57, 0, 0x1c000
	v_add_u32_e32 v156, s56, v171
	v_add_u32_e32 v175, s57, v171
	ds_read_b128 v[112:115], v156
	ds_read_b128 v[120:123], v156 offset:1024
	ds_read_b128 v[152:155], v156 offset:2048
	ds_read_b128 v[156:159], v156 offset:3072
	ds_read_b128 v[160:163], v175
	ds_read_b128 v[164:167], v175 offset:1024
	ds_read_b128 v[176:179], v175 offset:2048
	ds_read_b128 v[180:183], v175 offset:3072
	s_add_u32 s50, s76, 0x100000
	s_addc_u32 s51, s77, 0
	s_mov_b32 m0, s53
	v_lshl_add_u64 v[244:245], s[50:51], 0, v[140:141]
	ds_read_b128 v[184:187], v173 offset:32768
	ds_read_b128 v[188:191], v173 offset:33792
	ds_read_b128 v[204:207], v173 offset:34816
	ds_read_b128 v[208:211], v173 offset:35840
	ds_read_b128 v[212:215], v173 offset:36864
	ds_read_b128 v[216:219], v173 offset:37888
	ds_read_b128 v[220:223], v173 offset:38912
	ds_read_b128 v[224:227], v173 offset:39936
	global_load_lds_dwordx4 v[244:245], off
	v_lshl_add_u64 v[244:245], s[50:51], 0, v[142:143]
	s_mov_b32 m0, s64
	s_nop 0
	global_load_lds_dwordx4 v[244:245], off
	s_waitcnt vmcnt(8)
	s_waitcnt lgkmcnt(0)
	s_barrier
	s_setprio 1
	s_waitcnt lgkmcnt(0)
	v_mfma_f32_16x16x32_bf16 v[136:139], v[112:115], v[184:187], v[136:139]
	v_mfma_f32_16x16x32_bf16 v[136:139], v[120:123], v[188:191], v[136:139]
	v_mfma_f32_16x16x32_bf16 v[116:119], v[120:123], v[208:211], v[116:119]
	v_mfma_f32_16x16x32_bf16 v[116:119], v[112:115], v[204:207], v[116:119]
	v_mfma_f32_16x16x32_bf16 v[96:99], v[112:115], v[212:215], v[96:99]
	v_mfma_f32_16x16x32_bf16 v[96:99], v[120:123], v[216:219], v[96:99]
	v_mfma_f32_16x16x32_bf16 v[80:83], v[120:123], v[224:227], v[80:83]
	v_mfma_f32_16x16x32_bf16 v[80:83], v[112:115], v[220:223], v[80:83]
	v_mfma_f32_16x16x32_bf16 v[76:79], v[152:155], v[220:223], v[76:79]
	v_mfma_f32_16x16x32_bf16 v[76:79], v[156:159], v[224:227], v[76:79]
	v_mfma_f32_16x16x32_bf16 v[92:95], v[156:159], v[216:219], v[92:95]
	v_mfma_f32_16x16x32_bf16 v[92:95], v[152:155], v[212:215], v[92:95]
	v_mfma_f32_16x16x32_bf16 v[108:111], v[152:155], v[204:207], v[108:111]
	v_mfma_f32_16x16x32_bf16 v[108:111], v[156:159], v[208:211], v[108:111]
	v_mfma_f32_16x16x32_bf16 v[132:135], v[156:159], v[188:191], v[132:135]
	v_mfma_f32_16x16x32_bf16 v[132:135], v[152:155], v[184:187], v[132:135]
	v_mfma_f32_16x16x32_bf16 v[128:131], v[160:163], v[184:187], v[128:131]
	v_mfma_f32_16x16x32_bf16 v[128:131], v[164:167], v[188:191], v[128:131]
	v_mfma_f32_16x16x32_bf16 v[104:107], v[164:167], v[208:211], v[104:107]
	v_mfma_f32_16x16x32_bf16 v[104:107], v[160:163], v[204:207], v[104:107]
	v_mfma_f32_16x16x32_bf16 v[88:91], v[160:163], v[212:215], v[88:91]
	v_mfma_f32_16x16x32_bf16 v[88:91], v[164:167], v[216:219], v[88:91]
	v_mfma_f32_16x16x32_bf16 v[72:75], v[164:167], v[224:227], v[72:75]
	v_mfma_f32_16x16x32_bf16 v[72:75], v[160:163], v[220:223], v[72:75]
	v_mfma_f32_16x16x32_bf16 v[68:71], v[176:179], v[220:223], v[68:71]
	v_mfma_f32_16x16x32_bf16 v[68:71], v[180:183], v[224:227], v[68:71]
	v_mfma_f32_16x16x32_bf16 v[84:87], v[180:183], v[216:219], v[84:87]
	v_mfma_f32_16x16x32_bf16 v[84:87], v[176:179], v[212:215], v[84:87]
	v_mfma_f32_16x16x32_bf16 v[100:103], v[176:179], v[204:207], v[100:103]
	v_mfma_f32_16x16x32_bf16 v[100:103], v[180:183], v[208:211], v[100:103]
	v_mfma_f32_16x16x32_bf16 v[124:127], v[180:183], v[188:191], v[124:127]
	v_mfma_f32_16x16x32_bf16 v[124:127], v[176:179], v[184:187], v[124:127]
	s_setprio 0
	s_barrier
	s_add_i32 s50, s56, s46
	v_lshl_add_u64 v[168:169], v[168:169], 0, s[84:85]
	s_mov_b32 m0, s50
	ds_read_b128 v[184:187], v173 offset:49152
	ds_read_b128 v[188:191], v173 offset:50176
	ds_read_b128 v[204:207], v173 offset:51200
	ds_read_b128 v[208:211], v173 offset:52224
	ds_read_b128 v[212:215], v173 offset:53248
	ds_read_b128 v[216:219], v173 offset:54272
	ds_read_b128 v[220:223], v173 offset:55296
	ds_read_b128 v[224:227], v173 offset:56320
	global_load_lds_dwordx4 v[168:169], off
	s_add_i32 m0, s50, 0x2000
	s_add_u32 s50, s72, 0x100080
	v_lshl_add_u64 v[168:169], v[228:229], 0, s[84:85]
	s_addc_u32 s51, s73, 0
	s_add_i32 s56, s57, s46
	global_load_lds_dwordx4 v[168:169], off
	v_lshl_add_u64 v[168:169], s[50:51], 0, v[2:3]
	s_mov_b32 m0, s56
	s_nop 0
	global_load_lds_dwordx4 v[168:169], off
	v_lshl_add_u64 v[168:169], s[50:51], 0, v[144:145]
	s_add_i32 m0, s56, 0x2000
	s_nop 0
	global_load_lds_dwordx4 v[168:169], off
	s_cmp_eq_u32 s97, 60
	s_cbranch_scc0 .Ldefer_230_peel
	v_lshl_add_u64 v[168:169], v[240:241], 0, s[84:85]
	s_mov_b32 m0, s28
	s_nop 0
	global_load_lds_dwordx4 v[168:169], off
	v_lshl_add_u64 v[168:169], v[242:243], 0, s[84:85]
	s_mov_b32 m0, s65
	s_nop 0
	global_load_lds_dwordx4 v[168:169], off
; #define PG8_STAGE(bufoff, gbase, voff) do { _Pragma("unroll") for (int _i = 0; _i < 2; ++_i) \
;         __builtin_amdgcn_global_load_lds((const unsigned*)((const char*)(gbase) + (voff)[_i]), (PG8_LAS unsigned*)(lds + (bufoff) + ldsw + _i * 8192), 16, 0, 0); } while (0)
; #define PG8_LDA(dst, b, h) do { _Pragma("unroll") for (int m = 0; m < 4; ++m) _Pragma("unroll") for (int k = 0; k < 2; ++k) dst[m][k] = *(const PG8_LAS bf16x8*)(lds + PG8_SA(b, h) + aoff + m * 2048 + k * 1024); } while (0)
; #define PG8_WAIT_V(n) asm volatile("s_waitcnt vmcnt(" #n ")" ::: "memory")
; #define PG8_WAIT_L(n) asm volatile("s_waitcnt lgkmcnt(" #n ")" ::: "memory")
; #define PG8_BAR __builtin_amdgcn_s_barrier()
; template <class Epi, class Sched, bool ALIGN_EPI = false, bool SP2 = false, bool I8 = false>
; __device__ __forceinline__ void gemm_phase(PG8_LAS unsigned char* lds, const Gemm g, const Sched& S, const Epi& E) {
;     ...
;         for (int t = 0; t < nt; t += 2) {
;             const bool last = (t == nt - 2);
;             const char* a1 = cA + (size_t)(t + 1) * kstep;
;             const char* a2 = last ? nA : cA + (size_t)(t + 2) * kstep; const char* b2 = last ? nB : cB + (size_t)(t + 2) * kstep;
;             const char* a3 = a2 + kstep; const char* b3 = b2 + kstep;
;             if (last && has_next) S.a_ready(nxt);
;             if constexpr (SP2) {
;             PG8_LDB(B0, 0, 0); PG8_LDB(B1, 0, 1); PG8_SCHED; PG8_LDA(At, 0, 0); PG8_STAGE(PG8_SA(1, 1), a1 + hstep, voffA);
;             PG8_WAIT_V(8); PG8_WAIT_L(0); PG8_BAR; PG8_MMA(0, 0, At, B0); PG8_MMA(0, 1, At, B1); PG8_BAR; PG8_SCHED;
;             PG8_LDA(At, 0, 1); PG8_STAGE(PG8_SB(0, 0), b2, voffB); PG8_STAGE(PG8_SB(0, 1), b2 + hstep, voffB); PG8_STAGE(PG8_SA(0, 0), a2, voffA);
;             PG8_WAIT_V(8); PG8_WAIT_L(0); PG8_BAR; PG8_MMA(1, 0, At, B0); PG8_MMA(1, 1, At, B1); PG8_BAR; PG8_SCHED;
;             PG8_LDB(B0, 1, 0); PG8_LDB(B1, 1, 1); PG8_SCHED; PG8_LDA(At, 1, 0); PG8_STAGE(PG8_SA(0, 1), a2 + hstep, voffA);
;             PG8_WAIT_V(8); PG8_WAIT_L(0); PG8_BAR; PG8_MMA(0, 0, At, B0); PG8_MMA(0, 1, At, B1); PG8_BAR; PG8_SCHED;
;             PG8_LDA(At, 1, 1); PG8_STAGE(PG8_SB(1, 0), b3, voffB); PG8_STAGE(PG8_SB(1, 1), b3 + hstep, voffB); PG8_STAGE(PG8_SA(1, 0), a3, voffA);
;             PG8_WAIT_V(8); PG8_WAIT_L(0); PG8_BAR; PG8_MMA(1, 0, At, B0); PG8_MMA(1, 1, At, B1); PG8_BAR; PG8_SCHED;
.Ldefer_230_peel:
	s_waitcnt vmcnt(6)
	s_waitcnt lgkmcnt(0)
	s_barrier
	s_setprio 1
	s_waitcnt lgkmcnt(0)
	v_mfma_f32_16x16x32_bf16 v[64:67], v[112:115], v[184:187], v[64:67]
	v_mfma_f32_16x16x32_bf16 v[64:67], v[120:123], v[188:191], v[64:67]
	v_mfma_f32_16x16x32_bf16 v[48:51], v[120:123], v[208:211], v[48:51]
	v_mfma_f32_16x16x32_bf16 v[48:51], v[112:115], v[204:207], v[48:51]
	v_mfma_f32_16x16x32_bf16 v[32:35], v[112:115], v[212:215], v[32:35]
	v_mfma_f32_16x16x32_bf16 v[32:35], v[120:123], v[216:219], v[32:35]
	v_mfma_f32_16x16x32_bf16 v[16:19], v[120:123], v[224:227], v[16:19]
	v_mfma_f32_16x16x32_bf16 v[16:19], v[112:115], v[220:223], v[16:19]
	v_mfma_f32_16x16x32_bf16 v[12:15], v[152:155], v[220:223], v[12:15]
	v_mfma_f32_16x16x32_bf16 v[12:15], v[156:159], v[224:227], v[12:15]
	v_mfma_f32_16x16x32_bf16 v[28:31], v[156:159], v[216:219], v[28:31]
	v_mfma_f32_16x16x32_bf16 v[28:31], v[152:155], v[212:215], v[28:31]
	v_mfma_f32_16x16x32_bf16 v[44:47], v[152:155], v[204:207], v[44:47]
	v_mfma_f32_16x16x32_bf16 v[44:47], v[156:159], v[208:211], v[44:47]
	v_mfma_f32_16x16x32_bf16 v[60:63], v[156:159], v[188:191], v[60:63]
	v_mfma_f32_16x16x32_bf16 v[60:63], v[152:155], v[184:187], v[60:63]
	v_mfma_f32_16x16x32_bf16 v[56:59], v[160:163], v[184:187], v[56:59]
	v_mfma_f32_16x16x32_bf16 v[56:59], v[164:167], v[188:191], v[56:59]
	v_mfma_f32_16x16x32_bf16 v[40:43], v[164:167], v[208:211], v[40:43]
	v_mfma_f32_16x16x32_bf16 v[40:43], v[160:163], v[204:207], v[40:43]
	v_mfma_f32_16x16x32_bf16 v[24:27], v[160:163], v[212:215], v[24:27]
	v_mfma_f32_16x16x32_bf16 v[24:27], v[164:167], v[216:219], v[24:27]
	v_mfma_f32_16x16x32_bf16 v[8:11], v[164:167], v[224:227], v[8:11]
	v_mfma_f32_16x16x32_bf16 v[8:11], v[160:163], v[220:223], v[8:11]
	v_mfma_f32_16x16x32_bf16 v[4:7], v[176:179], v[220:223], v[4:7]
	v_mfma_f32_16x16x32_bf16 v[4:7], v[180:183], v[224:227], v[4:7]
	v_mfma_f32_16x16x32_bf16 v[20:23], v[180:183], v[216:219], v[20:23]
	v_mfma_f32_16x16x32_bf16 v[20:23], v[176:179], v[212:215], v[20:23]
	v_mfma_f32_16x16x32_bf16 v[36:39], v[176:179], v[204:207], v[36:39]
	v_mfma_f32_16x16x32_bf16 v[36:39], v[180:183], v[208:211], v[36:39]
	v_mfma_f32_16x16x32_bf16 v[52:55], v[180:183], v[188:191], v[52:55]
	v_mfma_f32_16x16x32_bf16 v[52:55], v[176:179], v[184:187], v[52:55]
	s_setprio 0
	s_barrier
	s_add_i32 s97, s97, 2
	s_add_u32 s12, s12, 0x100
	s_addc_u32 s13, s13, 0
	s_add_u32 s37, s37, 0x100
	s_addc_u32 s61, s61, 0
	s_cmp_gt_u32 s97, 61
	s_cbranch_scc1 .Lkloop_exit_1
.LBB0_230:
	s_add_u32 s50, s12, 0xfff00080
	s_addc_u32 s51, s13, -1
	s_add_i32 s56, 0, 0x10000
	s_cmp_eq_u32 s97, 60
	s_cselect_b32 s77, s11, s51
	s_cselect_b32 s76, s34, s50
	s_cselect_b32 s73, s27, s61
	s_cselect_b32 s72, s35, s37
	s_add_i32 s57, 0, 0x14000
	v_add_u32_e32 v156, s56, v171
	v_add_u32_e32 v168, s57, v171
	ds_read_b128 v[112:115], v156
	ds_read_b128 v[120:123], v156 offset:1024
	ds_read_b128 v[152:155], v156 offset:2048
	ds_read_b128 v[156:159], v156 offset:3072
	ds_read_b128 v[160:163], v168
	ds_read_b128 v[164:167], v168 offset:1024
	ds_read_b128 v[176:179], v168 offset:2048
	ds_read_b128 v[180:183], v168 offset:3072
	v_lshl_add_u64 v[168:169], v[240:241], 0, s[84:85]
	s_mov_b32 m0, s28
	s_nop 0
	global_load_lds_dwordx4 v[168:169], off
	v_lshl_add_u64 v[168:169], v[242:243], 0, s[84:85]
	s_mov_b32 m0, s65
	s_nop 0
	global_load_lds_dwordx4 v[168:169], off
	v_lshl_add_u64 v[168:169], s[12:13], 0, v[148:149]
	s_add_i32 m0, s47, 0xc000
	ds_read_b128 v[184:187], v173
	ds_read_b128 v[188:191], v173 offset:1024
	ds_read_b128 v[204:207], v173 offset:2048
	ds_read_b128 v[208:211], v173 offset:3072
	ds_read_b128 v[212:215], v173 offset:4096
	ds_read_b128 v[216:219], v173 offset:5120
	ds_read_b128 v[220:223], v173 offset:6144
	ds_read_b128 v[224:227], v173 offset:7168
	global_load_lds_dwordx4 v[168:169], off
	v_lshl_add_u64 v[168:169], s[12:13], 0, v[150:151]
	s_add_i32 m0, s47, 0xe000
	s_nop 0
	global_load_lds_dwordx4 v[168:169], off
	s_waitcnt vmcnt(8)
	s_waitcnt lgkmcnt(0)
	s_barrier
	s_setprio 1
	s_waitcnt lgkmcnt(0)
	v_mfma_f32_16x16x32_bf16 v[136:139], v[112:115], v[184:187], v[136:139]
	v_mfma_f32_16x16x32_bf16 v[136:139], v[120:123], v[188:191], v[136:139]
	v_mfma_f32_16x16x32_bf16 v[116:119], v[120:123], v[208:211], v[116:119]
	v_mfma_f32_16x16x32_bf16 v[116:119], v[112:115], v[204:207], v[116:119]
	v_mfma_f32_16x16x32_bf16 v[96:99], v[112:115], v[212:215], v[96:99]
	v_mfma_f32_16x16x32_bf16 v[96:99], v[120:123], v[216:219], v[96:99]
	v_mfma_f32_16x16x32_bf16 v[80:83], v[120:123], v[224:227], v[80:83]
	v_mfma_f32_16x16x32_bf16 v[80:83], v[112:115], v[220:223], v[80:83]
	v_mfma_f32_16x16x32_bf16 v[76:79], v[152:155], v[220:223], v[76:79]
	v_mfma_f32_16x16x32_bf16 v[76:79], v[156:159], v[224:227], v[76:79]
	v_mfma_f32_16x16x32_bf16 v[92:95], v[156:159], v[216:219], v[92:95]
	v_mfma_f32_16x16x32_bf16 v[92:95], v[152:155], v[212:215], v[92:95]
	v_mfma_f32_16x16x32_bf16 v[108:111], v[152:155], v[204:207], v[108:111]
	v_mfma_f32_16x16x32_bf16 v[108:111], v[156:159], v[208:211], v[108:111]
	v_mfma_f32_16x16x32_bf16 v[132:135], v[156:159], v[188:191], v[132:135]
	v_mfma_f32_16x16x32_bf16 v[132:135], v[152:155], v[184:187], v[132:135]
	v_mfma_f32_16x16x32_bf16 v[128:131], v[160:163], v[184:187], v[128:131]
	v_mfma_f32_16x16x32_bf16 v[128:131], v[164:167], v[188:191], v[128:131]
	v_mfma_f32_16x16x32_bf16 v[104:107], v[164:167], v[208:211], v[104:107]
	v_mfma_f32_16x16x32_bf16 v[104:107], v[160:163], v[204:207], v[104:107]
	v_mfma_f32_16x16x32_bf16 v[88:91], v[160:163], v[212:215], v[88:91]
	v_mfma_f32_16x16x32_bf16 v[88:91], v[164:167], v[216:219], v[88:91]
	v_mfma_f32_16x16x32_bf16 v[72:75], v[164:167], v[224:227], v[72:75]
	v_mfma_f32_16x16x32_bf16 v[72:75], v[160:163], v[220:223], v[72:75]
	v_mfma_f32_16x16x32_bf16 v[68:71], v[176:179], v[220:223], v[68:71]
	v_mfma_f32_16x16x32_bf16 v[68:71], v[180:183], v[224:227], v[68:71]
	v_mfma_f32_16x16x32_bf16 v[84:87], v[180:183], v[216:219], v[84:87]
	v_mfma_f32_16x16x32_bf16 v[84:87], v[176:179], v[212:215], v[84:87]
	v_mfma_f32_16x16x32_bf16 v[100:103], v[176:179], v[204:207], v[100:103]
	v_mfma_f32_16x16x32_bf16 v[100:103], v[180:183], v[208:211], v[100:103]
	v_mfma_f32_16x16x32_bf16 v[124:127], v[180:183], v[188:191], v[124:127]
	v_mfma_f32_16x16x32_bf16 v[124:127], v[176:179], v[184:187], v[124:127]
	s_setprio 0
	s_barrier
; #define PG8_STAGE(bufoff, gbase, voff) do { _Pragma("unroll") for (int _i = 0; _i < 2; ++_i) \
;         __builtin_amdgcn_global_load_lds((const unsigned*)((const char*)(gbase) + (voff)[_i]), (PG8_LAS unsigned*)(lds + (bufoff) + ldsw + _i * 8192), 16, 0, 0); } while (0)
; #define PG8_LDA(dst, b, h) do { _Pragma("unroll") for (int m = 0; m < 4; ++m) _Pragma("unroll") for (int k = 0; k < 2; ++k) dst[m][k] = *(const PG8_LAS bf16x8*)(lds + PG8_SA(b, h) + aoff + m * 2048 + k * 1024); } while (0)
; #define PG8_LDB(dst, b, h) do { _Pragma("unroll") for (int n = 0; n < 2; ++n) _Pragma("unroll") for (int k = 0; k < 2; ++k) dst[n][k] = *(const PG8_LAS bf16x8*)(lds + PG8_SB(b, h) + boff + n * 2048 + k * 1024); } while (0)
; #define PG8_WAIT_V(n) asm volatile("s_waitcnt vmcnt(" #n ")" ::: "memory")
; #define PG8_WAIT_L(n) asm volatile("s_waitcnt lgkmcnt(" #n ")" ::: "memory")
; #define PG8_BAR __builtin_amdgcn_s_barrier()
; #define PG8_SCHED __builtin_amdgcn_sched_barrier(0)
; template <class Epi, class Sched, bool ALIGN_EPI = false, bool SP2 = false, bool I8 = false>
; __device__ __forceinline__ void gemm_phase(PG8_LAS unsigned char* lds, const Gemm g, const Sched& S, const Epi& E) {
;     ...
;             PG8_LDA(At, 0, 1); PG8_STAGE(PG8_SB(0, 0), b2, voffB); PG8_STAGE(PG8_SB(0, 1), b2 + hstep, voffB); PG8_STAGE(PG8_SA(0, 0), a2, voffA);
;             PG8_WAIT_V(8); PG8_WAIT_L(0); PG8_BAR; PG8_MMA(1, 0, At, B0); PG8_MMA(1, 1, At, B1); PG8_BAR; PG8_SCHED;
;             PG8_LDB(B0, 1, 0); PG8_LDB(B1, 1, 1); PG8_SCHED; PG8_LDA(At, 1, 0); PG8_STAGE(PG8_SA(0, 1), a2 + hstep, voffA);
;             PG8_WAIT_V(8); PG8_WAIT_L(0); PG8_BAR; PG8_MMA(0, 0, At, B0); PG8_MMA(0, 1, At, B1); PG8_BAR; PG8_SCHED;
	s_add_i32 s50, s56, s46
	v_lshl_add_u64 v[168:169], s[72:73], 0, v[2:3]
	s_mov_b32 m0, s50
	ds_read_b128 v[184:187], v173 offset:16384
	ds_read_b128 v[188:191], v173 offset:17408
	ds_read_b128 v[204:207], v173 offset:18432
	ds_read_b128 v[208:211], v173 offset:19456
	ds_read_b128 v[212:215], v173 offset:20480
	ds_read_b128 v[216:219], v173 offset:21504
	ds_read_b128 v[220:223], v173 offset:22528
	ds_read_b128 v[224:227], v173 offset:23552
	global_load_lds_dwordx4 v[168:169], off
	s_add_i32 m0, s50, 0x2000
	s_add_u32 s50, s72, 0x100000
	v_lshl_add_u64 v[228:229], s[72:73], 0, v[144:145]
	s_addc_u32 s51, s73, 0
	s_add_i32 s56, s57, s46
	global_load_lds_dwordx4 v[228:229], off
	v_lshl_add_u64 v[240:241], s[50:51], 0, v[2:3]
	s_mov_b32 m0, s56
	v_lshl_add_u64 v[242:243], s[76:77], 0, v[142:143]
	global_load_lds_dwordx4 v[240:241], off
	v_lshl_add_u64 v[240:241], s[50:51], 0, v[144:145]
	s_add_i32 m0, s56, 0x2000
	s_nop 0
	global_load_lds_dwordx4 v[240:241], off
	v_lshl_add_u64 v[240:241], s[76:77], 0, v[140:141]
	s_waitcnt vmcnt(6)
	s_waitcnt lgkmcnt(0)
	s_barrier
	s_setprio 1
	s_waitcnt lgkmcnt(0)
	v_mfma_f32_16x16x32_bf16 v[64:67], v[112:115], v[184:187], v[64:67]
	v_mfma_f32_16x16x32_bf16 v[64:67], v[120:123], v[188:191], v[64:67]
	v_mfma_f32_16x16x32_bf16 v[48:51], v[120:123], v[208:211], v[48:51]
	v_mfma_f32_16x16x32_bf16 v[48:51], v[112:115], v[204:207], v[48:51]
	v_mfma_f32_16x16x32_bf16 v[32:35], v[112:115], v[212:215], v[32:35]
	v_mfma_f32_16x16x32_bf16 v[32:35], v[120:123], v[216:219], v[32:35]
	v_mfma_f32_16x16x32_bf16 v[16:19], v[120:123], v[224:227], v[16:19]
	v_mfma_f32_16x16x32_bf16 v[16:19], v[112:115], v[220:223], v[16:19]
	v_mfma_f32_16x16x32_bf16 v[12:15], v[152:155], v[220:223], v[12:15]
	v_mfma_f32_16x16x32_bf16 v[12:15], v[156:159], v[224:227], v[12:15]
	v_mfma_f32_16x16x32_bf16 v[28:31], v[156:159], v[216:219], v[28:31]
	v_mfma_f32_16x16x32_bf16 v[28:31], v[152:155], v[212:215], v[28:31]
	v_mfma_f32_16x16x32_bf16 v[44:47], v[152:155], v[204:207], v[44:47]
	v_mfma_f32_16x16x32_bf16 v[44:47], v[156:159], v[208:211], v[44:47]
	v_mfma_f32_16x16x32_bf16 v[60:63], v[156:159], v[188:191], v[60:63]
	v_mfma_f32_16x16x32_bf16 v[60:63], v[152:155], v[184:187], v[60:63]
	v_mfma_f32_16x16x32_bf16 v[56:59], v[160:163], v[184:187], v[56:59]
	v_mfma_f32_16x16x32_bf16 v[56:59], v[164:167], v[188:191], v[56:59]
	v_mfma_f32_16x16x32_bf16 v[40:43], v[164:167], v[208:211], v[40:43]
	v_mfma_f32_16x16x32_bf16 v[40:43], v[160:163], v[204:207], v[40:43]
	v_mfma_f32_16x16x32_bf16 v[24:27], v[160:163], v[212:215], v[24:27]
	v_mfma_f32_16x16x32_bf16 v[24:27], v[164:167], v[216:219], v[24:27]
	v_mfma_f32_16x16x32_bf16 v[8:11], v[164:167], v[224:227], v[8:11]
	v_mfma_f32_16x16x32_bf16 v[8:11], v[160:163], v[220:223], v[8:11]
	v_mfma_f32_16x16x32_bf16 v[4:7], v[176:179], v[220:223], v[4:7]
	v_mfma_f32_16x16x32_bf16 v[4:7], v[180:183], v[224:227], v[4:7]
	v_mfma_f32_16x16x32_bf16 v[20:23], v[180:183], v[216:219], v[20:23]
	v_mfma_f32_16x16x32_bf16 v[20:23], v[176:179], v[212:215], v[20:23]
	v_mfma_f32_16x16x32_bf16 v[36:39], v[176:179], v[204:207], v[36:39]
	v_mfma_f32_16x16x32_bf16 v[36:39], v[180:183], v[208:211], v[36:39]
	v_mfma_f32_16x16x32_bf16 v[52:55], v[180:183], v[188:191], v[52:55]
	v_mfma_f32_16x16x32_bf16 v[52:55], v[176:179], v[184:187], v[52:55]
	s_setprio 0
	s_barrier
	s_mov_b32 m0, s47
	s_nop 0
	global_load_lds_dwordx4 v[240:241], off
	s_mov_b32 m0, s52
	s_nop 0
	global_load_lds_dwordx4 v[242:243], off
	s_add_i32 s56, 0, 0x18000
	s_add_i32 s57, 0, 0x1c000
	v_add_u32_e32 v156, s56, v171
	v_add_u32_e32 v175, s57, v171
	ds_read_b128 v[112:115], v156
	ds_read_b128 v[120:123], v156 offset:1024
	ds_read_b128 v[152:155], v156 offset:2048
	ds_read_b128 v[156:159], v156 offset:3072
	ds_read_b128 v[160:163], v175
	ds_read_b128 v[164:167], v175 offset:1024
	ds_read_b128 v[176:179], v175 offset:2048
	ds_read_b128 v[180:183], v175 offset:3072
	s_add_u32 s50, s76, 0x100000
	s_addc_u32 s51, s77, 0
	s_mov_b32 m0, s53
	v_lshl_add_u64 v[244:245], s[50:51], 0, v[140:141]
	ds_read_b128 v[184:187], v173 offset:32768
	ds_read_b128 v[188:191], v173 offset:33792
	ds_read_b128 v[204:207], v173 offset:34816
	ds_read_b128 v[208:211], v173 offset:35840
	ds_read_b128 v[212:215], v173 offset:36864
	ds_read_b128 v[216:219], v173 offset:37888
	ds_read_b128 v[220:223], v173 offset:38912
	ds_read_b128 v[224:227], v173 offset:39936
	global_load_lds_dwordx4 v[244:245], off
	v_lshl_add_u64 v[244:245], s[50:51], 0, v[142:143]
	s_mov_b32 m0, s64
	s_nop 0
	global_load_lds_dwordx4 v[244:245], off
	s_waitcnt vmcnt(8)
	s_waitcnt lgkmcnt(0)
	s_barrier
; #define PG8_STAGE(bufoff, gbase, voff) do { _Pragma("unroll") for (int _i = 0; _i < 2; ++_i) \
;         __builtin_amdgcn_global_load_lds((const unsigned*)((const char*)(gbase) + (voff)[_i]), (PG8_LAS unsigned*)(lds + (bufoff) + ldsw + _i * 8192), 16, 0, 0); } while (0)
; #define PG8_LDA(dst, b, h) do { _Pragma("unroll") for (int m = 0; m < 4; ++m) _Pragma("unroll") for (int k = 0; k < 2; ++k) dst[m][k] = *(const PG8_LAS bf16x8*)(lds + PG8_SA(b, h) + aoff + m * 2048 + k * 1024); } while (0)
; #define PG8_WAIT_V(n) asm volatile("s_waitcnt vmcnt(" #n ")" ::: "memory")
; #define PG8_WAIT_L(n) asm volatile("s_waitcnt lgkmcnt(" #n ")" ::: "memory")
; #define PG8_BAR __builtin_amdgcn_s_barrier()
; #define PG8_SCHED __builtin_amdgcn_sched_barrier(0)
; template <class Epi, class Sched, bool ALIGN_EPI = false, bool SP2 = false, bool I8 = false>
; __device__ __forceinline__ void gemm_phase(PG8_LAS unsigned char* lds, const Gemm g, const Sched& S, const Epi& E) {
;     ...
;             PG8_WAIT_V(8); PG8_WAIT_L(0); PG8_BAR; PG8_MMA(0, 0, At, B0); PG8_MMA(0, 1, At, B1); PG8_BAR; PG8_SCHED;
;             PG8_LDA(At, 1, 1); PG8_STAGE(PG8_SB(1, 0), b3, voffB); PG8_STAGE(PG8_SB(1, 1), b3 + hstep, voffB); PG8_STAGE(PG8_SA(1, 0), a3, voffA);
;             PG8_WAIT_V(8); PG8_WAIT_L(0); PG8_BAR; PG8_MMA(1, 0, At, B0); PG8_MMA(1, 1, At, B1); PG8_BAR; PG8_SCHED;
	s_setprio 1
	s_waitcnt lgkmcnt(0)
	v_mfma_f32_16x16x32_bf16 v[136:139], v[112:115], v[184:187], v[136:139]
	v_mfma_f32_16x16x32_bf16 v[136:139], v[120:123], v[188:191], v[136:139]
	v_mfma_f32_16x16x32_bf16 v[116:119], v[120:123], v[208:211], v[116:119]
	v_mfma_f32_16x16x32_bf16 v[116:119], v[112:115], v[204:207], v[116:119]
	v_mfma_f32_16x16x32_bf16 v[96:99], v[112:115], v[212:215], v[96:99]
	v_mfma_f32_16x16x32_bf16 v[96:99], v[120:123], v[216:219], v[96:99]
	v_mfma_f32_16x16x32_bf16 v[80:83], v[120:123], v[224:227], v[80:83]
	v_mfma_f32_16x16x32_bf16 v[80:83], v[112:115], v[220:223], v[80:83]
	v_mfma_f32_16x16x32_bf16 v[76:79], v[152:155], v[220:223], v[76:79]
	v_mfma_f32_16x16x32_bf16 v[76:79], v[156:159], v[224:227], v[76:79]
	v_mfma_f32_16x16x32_bf16 v[92:95], v[156:159], v[216:219], v[92:95]
	v_mfma_f32_16x16x32_bf16 v[92:95], v[152:155], v[212:215], v[92:95]
	v_mfma_f32_16x16x32_bf16 v[108:111], v[152:155], v[204:207], v[108:111]
	v_mfma_f32_16x16x32_bf16 v[108:111], v[156:159], v[208:211], v[108:111]
	v_mfma_f32_16x16x32_bf16 v[132:135], v[156:159], v[188:191], v[132:135]
	v_mfma_f32_16x16x32_bf16 v[132:135], v[152:155], v[184:187], v[132:135]
	v_mfma_f32_16x16x32_bf16 v[128:131], v[160:163], v[184:187], v[128:131]
	v_mfma_f32_16x16x32_bf16 v[128:131], v[164:167], v[188:191], v[128:131]
	v_mfma_f32_16x16x32_bf16 v[104:107], v[164:167], v[208:211], v[104:107]
	v_mfma_f32_16x16x32_bf16 v[104:107], v[160:163], v[204:207], v[104:107]
	v_mfma_f32_16x16x32_bf16 v[88:91], v[160:163], v[212:215], v[88:91]
	v_mfma_f32_16x16x32_bf16 v[88:91], v[164:167], v[216:219], v[88:91]
	v_mfma_f32_16x16x32_bf16 v[72:75], v[164:167], v[224:227], v[72:75]
	v_mfma_f32_16x16x32_bf16 v[72:75], v[160:163], v[220:223], v[72:75]
	v_mfma_f32_16x16x32_bf16 v[68:71], v[176:179], v[220:223], v[68:71]
	v_mfma_f32_16x16x32_bf16 v[68:71], v[180:183], v[224:227], v[68:71]
	v_mfma_f32_16x16x32_bf16 v[84:87], v[180:183], v[216:219], v[84:87]
	v_mfma_f32_16x16x32_bf16 v[84:87], v[176:179], v[212:215], v[84:87]
	v_mfma_f32_16x16x32_bf16 v[100:103], v[176:179], v[204:207], v[100:103]
	v_mfma_f32_16x16x32_bf16 v[100:103], v[180:183], v[208:211], v[100:103]
	v_mfma_f32_16x16x32_bf16 v[124:127], v[180:183], v[188:191], v[124:127]
	v_mfma_f32_16x16x32_bf16 v[124:127], v[176:179], v[184:187], v[124:127]
	s_setprio 0
	s_barrier
	s_add_i32 s50, s56, s46
	v_lshl_add_u64 v[168:169], v[168:169], 0, s[84:85]
	s_mov_b32 m0, s50
	ds_read_b128 v[184:187], v173 offset:49152
	ds_read_b128 v[188:191], v173 offset:50176
	ds_read_b128 v[204:207], v173 offset:51200
	ds_read_b128 v[208:211], v173 offset:52224
	ds_read_b128 v[212:215], v173 offset:53248
	ds_read_b128 v[216:219], v173 offset:54272
	ds_read_b128 v[220:223], v173 offset:55296
	ds_read_b128 v[224:227], v173 offset:56320
	global_load_lds_dwordx4 v[168:169], off
	s_add_i32 m0, s50, 0x2000
	s_add_u32 s50, s72, 0x100080
	v_lshl_add_u64 v[168:169], v[228:229], 0, s[84:85]
	s_addc_u32 s51, s73, 0
	s_add_i32 s56, s57, s46
	global_load_lds_dwordx4 v[168:169], off
	v_lshl_add_u64 v[168:169], s[50:51], 0, v[2:3]
	s_mov_b32 m0, s56
	s_nop 0
	global_load_lds_dwordx4 v[168:169], off
	v_lshl_add_u64 v[168:169], s[50:51], 0, v[144:145]
	s_add_i32 m0, s56, 0x2000
	s_nop 0
	global_load_lds_dwordx4 v[168:169], off
	s_cmp_eq_u32 s97, 60
	s_cbranch_scc0 .Ldefer_230_body
	v_lshl_add_u64 v[168:169], v[240:241], 0, s[84:85]
	s_mov_b32 m0, s28
	s_nop 0
	global_load_lds_dwordx4 v[168:169], off
	v_lshl_add_u64 v[168:169], v[242:243], 0, s[84:85]
	s_mov_b32 m0, s65
	s_nop 0
	global_load_lds_dwordx4 v[168:169], off
.Ldefer_230_body:
	s_waitcnt vmcnt(6)
	s_waitcnt lgkmcnt(0)
	s_barrier
	s_setprio 1
	s_waitcnt lgkmcnt(0)
	v_mfma_f32_16x16x32_bf16 v[64:67], v[112:115], v[184:187], v[64:67]
	v_mfma_f32_16x16x32_bf16 v[64:67], v[120:123], v[188:191], v[64:67]
	v_mfma_f32_16x16x32_bf16 v[48:51], v[120:123], v[208:211], v[48:51]
	v_mfma_f32_16x16x32_bf16 v[48:51], v[112:115], v[204:207], v[48:51]
	v_mfma_f32_16x16x32_bf16 v[32:35], v[112:115], v[212:215], v[32:35]
	v_mfma_f32_16x16x32_bf16 v[32:35], v[120:123], v[216:219], v[32:35]
	v_mfma_f32_16x16x32_bf16 v[16:19], v[120:123], v[224:227], v[16:19]
	v_mfma_f32_16x16x32_bf16 v[16:19], v[112:115], v[220:223], v[16:19]
	v_mfma_f32_16x16x32_bf16 v[12:15], v[152:155], v[220:223], v[12:15]
	v_mfma_f32_16x16x32_bf16 v[12:15], v[156:159], v[224:227], v[12:15]
	v_mfma_f32_16x16x32_bf16 v[28:31], v[156:159], v[216:219], v[28:31]
	v_mfma_f32_16x16x32_bf16 v[28:31], v[152:155], v[212:215], v[28:31]
	v_mfma_f32_16x16x32_bf16 v[44:47], v[152:155], v[204:207], v[44:47]
	v_mfma_f32_16x16x32_bf16 v[44:47], v[156:159], v[208:211], v[44:47]
	v_mfma_f32_16x16x32_bf16 v[60:63], v[156:159], v[188:191], v[60:63]
	v_mfma_f32_16x16x32_bf16 v[60:63], v[152:155], v[184:187], v[60:63]
	v_mfma_f32_16x16x32_bf16 v[56:59], v[160:163], v[184:187], v[56:59]
	v_mfma_f32_16x16x32_bf16 v[56:59], v[164:167], v[188:191], v[56:59]
	v_mfma_f32_16x16x32_bf16 v[40:43], v[164:167], v[208:211], v[40:43]
	v_mfma_f32_16x16x32_bf16 v[40:43], v[160:163], v[204:207], v[40:43]
	v_mfma_f32_16x16x32_bf16 v[24:27], v[160:163], v[212:215], v[24:27]
	v_mfma_f32_16x16x32_bf16 v[24:27], v[164:167], v[216:219], v[24:27]
	v_mfma_f32_16x16x32_bf16 v[8:11], v[164:167], v[224:227], v[8:11]
	v_mfma_f32_16x16x32_bf16 v[8:11], v[160:163], v[220:223], v[8:11]
	v_mfma_f32_16x16x32_bf16 v[4:7], v[176:179], v[220:223], v[4:7]
	v_mfma_f32_16x16x32_bf16 v[4:7], v[180:183], v[224:227], v[4:7]
	v_mfma_f32_16x16x32_bf16 v[20:23], v[180:183], v[216:219], v[20:23]
	v_mfma_f32_16x16x32_bf16 v[20:23], v[176:179], v[212:215], v[20:23]
	v_mfma_f32_16x16x32_bf16 v[36:39], v[176:179], v[204:207], v[36:39]
	v_mfma_f32_16x16x32_bf16 v[36:39], v[180:183], v[208:211], v[36:39]
	v_mfma_f32_16x16x32_bf16 v[52:55], v[180:183], v[188:191], v[52:55]
	v_mfma_f32_16x16x32_bf16 v[52:55], v[176:179], v[184:187], v[52:55]
	s_setprio 0
	s_barrier
	s_add_i32 s97, s97, 2
	s_add_u32 s12, s12, 0x100
	s_addc_u32 s13, s13, 0
	s_add_u32 s37, s37, 0x100
	s_addc_u32 s61, s61, 0
	s_cmp_gt_u32 s97, 61
	s_cbranch_scc0 .LBB0_230

; #define PG8_STAGE(bufoff, gbase, voff) do { _Pragma("unroll") for (int _i = 0; _i < 2; ++_i) \
;         __builtin_amdgcn_global_load_lds((const unsigned*)((const char*)(gbase) + (voff)[_i]), (PG8_LAS unsigned*)(lds + (bufoff) + ldsw + _i * 8192), 16, 0, 0); } while (0)
; #define PG8_LDA(dst, b, h) do { _Pragma("unroll") for (int m = 0; m < 4; ++m) _Pragma("unroll") for (int k = 0; k < 2; ++k) dst[m][k] = *(const PG8_LAS bf16x8*)(lds + PG8_SA(b, h) + aoff + m * 2048 + k * 1024); } while (0)
; #define PG8_LDB(dst, b, h) do { _Pragma("unroll") for (int n = 0; n < 2; ++n) _Pragma("unroll") for (int k = 0; k < 2; ++k) dst[n][k] = *(const PG8_LAS bf16x8*)(lds + PG8_SB(b, h) + boff + n * 2048 + k * 1024); } while (0)
; #define PG8_WAIT_V(n) asm volatile("s_waitcnt vmcnt(" #n ")" ::: "memory")
; #define PG8_WAIT_L(n) asm volatile("s_waitcnt lgkmcnt(" #n ")" ::: "memory")
; #define PG8_BAR __builtin_amdgcn_s_barrier()
; #define PG8_SCHED __builtin_amdgcn_sched_barrier(0)
; template <class Epi, class Sched, bool ALIGN_EPI = false, bool SP2 = false, bool I8 = false>
; __device__ __forceinline__ void gemm_phase(PG8_LAS unsigned char* lds, const Gemm g, const Sched& S, const Epi& E) {
;     ...
;         const bool has_next = S.next(ui + 1, nxt);
;         const char* nA = has_next ? (const char*)g.A + (size_t)nxt.pm * tstep : cA; const char* nB = has_next ? (const char*)g.Bt + (size_t)nxt.pn * tstep : cB;
;         for (int t = 0; t < nt; t += 2) {
;             const bool last = (t == nt - 2);
;             const char* a1 = cA + (size_t)(t + 1) * kstep;
;             const char* a2 = last ? nA : cA + (size_t)(t + 2) * kstep; const char* b2 = last ? nB : cB + (size_t)(t + 2) * kstep;
;             const char* a3 = a2 + kstep; const char* b3 = b2 + kstep;
;             if (last && has_next) S.a_ready(nxt);
;             if constexpr (SP2) {
;             PG8_LDB(B0, 0, 0); PG8_LDB(B1, 0, 1); PG8_SCHED; PG8_LDA(At, 0, 0); PG8_STAGE(PG8_SA(1, 1), a1 + hstep, voffA);
;             PG8_WAIT_V(8); PG8_WAIT_L(0); PG8_BAR; PG8_MMA(0, 0, At, B0); PG8_MMA(0, 1, At, B1); PG8_BAR; PG8_SCHED;
;             PG8_LDA(At, 0, 1); PG8_STAGE(PG8_SB(0, 0), b2, voffB); PG8_STAGE(PG8_SB(0, 1), b2 + hstep, voffB); PG8_STAGE(PG8_SA(0, 0), a2, voffA);
;             PG8_WAIT_V(8); PG8_WAIT_L(0); PG8_BAR; PG8_MMA(1, 0, At, B0); PG8_MMA(1, 1, At, B1); PG8_BAR; PG8_SCHED;
.LBB0_1455:
	s_ashr_i32 s17, s16, 31
	s_lshl_b64 s[20:21], s[16:17], 21
	s_add_u32 s20, s28, s20
	s_addc_u32 s21, s34, s21
	s_and_b64 s[22:23], s[8:9], exec
	s_cselect_b32 s17, s21, s25
	s_cselect_b32 s51, s20, s24
	s_ashr_i32 s19, s18, 31
	s_lshl_b64 s[22:23], s[18:19], 21
	s_add_u32 s22, s35, s22
	s_addc_u32 s23, s39, s23
	s_and_b64 s[36:37], s[8:9], exec
	s_cselect_b32 s19, s23, s27
	s_cselect_b32 s52, s22, s26
	s_add_u32 s24, s24, 0x100080
	s_addc_u32 s25, s25, 0
	s_add_u32 s53, s26, 0x100
	s_addc_u32 s54, s27, 0
	s_mov_b32 s55, -2
	s_waitcnt vmcnt(0)
	s_add_u32 s26, s24, 0xfff00080
	s_addc_u32 s27, s25, -1
	s_add_i32 s56, 0, 0x10000
	s_cmp_eq_u32 s55, 60
	s_cselect_b32 s37, s17, s27
	s_cselect_b32 s36, s51, s26
	s_cselect_b32 s27, s19, s54
	s_cselect_b32 s26, s52, s53
	s_add_i32 s58, 0, 0x14000
	v_add_u32_e32 v144, s56, v240
	v_add_u32_e32 v160, s58, v240
	ds_read_b128 v[124:127], v144
	ds_read_b128 v[128:131], v144 offset:1024
	ds_read_b128 v[132:135], v144 offset:2048
	ds_read_b128 v[144:147], v144 offset:3072
	ds_read_b128 v[148:151], v160
	ds_read_b128 v[152:155], v160 offset:1024
	ds_read_b128 v[156:159], v160 offset:2048
	ds_read_b128 v[160:163], v160 offset:3072
	v_lshl_add_u64 v[218:219], s[24:25], 0, v[210:211]
	s_add_i32 m0, s41, 0xc000
	ds_read_b128 v[164:167], v242
	ds_read_b128 v[168:171], v242 offset:1024
	ds_read_b128 v[172:175], v242 offset:2048
	ds_read_b128 v[176:179], v242 offset:3072
	ds_read_b128 v[180:183], v242 offset:4096
	ds_read_b128 v[184:187], v242 offset:5120
	ds_read_b128 v[188:191], v242 offset:6144
	ds_read_b128 v[214:217], v242 offset:7168
	global_load_lds_dwordx4 v[218:219], off
	v_lshl_add_u64 v[218:219], s[24:25], 0, v[212:213]
	s_add_i32 m0, s41, 0xe000
	s_nop 0
	global_load_lds_dwordx4 v[218:219], off
	s_waitcnt vmcnt(8)
	s_waitcnt lgkmcnt(0)
	s_barrier
	s_setprio 1
	s_waitcnt lgkmcnt(0)
	v_mfma_f32_16x16x32_bf16 v[140:143], v[124:127], v[164:167], 0
	v_mfma_f32_16x16x32_bf16 v[140:143], v[128:131], v[168:171], v[140:143]
	v_mfma_f32_16x16x32_bf16 v[112:115], v[128:131], v[176:179], 0
	v_mfma_f32_16x16x32_bf16 v[112:115], v[124:127], v[172:175], v[112:115]
	v_mfma_f32_16x16x32_bf16 v[96:99], v[124:127], v[180:183], 0
	v_mfma_f32_16x16x32_bf16 v[96:99], v[128:131], v[184:187], v[96:99]
	v_mfma_f32_16x16x32_bf16 v[80:83], v[128:131], v[214:217], 0
	v_mfma_f32_16x16x32_bf16 v[80:83], v[124:127], v[188:191], v[80:83]
	v_mfma_f32_16x16x32_bf16 v[76:79], v[132:135], v[188:191], 0
	v_mfma_f32_16x16x32_bf16 v[76:79], v[144:147], v[214:217], v[76:79]
	v_mfma_f32_16x16x32_bf16 v[92:95], v[144:147], v[184:187], 0
	v_mfma_f32_16x16x32_bf16 v[92:95], v[132:135], v[180:183], v[92:95]
	v_mfma_f32_16x16x32_bf16 v[108:111], v[132:135], v[172:175], 0
	v_mfma_f32_16x16x32_bf16 v[108:111], v[144:147], v[176:179], v[108:111]
	v_mfma_f32_16x16x32_bf16 v[136:139], v[144:147], v[168:171], 0
	v_mfma_f32_16x16x32_bf16 v[136:139], v[132:135], v[164:167], v[136:139]
	v_mfma_f32_16x16x32_bf16 v[120:123], v[148:151], v[164:167], 0
	v_mfma_f32_16x16x32_bf16 v[120:123], v[152:155], v[168:171], v[120:123]
	v_mfma_f32_16x16x32_bf16 v[104:107], v[152:155], v[176:179], 0
	v_mfma_f32_16x16x32_bf16 v[104:107], v[148:151], v[172:175], v[104:107]
	v_mfma_f32_16x16x32_bf16 v[88:91], v[148:151], v[180:183], 0
	v_mfma_f32_16x16x32_bf16 v[88:91], v[152:155], v[184:187], v[88:91]
	v_mfma_f32_16x16x32_bf16 v[72:75], v[152:155], v[214:217], 0
	v_mfma_f32_16x16x32_bf16 v[72:75], v[148:151], v[188:191], v[72:75]
	v_mfma_f32_16x16x32_bf16 v[68:71], v[156:159], v[188:191], 0
	v_mfma_f32_16x16x32_bf16 v[68:71], v[160:163], v[214:217], v[68:71]
	v_mfma_f32_16x16x32_bf16 v[84:87], v[160:163], v[184:187], 0
	v_mfma_f32_16x16x32_bf16 v[84:87], v[156:159], v[180:183], v[84:87]
	v_mfma_f32_16x16x32_bf16 v[100:103], v[156:159], v[172:175], 0
	v_mfma_f32_16x16x32_bf16 v[100:103], v[160:163], v[176:179], v[100:103]
	v_mfma_f32_16x16x32_bf16 v[116:119], v[160:163], v[168:171], 0
	v_mfma_f32_16x16x32_bf16 v[116:119], v[156:159], v[164:167], v[116:119]
	s_setprio 0
	s_barrier
	s_add_i32 s56, s56, s40
	v_lshl_add_u64 v[218:219], s[26:27], 0, v[2:3]
	s_mov_b32 m0, s56
	ds_read_b128 v[164:167], v242 offset:16384
	ds_read_b128 v[168:171], v242 offset:17408
	ds_read_b128 v[172:175], v242 offset:18432
	ds_read_b128 v[176:179], v242 offset:19456
	ds_read_b128 v[180:183], v242 offset:20480
	ds_read_b128 v[184:187], v242 offset:21504
	ds_read_b128 v[188:191], v242 offset:22528
	ds_read_b128 v[214:217], v242 offset:23552
	global_load_lds_dwordx4 v[218:219], off
	s_add_i32 m0, s56, 0x2000
	s_add_u32 s56, s26, 0x100000
	v_lshl_add_u64 v[220:221], s[26:27], 0, v[204:205]
	s_addc_u32 s57, s27, 0
	s_add_i32 s58, s58, s40
	global_load_lds_dwordx4 v[220:221], off
	v_lshl_add_u64 v[222:223], s[56:57], 0, v[2:3]
	s_mov_b32 m0, s58
	v_lshl_add_u64 v[224:225], s[36:37], 0, v[206:207]
	global_load_lds_dwordx4 v[222:223], off
	v_lshl_add_u64 v[222:223], s[56:57], 0, v[204:205]
	s_add_i32 m0, s58, 0x2000
	s_nop 0
	global_load_lds_dwordx4 v[222:223], off
	v_lshl_add_u64 v[222:223], s[36:37], 0, v[208:209]
	s_waitcnt vmcnt(6)
	s_waitcnt lgkmcnt(0)
	s_barrier
; #define PG8_STAGE(bufoff, gbase, voff) do { _Pragma("unroll") for (int _i = 0; _i < 2; ++_i) \
;         __builtin_amdgcn_global_load_lds((const unsigned*)((const char*)(gbase) + (voff)[_i]), (PG8_LAS unsigned*)(lds + (bufoff) + ldsw + _i * 8192), 16, 0, 0); } while (0)
; #define PG8_LDA(dst, b, h) do { _Pragma("unroll") for (int m = 0; m < 4; ++m) _Pragma("unroll") for (int k = 0; k < 2; ++k) dst[m][k] = *(const PG8_LAS bf16x8*)(lds + PG8_SA(b, h) + aoff + m * 2048 + k * 1024); } while (0)
; #define PG8_LDB(dst, b, h) do { _Pragma("unroll") for (int n = 0; n < 2; ++n) _Pragma("unroll") for (int k = 0; k < 2; ++k) dst[n][k] = *(const PG8_LAS bf16x8*)(lds + PG8_SB(b, h) + boff + n * 2048 + k * 1024); } while (0)
; #define PG8_WAIT_V(n) asm volatile("s_waitcnt vmcnt(" #n ")" ::: "memory")
; #define PG8_WAIT_L(n) asm volatile("s_waitcnt lgkmcnt(" #n ")" ::: "memory")
; #define PG8_BAR __builtin_amdgcn_s_barrier()
; #define PG8_SCHED __builtin_amdgcn_sched_barrier(0)
; template <class Epi, class Sched, bool ALIGN_EPI = false, bool SP2 = false, bool I8 = false>
; __device__ __forceinline__ void gemm_phase(PG8_LAS unsigned char* lds, const Gemm g, const Sched& S, const Epi& E) {
;     ...
;             PG8_WAIT_V(8); PG8_WAIT_L(0); PG8_BAR; PG8_MMA(1, 0, At, B0); PG8_MMA(1, 1, At, B1); PG8_BAR; PG8_SCHED;
;             PG8_LDB(B0, 1, 0); PG8_LDB(B1, 1, 1); PG8_SCHED; PG8_LDA(At, 1, 0); PG8_STAGE(PG8_SA(0, 1), a2 + hstep, voffA);
;             PG8_WAIT_V(8); PG8_WAIT_L(0); PG8_BAR; PG8_MMA(0, 0, At, B0); PG8_MMA(0, 1, At, B1); PG8_BAR; PG8_SCHED;
;             PG8_LDA(At, 1, 1); PG8_STAGE(PG8_SB(1, 0), b3, voffB); PG8_STAGE(PG8_SB(1, 1), b3 + hstep, voffB); PG8_STAGE(PG8_SA(1, 0), a3, voffA);
;             PG8_WAIT_V(8); PG8_WAIT_L(0); PG8_BAR; PG8_MMA(1, 0, At, B0); PG8_MMA(1, 1, At, B1); PG8_BAR; PG8_SCHED;
	s_setprio 1
	s_waitcnt lgkmcnt(0)
	v_mfma_f32_16x16x32_bf16 v[64:67], v[124:127], v[164:167], 0
	v_mfma_f32_16x16x32_bf16 v[64:67], v[128:131], v[168:171], v[64:67]
	v_mfma_f32_16x16x32_bf16 v[48:51], v[128:131], v[176:179], 0
	v_mfma_f32_16x16x32_bf16 v[48:51], v[124:127], v[172:175], v[48:51]
	v_mfma_f32_16x16x32_bf16 v[32:35], v[124:127], v[180:183], 0
	v_mfma_f32_16x16x32_bf16 v[32:35], v[128:131], v[184:187], v[32:35]
	v_mfma_f32_16x16x32_bf16 v[16:19], v[128:131], v[214:217], 0
	v_mfma_f32_16x16x32_bf16 v[16:19], v[124:127], v[188:191], v[16:19]
	v_mfma_f32_16x16x32_bf16 v[12:15], v[132:135], v[188:191], 0
	v_mfma_f32_16x16x32_bf16 v[12:15], v[144:147], v[214:217], v[12:15]
	v_mfma_f32_16x16x32_bf16 v[28:31], v[144:147], v[184:187], 0
	v_mfma_f32_16x16x32_bf16 v[28:31], v[132:135], v[180:183], v[28:31]
	v_mfma_f32_16x16x32_bf16 v[44:47], v[132:135], v[172:175], 0
	v_mfma_f32_16x16x32_bf16 v[44:47], v[144:147], v[176:179], v[44:47]
	v_mfma_f32_16x16x32_bf16 v[60:63], v[144:147], v[168:171], 0
	v_mfma_f32_16x16x32_bf16 v[60:63], v[132:135], v[164:167], v[60:63]
	v_mfma_f32_16x16x32_bf16 v[56:59], v[148:151], v[164:167], 0
	v_mfma_f32_16x16x32_bf16 v[56:59], v[152:155], v[168:171], v[56:59]
	v_mfma_f32_16x16x32_bf16 v[40:43], v[152:155], v[176:179], 0
	v_mfma_f32_16x16x32_bf16 v[40:43], v[148:151], v[172:175], v[40:43]
	v_mfma_f32_16x16x32_bf16 v[24:27], v[148:151], v[180:183], 0
	v_mfma_f32_16x16x32_bf16 v[24:27], v[152:155], v[184:187], v[24:27]
	v_mfma_f32_16x16x32_bf16 v[8:11], v[152:155], v[214:217], 0
	v_mfma_f32_16x16x32_bf16 v[8:11], v[148:151], v[188:191], v[8:11]
	v_mfma_f32_16x16x32_bf16 v[4:7], v[156:159], v[188:191], 0
	v_mfma_f32_16x16x32_bf16 v[4:7], v[160:163], v[214:217], v[4:7]
	v_mfma_f32_16x16x32_bf16 v[20:23], v[160:163], v[184:187], 0
	v_mfma_f32_16x16x32_bf16 v[20:23], v[156:159], v[180:183], v[20:23]
	v_mfma_f32_16x16x32_bf16 v[36:39], v[156:159], v[172:175], 0
	v_mfma_f32_16x16x32_bf16 v[36:39], v[160:163], v[176:179], v[36:39]
	v_mfma_f32_16x16x32_bf16 v[52:55], v[160:163], v[168:171], 0
	v_mfma_f32_16x16x32_bf16 v[52:55], v[156:159], v[164:167], v[52:55]
	s_setprio 0
	s_barrier
	s_mov_b32 m0, s41
	s_nop 0
	global_load_lds_dwordx4 v[222:223], off
	s_mov_b32 m0, s42
	s_nop 0
	global_load_lds_dwordx4 v[224:225], off
	s_add_i32 s56, 0, 0x18000
	s_add_i32 s57, 0, 0x1c000
	v_add_u32_e32 v144, s56, v240
	v_add_u32_e32 v160, s57, v240
	ds_read_b128 v[124:127], v144
	ds_read_b128 v[128:131], v144 offset:1024
	ds_read_b128 v[132:135], v144 offset:2048
	ds_read_b128 v[144:147], v144 offset:3072
	ds_read_b128 v[148:151], v160
	ds_read_b128 v[152:155], v160 offset:1024
	ds_read_b128 v[156:159], v160 offset:2048
	ds_read_b128 v[160:163], v160 offset:3072
	s_add_u32 s36, s36, 0x100000
	s_addc_u32 s37, s37, 0
	s_mov_b32 m0, s43
	v_lshl_add_u64 v[226:227], s[36:37], 0, v[208:209]
	ds_read_b128 v[164:167], v242 offset:32768
	ds_read_b128 v[168:171], v242 offset:33792
	ds_read_b128 v[172:175], v242 offset:34816
	ds_read_b128 v[176:179], v242 offset:35840
	ds_read_b128 v[180:183], v242 offset:36864
	ds_read_b128 v[184:187], v242 offset:37888
	ds_read_b128 v[188:191], v242 offset:38912
	ds_read_b128 v[214:217], v242 offset:39936
	global_load_lds_dwordx4 v[226:227], off
	v_lshl_add_u64 v[226:227], s[36:37], 0, v[206:207]
	s_mov_b32 m0, s44
	s_nop 0
	global_load_lds_dwordx4 v[226:227], off
	s_waitcnt vmcnt(8)
	s_waitcnt lgkmcnt(0)
	s_barrier
	s_setprio 1
	s_waitcnt lgkmcnt(0)
	v_mfma_f32_16x16x32_bf16 v[140:143], v[124:127], v[164:167], v[140:143]
	v_mfma_f32_16x16x32_bf16 v[140:143], v[128:131], v[168:171], v[140:143]
	v_mfma_f32_16x16x32_bf16 v[112:115], v[128:131], v[176:179], v[112:115]
	v_mfma_f32_16x16x32_bf16 v[112:115], v[124:127], v[172:175], v[112:115]
	v_mfma_f32_16x16x32_bf16 v[96:99], v[124:127], v[180:183], v[96:99]
	v_mfma_f32_16x16x32_bf16 v[96:99], v[128:131], v[184:187], v[96:99]
	v_mfma_f32_16x16x32_bf16 v[80:83], v[128:131], v[214:217], v[80:83]
	v_mfma_f32_16x16x32_bf16 v[80:83], v[124:127], v[188:191], v[80:83]
	v_mfma_f32_16x16x32_bf16 v[76:79], v[132:135], v[188:191], v[76:79]
	v_mfma_f32_16x16x32_bf16 v[76:79], v[144:147], v[214:217], v[76:79]
	v_mfma_f32_16x16x32_bf16 v[92:95], v[144:147], v[184:187], v[92:95]
	v_mfma_f32_16x16x32_bf16 v[92:95], v[132:135], v[180:183], v[92:95]
	v_mfma_f32_16x16x32_bf16 v[108:111], v[132:135], v[172:175], v[108:111]
	v_mfma_f32_16x16x32_bf16 v[108:111], v[144:147], v[176:179], v[108:111]
	v_mfma_f32_16x16x32_bf16 v[136:139], v[144:147], v[168:171], v[136:139]
	v_mfma_f32_16x16x32_bf16 v[136:139], v[132:135], v[164:167], v[136:139]
	v_mfma_f32_16x16x32_bf16 v[120:123], v[148:151], v[164:167], v[120:123]
	v_mfma_f32_16x16x32_bf16 v[120:123], v[152:155], v[168:171], v[120:123]
	v_mfma_f32_16x16x32_bf16 v[104:107], v[152:155], v[176:179], v[104:107]
	v_mfma_f32_16x16x32_bf16 v[104:107], v[148:151], v[172:175], v[104:107]
	v_mfma_f32_16x16x32_bf16 v[88:91], v[148:151], v[180:183], v[88:91]
	v_mfma_f32_16x16x32_bf16 v[88:91], v[152:155], v[184:187], v[88:91]
	v_mfma_f32_16x16x32_bf16 v[72:75], v[152:155], v[214:217], v[72:75]
	v_mfma_f32_16x16x32_bf16 v[72:75], v[148:151], v[188:191], v[72:75]
	v_mfma_f32_16x16x32_bf16 v[68:71], v[156:159], v[188:191], v[68:71]
	v_mfma_f32_16x16x32_bf16 v[68:71], v[160:163], v[214:217], v[68:71]
	v_mfma_f32_16x16x32_bf16 v[84:87], v[160:163], v[184:187], v[84:87]
	v_mfma_f32_16x16x32_bf16 v[84:87], v[156:159], v[180:183], v[84:87]
	v_mfma_f32_16x16x32_bf16 v[100:103], v[156:159], v[172:175], v[100:103]
	v_mfma_f32_16x16x32_bf16 v[100:103], v[160:163], v[176:179], v[100:103]
	v_mfma_f32_16x16x32_bf16 v[116:119], v[160:163], v[168:171], v[116:119]
	v_mfma_f32_16x16x32_bf16 v[116:119], v[156:159], v[164:167], v[116:119]
	s_setprio 0
	s_barrier
	s_add_i32 s36, s56, s40
	v_lshl_add_u64 v[218:219], v[218:219], 0, s[84:85]
	s_mov_b32 m0, s36
	ds_read_b128 v[164:167], v242 offset:49152
	ds_read_b128 v[168:171], v242 offset:50176
	ds_read_b128 v[172:175], v242 offset:51200
	ds_read_b128 v[176:179], v242 offset:52224
	ds_read_b128 v[180:183], v242 offset:53248
	ds_read_b128 v[184:187], v242 offset:54272
	ds_read_b128 v[188:191], v242 offset:55296
	ds_read_b128 v[214:217], v242 offset:56320
	global_load_lds_dwordx4 v[218:219], off
	s_add_i32 m0, s36, 0x2000
	s_add_u32 s26, s26, 0x100080
	v_lshl_add_u64 v[218:219], v[220:221], 0, s[84:85]
	s_addc_u32 s27, s27, 0
	s_add_i32 s36, s57, s40
	global_load_lds_dwordx4 v[218:219], off
	v_lshl_add_u64 v[218:219], s[26:27], 0, v[2:3]
	s_mov_b32 m0, s36
	s_nop 0
	global_load_lds_dwordx4 v[218:219], off
	v_lshl_add_u64 v[218:219], s[26:27], 0, v[204:205]
	s_add_i32 m0, s36, 0x2000
	s_nop 0
	global_load_lds_dwordx4 v[218:219], off
	s_cmp_eq_u32 s55, 60
	s_cbranch_scc0 .Ldefer_1456_peel
	v_lshl_add_u64 v[218:219], v[222:223], 0, s[84:85]
	s_mov_b32 m0, s45
	s_nop 0
	global_load_lds_dwordx4 v[218:219], off
	v_lshl_add_u64 v[218:219], v[224:225], 0, s[84:85]
	s_mov_b32 m0, s46
	s_nop 0
	global_load_lds_dwordx4 v[218:219], off
; #define PG8_STAGE(bufoff, gbase, voff) do { _Pragma("unroll") for (int _i = 0; _i < 2; ++_i) \
;         __builtin_amdgcn_global_load_lds((const unsigned*)((const char*)(gbase) + (voff)[_i]), (PG8_LAS unsigned*)(lds + (bufoff) + ldsw + _i * 8192), 16, 0, 0); } while (0)
; #define PG8_LDA(dst, b, h) do { _Pragma("unroll") for (int m = 0; m < 4; ++m) _Pragma("unroll") for (int k = 0; k < 2; ++k) dst[m][k] = *(const PG8_LAS bf16x8*)(lds + PG8_SA(b, h) + aoff + m * 2048 + k * 1024); } while (0)
; #define PG8_WAIT_V(n) asm volatile("s_waitcnt vmcnt(" #n ")" ::: "memory")
; #define PG8_WAIT_L(n) asm volatile("s_waitcnt lgkmcnt(" #n ")" ::: "memory")
; #define PG8_BAR __builtin_amdgcn_s_barrier()
; template <class Epi, class Sched, bool ALIGN_EPI = false, bool SP2 = false, bool I8 = false>
; __device__ __forceinline__ void gemm_phase(PG8_LAS unsigned char* lds, const Gemm g, const Sched& S, const Epi& E) {
;     ...
;         for (int t = 0; t < nt; t += 2) {
;             const bool last = (t == nt - 2);
;             const char* a1 = cA + (size_t)(t + 1) * kstep;
;             const char* a2 = last ? nA : cA + (size_t)(t + 2) * kstep; const char* b2 = last ? nB : cB + (size_t)(t + 2) * kstep;
;             const char* a3 = a2 + kstep; const char* b3 = b2 + kstep;
;             if (last && has_next) S.a_ready(nxt);
;             if constexpr (SP2) {
;             PG8_LDB(B0, 0, 0); PG8_LDB(B1, 0, 1); PG8_SCHED; PG8_LDA(At, 0, 0); PG8_STAGE(PG8_SA(1, 1), a1 + hstep, voffA);
;             PG8_WAIT_V(8); PG8_WAIT_L(0); PG8_BAR; PG8_MMA(0, 0, At, B0); PG8_MMA(0, 1, At, B1); PG8_BAR; PG8_SCHED;
;             PG8_LDA(At, 0, 1); PG8_STAGE(PG8_SB(0, 0), b2, voffB); PG8_STAGE(PG8_SB(0, 1), b2 + hstep, voffB); PG8_STAGE(PG8_SA(0, 0), a2, voffA);
;             PG8_WAIT_V(8); PG8_WAIT_L(0); PG8_BAR; PG8_MMA(1, 0, At, B0); PG8_MMA(1, 1, At, B1); PG8_BAR; PG8_SCHED;
;             PG8_LDB(B0, 1, 0); PG8_LDB(B1, 1, 1); PG8_SCHED; PG8_LDA(At, 1, 0); PG8_STAGE(PG8_SA(0, 1), a2 + hstep, voffA);
;             PG8_WAIT_V(8); PG8_WAIT_L(0); PG8_BAR; PG8_MMA(0, 0, At, B0); PG8_MMA(0, 1, At, B1); PG8_BAR; PG8_SCHED;
;             PG8_LDA(At, 1, 1); PG8_STAGE(PG8_SB(1, 0), b3, voffB); PG8_STAGE(PG8_SB(1, 1), b3 + hstep, voffB); PG8_STAGE(PG8_SA(1, 0), a3, voffA);
;             PG8_WAIT_V(8); PG8_WAIT_L(0); PG8_BAR; PG8_MMA(1, 0, At, B0); PG8_MMA(1, 1, At, B1); PG8_BAR; PG8_SCHED;
.Ldefer_1456_peel:
	s_waitcnt vmcnt(6)
	s_waitcnt lgkmcnt(0)
	s_barrier
	s_setprio 1
	s_waitcnt lgkmcnt(0)
	v_mfma_f32_16x16x32_bf16 v[64:67], v[124:127], v[164:167], v[64:67]
	v_mfma_f32_16x16x32_bf16 v[64:67], v[128:131], v[168:171], v[64:67]
	v_mfma_f32_16x16x32_bf16 v[48:51], v[128:131], v[176:179], v[48:51]
	v_mfma_f32_16x16x32_bf16 v[48:51], v[124:127], v[172:175], v[48:51]
	v_mfma_f32_16x16x32_bf16 v[32:35], v[124:127], v[180:183], v[32:35]
	v_mfma_f32_16x16x32_bf16 v[32:35], v[128:131], v[184:187], v[32:35]
	v_mfma_f32_16x16x32_bf16 v[16:19], v[128:131], v[214:217], v[16:19]
	v_mfma_f32_16x16x32_bf16 v[16:19], v[124:127], v[188:191], v[16:19]
	v_mfma_f32_16x16x32_bf16 v[12:15], v[132:135], v[188:191], v[12:15]
	v_mfma_f32_16x16x32_bf16 v[12:15], v[144:147], v[214:217], v[12:15]
	v_mfma_f32_16x16x32_bf16 v[28:31], v[144:147], v[184:187], v[28:31]
	v_mfma_f32_16x16x32_bf16 v[28:31], v[132:135], v[180:183], v[28:31]
	v_mfma_f32_16x16x32_bf16 v[44:47], v[132:135], v[172:175], v[44:47]
	v_mfma_f32_16x16x32_bf16 v[44:47], v[144:147], v[176:179], v[44:47]
	v_mfma_f32_16x16x32_bf16 v[60:63], v[144:147], v[168:171], v[60:63]
	v_mfma_f32_16x16x32_bf16 v[60:63], v[132:135], v[164:167], v[60:63]
	v_mfma_f32_16x16x32_bf16 v[56:59], v[148:151], v[164:167], v[56:59]
	v_mfma_f32_16x16x32_bf16 v[56:59], v[152:155], v[168:171], v[56:59]
	v_mfma_f32_16x16x32_bf16 v[40:43], v[152:155], v[176:179], v[40:43]
	v_mfma_f32_16x16x32_bf16 v[40:43], v[148:151], v[172:175], v[40:43]
	v_mfma_f32_16x16x32_bf16 v[24:27], v[148:151], v[180:183], v[24:27]
	v_mfma_f32_16x16x32_bf16 v[24:27], v[152:155], v[184:187], v[24:27]
	v_mfma_f32_16x16x32_bf16 v[8:11], v[152:155], v[214:217], v[8:11]
	v_mfma_f32_16x16x32_bf16 v[8:11], v[148:151], v[188:191], v[8:11]
	v_mfma_f32_16x16x32_bf16 v[4:7], v[156:159], v[188:191], v[4:7]
	v_mfma_f32_16x16x32_bf16 v[4:7], v[160:163], v[214:217], v[4:7]
	v_mfma_f32_16x16x32_bf16 v[20:23], v[160:163], v[184:187], v[20:23]
	v_mfma_f32_16x16x32_bf16 v[20:23], v[156:159], v[180:183], v[20:23]
	v_mfma_f32_16x16x32_bf16 v[36:39], v[156:159], v[172:175], v[36:39]
	v_mfma_f32_16x16x32_bf16 v[36:39], v[160:163], v[176:179], v[36:39]
	v_mfma_f32_16x16x32_bf16 v[52:55], v[160:163], v[168:171], v[52:55]
	v_mfma_f32_16x16x32_bf16 v[52:55], v[156:159], v[164:167], v[52:55]
	s_setprio 0
	s_barrier
	s_add_i32 s55, s55, 2
	s_add_u32 s24, s24, 0x100
	s_addc_u32 s25, s25, 0
	s_add_u32 s53, s53, 0x100
	s_addc_u32 s54, s54, 0
	s_cmp_gt_u32 s55, 61
	s_cbranch_scc1 .Lkloop_exit_2
.LBB0_1456:
	s_add_u32 s26, s24, 0xfff00080
	s_addc_u32 s27, s25, -1
	s_add_i32 s56, 0, 0x10000
	s_cmp_eq_u32 s55, 60
	s_cselect_b32 s37, s17, s27
	s_cselect_b32 s36, s51, s26
	s_cselect_b32 s27, s19, s54
	s_cselect_b32 s26, s52, s53
	s_add_i32 s58, 0, 0x14000
	v_add_u32_e32 v144, s56, v240
	v_add_u32_e32 v160, s58, v240
	ds_read_b128 v[124:127], v144
	ds_read_b128 v[128:131], v144 offset:1024
	ds_read_b128 v[132:135], v144 offset:2048
	ds_read_b128 v[144:147], v144 offset:3072
	ds_read_b128 v[148:151], v160
	ds_read_b128 v[152:155], v160 offset:1024
	ds_read_b128 v[156:159], v160 offset:2048
	ds_read_b128 v[160:163], v160 offset:3072
	v_lshl_add_u64 v[218:219], v[222:223], 0, s[84:85]
	s_mov_b32 m0, s45
	s_nop 0
	global_load_lds_dwordx4 v[218:219], off
	v_lshl_add_u64 v[218:219], v[224:225], 0, s[84:85]
	s_mov_b32 m0, s46
	s_nop 0
	global_load_lds_dwordx4 v[218:219], off
	v_lshl_add_u64 v[218:219], s[24:25], 0, v[210:211]
	s_add_i32 m0, s41, 0xc000
	ds_read_b128 v[164:167], v242
	ds_read_b128 v[168:171], v242 offset:1024
	ds_read_b128 v[172:175], v242 offset:2048
	ds_read_b128 v[176:179], v242 offset:3072
	ds_read_b128 v[180:183], v242 offset:4096
	ds_read_b128 v[184:187], v242 offset:5120
	ds_read_b128 v[188:191], v242 offset:6144
	ds_read_b128 v[214:217], v242 offset:7168
	global_load_lds_dwordx4 v[218:219], off
	v_lshl_add_u64 v[218:219], s[24:25], 0, v[212:213]
	s_add_i32 m0, s41, 0xe000
	s_nop 0
	global_load_lds_dwordx4 v[218:219], off
	s_waitcnt vmcnt(8)
	s_waitcnt lgkmcnt(0)
	s_barrier
	s_setprio 1
	s_waitcnt lgkmcnt(0)
	v_mfma_f32_16x16x32_bf16 v[140:143], v[124:127], v[164:167], v[140:143]
	v_mfma_f32_16x16x32_bf16 v[140:143], v[128:131], v[168:171], v[140:143]
	v_mfma_f32_16x16x32_bf16 v[112:115], v[128:131], v[176:179], v[112:115]
	v_mfma_f32_16x16x32_bf16 v[112:115], v[124:127], v[172:175], v[112:115]
	v_mfma_f32_16x16x32_bf16 v[96:99], v[124:127], v[180:183], v[96:99]
	v_mfma_f32_16x16x32_bf16 v[96:99], v[128:131], v[184:187], v[96:99]
	v_mfma_f32_16x16x32_bf16 v[80:83], v[128:131], v[214:217], v[80:83]
	v_mfma_f32_16x16x32_bf16 v[80:83], v[124:127], v[188:191], v[80:83]
	v_mfma_f32_16x16x32_bf16 v[76:79], v[132:135], v[188:191], v[76:79]
	v_mfma_f32_16x16x32_bf16 v[76:79], v[144:147], v[214:217], v[76:79]
	v_mfma_f32_16x16x32_bf16 v[92:95], v[144:147], v[184:187], v[92:95]
	v_mfma_f32_16x16x32_bf16 v[92:95], v[132:135], v[180:183], v[92:95]
	v_mfma_f32_16x16x32_bf16 v[108:111], v[132:135], v[172:175], v[108:111]
	v_mfma_f32_16x16x32_bf16 v[108:111], v[144:147], v[176:179], v[108:111]
	v_mfma_f32_16x16x32_bf16 v[136:139], v[144:147], v[168:171], v[136:139]
	v_mfma_f32_16x16x32_bf16 v[136:139], v[132:135], v[164:167], v[136:139]
	v_mfma_f32_16x16x32_bf16 v[120:123], v[148:151], v[164:167], v[120:123]
	v_mfma_f32_16x16x32_bf16 v[120:123], v[152:155], v[168:171], v[120:123]
	v_mfma_f32_16x16x32_bf16 v[104:107], v[152:155], v[176:179], v[104:107]
	v_mfma_f32_16x16x32_bf16 v[104:107], v[148:151], v[172:175], v[104:107]
	v_mfma_f32_16x16x32_bf16 v[88:91], v[148:151], v[180:183], v[88:91]
	v_mfma_f32_16x16x32_bf16 v[88:91], v[152:155], v[184:187], v[88:91]
	v_mfma_f32_16x16x32_bf16 v[72:75], v[152:155], v[214:217], v[72:75]
	v_mfma_f32_16x16x32_bf16 v[72:75], v[148:151], v[188:191], v[72:75]
	v_mfma_f32_16x16x32_bf16 v[68:71], v[156:159], v[188:191], v[68:71]
	v_mfma_f32_16x16x32_bf16 v[68:71], v[160:163], v[214:217], v[68:71]
	v_mfma_f32_16x16x32_bf16 v[84:87], v[160:163], v[184:187], v[84:87]
	v_mfma_f32_16x16x32_bf16 v[84:87], v[156:159], v[180:183], v[84:87]
	v_mfma_f32_16x16x32_bf16 v[100:103], v[156:159], v[172:175], v[100:103]
	v_mfma_f32_16x16x32_bf16 v[100:103], v[160:163], v[176:179], v[100:103]
	v_mfma_f32_16x16x32_bf16 v[116:119], v[160:163], v[168:171], v[116:119]
	v_mfma_f32_16x16x32_bf16 v[116:119], v[156:159], v[164:167], v[116:119]
	s_setprio 0
	s_barrier
; #define PG8_STAGE(bufoff, gbase, voff) do { _Pragma("unroll") for (int _i = 0; _i < 2; ++_i) \
;         __builtin_amdgcn_global_load_lds((const unsigned*)((const char*)(gbase) + (voff)[_i]), (PG8_LAS unsigned*)(lds + (bufoff) + ldsw + _i * 8192), 16, 0, 0); } while (0)
; #define PG8_LDA(dst, b, h) do { _Pragma("unroll") for (int m = 0; m < 4; ++m) _Pragma("unroll") for (int k = 0; k < 2; ++k) dst[m][k] = *(const PG8_LAS bf16x8*)(lds + PG8_SA(b, h) + aoff + m * 2048 + k * 1024); } while (0)
; #define PG8_LDB(dst, b, h) do { _Pragma("unroll") for (int n = 0; n < 2; ++n) _Pragma("unroll") for (int k = 0; k < 2; ++k) dst[n][k] = *(const PG8_LAS bf16x8*)(lds + PG8_SB(b, h) + boff + n * 2048 + k * 1024); } while (0)
; #define PG8_WAIT_V(n) asm volatile("s_waitcnt vmcnt(" #n ")" ::: "memory")
; #define PG8_WAIT_L(n) asm volatile("s_waitcnt lgkmcnt(" #n ")" ::: "memory")
; #define PG8_BAR __builtin_amdgcn_s_barrier()
; #define PG8_SCHED __builtin_amdgcn_sched_barrier(0)
; template <class Epi, class Sched, bool ALIGN_EPI = false, bool SP2 = false, bool I8 = false>
; __device__ __forceinline__ void gemm_phase(PG8_LAS unsigned char* lds, const Gemm g, const Sched& S, const Epi& E) {
;     ...
;             PG8_LDA(At, 0, 1); PG8_STAGE(PG8_SB(0, 0), b2, voffB); PG8_STAGE(PG8_SB(0, 1), b2 + hstep, voffB); PG8_STAGE(PG8_SA(0, 0), a2, voffA);
;             PG8_WAIT_V(8); PG8_WAIT_L(0); PG8_BAR; PG8_MMA(1, 0, At, B0); PG8_MMA(1, 1, At, B1); PG8_BAR; PG8_SCHED;
;             PG8_LDB(B0, 1, 0); PG8_LDB(B1, 1, 1); PG8_SCHED; PG8_LDA(At, 1, 0); PG8_STAGE(PG8_SA(0, 1), a2 + hstep, voffA);
;             PG8_WAIT_V(8); PG8_WAIT_L(0); PG8_BAR; PG8_MMA(0, 0, At, B0); PG8_MMA(0, 1, At, B1); PG8_BAR; PG8_SCHED;
	s_add_i32 s56, s56, s40
	v_lshl_add_u64 v[218:219], s[26:27], 0, v[2:3]
	s_mov_b32 m0, s56
	ds_read_b128 v[164:167], v242 offset:16384
	ds_read_b128 v[168:171], v242 offset:17408
	ds_read_b128 v[172:175], v242 offset:18432
	ds_read_b128 v[176:179], v242 offset:19456
	ds_read_b128 v[180:183], v242 offset:20480
	ds_read_b128 v[184:187], v242 offset:21504
	ds_read_b128 v[188:191], v242 offset:22528
	ds_read_b128 v[214:217], v242 offset:23552
	global_load_lds_dwordx4 v[218:219], off
	s_add_i32 m0, s56, 0x2000
	s_add_u32 s56, s26, 0x100000
	v_lshl_add_u64 v[220:221], s[26:27], 0, v[204:205]
	s_addc_u32 s57, s27, 0
	s_add_i32 s58, s58, s40
	global_load_lds_dwordx4 v[220:221], off
	v_lshl_add_u64 v[222:223], s[56:57], 0, v[2:3]
	s_mov_b32 m0, s58
	v_lshl_add_u64 v[224:225], s[36:37], 0, v[206:207]
	global_load_lds_dwordx4 v[222:223], off
	v_lshl_add_u64 v[222:223], s[56:57], 0, v[204:205]
	s_add_i32 m0, s58, 0x2000
	s_nop 0
	global_load_lds_dwordx4 v[222:223], off
	v_lshl_add_u64 v[222:223], s[36:37], 0, v[208:209]
	s_waitcnt vmcnt(6)
	s_waitcnt lgkmcnt(0)
	s_barrier
	s_setprio 1
	s_waitcnt lgkmcnt(0)
	v_mfma_f32_16x16x32_bf16 v[64:67], v[124:127], v[164:167], v[64:67]
	v_mfma_f32_16x16x32_bf16 v[64:67], v[128:131], v[168:171], v[64:67]
	v_mfma_f32_16x16x32_bf16 v[48:51], v[128:131], v[176:179], v[48:51]
	v_mfma_f32_16x16x32_bf16 v[48:51], v[124:127], v[172:175], v[48:51]
	v_mfma_f32_16x16x32_bf16 v[32:35], v[124:127], v[180:183], v[32:35]
	v_mfma_f32_16x16x32_bf16 v[32:35], v[128:131], v[184:187], v[32:35]
	v_mfma_f32_16x16x32_bf16 v[16:19], v[128:131], v[214:217], v[16:19]
	v_mfma_f32_16x16x32_bf16 v[16:19], v[124:127], v[188:191], v[16:19]
	v_mfma_f32_16x16x32_bf16 v[12:15], v[132:135], v[188:191], v[12:15]
	v_mfma_f32_16x16x32_bf16 v[12:15], v[144:147], v[214:217], v[12:15]
	v_mfma_f32_16x16x32_bf16 v[28:31], v[144:147], v[184:187], v[28:31]
	v_mfma_f32_16x16x32_bf16 v[28:31], v[132:135], v[180:183], v[28:31]
	v_mfma_f32_16x16x32_bf16 v[44:47], v[132:135], v[172:175], v[44:47]
	v_mfma_f32_16x16x32_bf16 v[44:47], v[144:147], v[176:179], v[44:47]
	v_mfma_f32_16x16x32_bf16 v[60:63], v[144:147], v[168:171], v[60:63]
	v_mfma_f32_16x16x32_bf16 v[60:63], v[132:135], v[164:167], v[60:63]
	v_mfma_f32_16x16x32_bf16 v[56:59], v[148:151], v[164:167], v[56:59]
	v_mfma_f32_16x16x32_bf16 v[56:59], v[152:155], v[168:171], v[56:59]
	v_mfma_f32_16x16x32_bf16 v[40:43], v[152:155], v[176:179], v[40:43]
	v_mfma_f32_16x16x32_bf16 v[40:43], v[148:151], v[172:175], v[40:43]
	v_mfma_f32_16x16x32_bf16 v[24:27], v[148:151], v[180:183], v[24:27]
	v_mfma_f32_16x16x32_bf16 v[24:27], v[152:155], v[184:187], v[24:27]
	v_mfma_f32_16x16x32_bf16 v[8:11], v[152:155], v[214:217], v[8:11]
	v_mfma_f32_16x16x32_bf16 v[8:11], v[148:151], v[188:191], v[8:11]
	v_mfma_f32_16x16x32_bf16 v[4:7], v[156:159], v[188:191], v[4:7]
	v_mfma_f32_16x16x32_bf16 v[4:7], v[160:163], v[214:217], v[4:7]
	v_mfma_f32_16x16x32_bf16 v[20:23], v[160:163], v[184:187], v[20:23]
	v_mfma_f32_16x16x32_bf16 v[20:23], v[156:159], v[180:183], v[20:23]
	v_mfma_f32_16x16x32_bf16 v[36:39], v[156:159], v[172:175], v[36:39]
	v_mfma_f32_16x16x32_bf16 v[36:39], v[160:163], v[176:179], v[36:39]
	v_mfma_f32_16x16x32_bf16 v[52:55], v[160:163], v[168:171], v[52:55]
	v_mfma_f32_16x16x32_bf16 v[52:55], v[156:159], v[164:167], v[52:55]
	s_setprio 0
	s_barrier
	s_mov_b32 m0, s41
	s_nop 0
	global_load_lds_dwordx4 v[222:223], off
	s_mov_b32 m0, s42
	s_nop 0
	global_load_lds_dwordx4 v[224:225], off
	s_add_i32 s56, 0, 0x18000
	s_add_i32 s57, 0, 0x1c000
	v_add_u32_e32 v144, s56, v240
	v_add_u32_e32 v160, s57, v240
	ds_read_b128 v[124:127], v144
	ds_read_b128 v[128:131], v144 offset:1024
	ds_read_b128 v[132:135], v144 offset:2048
	ds_read_b128 v[144:147], v144 offset:3072
	ds_read_b128 v[148:151], v160
	ds_read_b128 v[152:155], v160 offset:1024
	ds_read_b128 v[156:159], v160 offset:2048
	ds_read_b128 v[160:163], v160 offset:3072
	s_add_u32 s36, s36, 0x100000
	s_addc_u32 s37, s37, 0
	s_mov_b32 m0, s43
	v_lshl_add_u64 v[226:227], s[36:37], 0, v[208:209]
	ds_read_b128 v[164:167], v242 offset:32768
	ds_read_b128 v[168:171], v242 offset:33792
	ds_read_b128 v[172:175], v242 offset:34816
	ds_read_b128 v[176:179], v242 offset:35840
	ds_read_b128 v[180:183], v242 offset:36864
	ds_read_b128 v[184:187], v242 offset:37888
	ds_read_b128 v[188:191], v242 offset:38912
	ds_read_b128 v[214:217], v242 offset:39936
	global_load_lds_dwordx4 v[226:227], off
	v_lshl_add_u64 v[226:227], s[36:37], 0, v[206:207]
	s_mov_b32 m0, s44
	s_nop 0
	global_load_lds_dwordx4 v[226:227], off
	s_waitcnt vmcnt(8)
	s_waitcnt lgkmcnt(0)
	s_barrier
; #define PG8_STAGE(bufoff, gbase, voff) do { _Pragma("unroll") for (int _i = 0; _i < 2; ++_i) \
;         __builtin_amdgcn_global_load_lds((const unsigned*)((const char*)(gbase) + (voff)[_i]), (PG8_LAS unsigned*)(lds + (bufoff) + ldsw + _i * 8192), 16, 0, 0); } while (0)
; #define PG8_LDA(dst, b, h) do { _Pragma("unroll") for (int m = 0; m < 4; ++m) _Pragma("unroll") for (int k = 0; k < 2; ++k) dst[m][k] = *(const PG8_LAS bf16x8*)(lds + PG8_SA(b, h) + aoff + m * 2048 + k * 1024); } while (0)
; #define PG8_WAIT_V(n) asm volatile("s_waitcnt vmcnt(" #n ")" ::: "memory")
; #define PG8_WAIT_L(n) asm volatile("s_waitcnt lgkmcnt(" #n ")" ::: "memory")
; #define PG8_BAR __builtin_amdgcn_s_barrier()
; #define PG8_SCHED __builtin_amdgcn_sched_barrier(0)
; template <class Epi, class Sched, bool ALIGN_EPI = false, bool SP2 = false, bool I8 = false>
; __device__ __forceinline__ void gemm_phase(PG8_LAS unsigned char* lds, const Gemm g, const Sched& S, const Epi& E) {
;     ...
;             PG8_WAIT_V(8); PG8_WAIT_L(0); PG8_BAR; PG8_MMA(0, 0, At, B0); PG8_MMA(0, 1, At, B1); PG8_BAR; PG8_SCHED;
;             PG8_LDA(At, 1, 1); PG8_STAGE(PG8_SB(1, 0), b3, voffB); PG8_STAGE(PG8_SB(1, 1), b3 + hstep, voffB); PG8_STAGE(PG8_SA(1, 0), a3, voffA);
;             PG8_WAIT_V(8); PG8_WAIT_L(0); PG8_BAR; PG8_MMA(1, 0, At, B0); PG8_MMA(1, 1, At, B1); PG8_BAR; PG8_SCHED;
	s_setprio 1
	s_waitcnt lgkmcnt(0)
	v_mfma_f32_16x16x32_bf16 v[140:143], v[124:127], v[164:167], v[140:143]
	v_mfma_f32_16x16x32_bf16 v[140:143], v[128:131], v[168:171], v[140:143]
	v_mfma_f32_16x16x32_bf16 v[112:115], v[128:131], v[176:179], v[112:115]
	v_mfma_f32_16x16x32_bf16 v[112:115], v[124:127], v[172:175], v[112:115]
	v_mfma_f32_16x16x32_bf16 v[96:99], v[124:127], v[180:183], v[96:99]
	v_mfma_f32_16x16x32_bf16 v[96:99], v[128:131], v[184:187], v[96:99]
	v_mfma_f32_16x16x32_bf16 v[80:83], v[128:131], v[214:217], v[80:83]
	v_mfma_f32_16x16x32_bf16 v[80:83], v[124:127], v[188:191], v[80:83]
	v_mfma_f32_16x16x32_bf16 v[76:79], v[132:135], v[188:191], v[76:79]
	v_mfma_f32_16x16x32_bf16 v[76:79], v[144:147], v[214:217], v[76:79]
	v_mfma_f32_16x16x32_bf16 v[92:95], v[144:147], v[184:187], v[92:95]
	v_mfma_f32_16x16x32_bf16 v[92:95], v[132:135], v[180:183], v[92:95]
	v_mfma_f32_16x16x32_bf16 v[108:111], v[132:135], v[172:175], v[108:111]
	v_mfma_f32_16x16x32_bf16 v[108:111], v[144:147], v[176:179], v[108:111]
	v_mfma_f32_16x16x32_bf16 v[136:139], v[144:147], v[168:171], v[136:139]
	v_mfma_f32_16x16x32_bf16 v[136:139], v[132:135], v[164:167], v[136:139]
	v_mfma_f32_16x16x32_bf16 v[120:123], v[148:151], v[164:167], v[120:123]
	v_mfma_f32_16x16x32_bf16 v[120:123], v[152:155], v[168:171], v[120:123]
	v_mfma_f32_16x16x32_bf16 v[104:107], v[152:155], v[176:179], v[104:107]
	v_mfma_f32_16x16x32_bf16 v[104:107], v[148:151], v[172:175], v[104:107]
	v_mfma_f32_16x16x32_bf16 v[88:91], v[148:151], v[180:183], v[88:91]
	v_mfma_f32_16x16x32_bf16 v[88:91], v[152:155], v[184:187], v[88:91]
	v_mfma_f32_16x16x32_bf16 v[72:75], v[152:155], v[214:217], v[72:75]
	v_mfma_f32_16x16x32_bf16 v[72:75], v[148:151], v[188:191], v[72:75]
	v_mfma_f32_16x16x32_bf16 v[68:71], v[156:159], v[188:191], v[68:71]
	v_mfma_f32_16x16x32_bf16 v[68:71], v[160:163], v[214:217], v[68:71]
	v_mfma_f32_16x16x32_bf16 v[84:87], v[160:163], v[184:187], v[84:87]
	v_mfma_f32_16x16x32_bf16 v[84:87], v[156:159], v[180:183], v[84:87]
	v_mfma_f32_16x16x32_bf16 v[100:103], v[156:159], v[172:175], v[100:103]
	v_mfma_f32_16x16x32_bf16 v[100:103], v[160:163], v[176:179], v[100:103]
	v_mfma_f32_16x16x32_bf16 v[116:119], v[160:163], v[168:171], v[116:119]
	v_mfma_f32_16x16x32_bf16 v[116:119], v[156:159], v[164:167], v[116:119]
	s_setprio 0
	s_barrier
	s_add_i32 s36, s56, s40
	v_lshl_add_u64 v[218:219], v[218:219], 0, s[84:85]
	s_mov_b32 m0, s36
	ds_read_b128 v[164:167], v242 offset:49152
	ds_read_b128 v[168:171], v242 offset:50176
	ds_read_b128 v[172:175], v242 offset:51200
	ds_read_b128 v[176:179], v242 offset:52224
	ds_read_b128 v[180:183], v242 offset:53248
	ds_read_b128 v[184:187], v242 offset:54272
	ds_read_b128 v[188:191], v242 offset:55296
	ds_read_b128 v[214:217], v242 offset:56320
	global_load_lds_dwordx4 v[218:219], off
	s_add_i32 m0, s36, 0x2000
	s_add_u32 s26, s26, 0x100080
	v_lshl_add_u64 v[218:219], v[220:221], 0, s[84:85]
	s_addc_u32 s27, s27, 0
	s_add_i32 s36, s57, s40
	global_load_lds_dwordx4 v[218:219], off
	v_lshl_add_u64 v[218:219], s[26:27], 0, v[2:3]
	s_mov_b32 m0, s36
	s_nop 0
	global_load_lds_dwordx4 v[218:219], off
	v_lshl_add_u64 v[218:219], s[26:27], 0, v[204:205]
	s_add_i32 m0, s36, 0x2000
	s_nop 0
	global_load_lds_dwordx4 v[218:219], off
	s_cmp_eq_u32 s55, 60
	s_cbranch_scc0 .Ldefer_1456_body
	v_lshl_add_u64 v[218:219], v[222:223], 0, s[84:85]
	s_mov_b32 m0, s45
	s_nop 0
	global_load_lds_dwordx4 v[218:219], off
	v_lshl_add_u64 v[218:219], v[224:225], 0, s[84:85]
	s_mov_b32 m0, s46
	s_nop 0
	global_load_lds_dwordx4 v[218:219], off
.Ldefer_1456_body:
	s_waitcnt vmcnt(6)
	s_waitcnt lgkmcnt(0)
	s_barrier
	s_setprio 1
	s_waitcnt lgkmcnt(0)
	v_mfma_f32_16x16x32_bf16 v[64:67], v[124:127], v[164:167], v[64:67]
	v_mfma_f32_16x16x32_bf16 v[64:67], v[128:131], v[168:171], v[64:67]
	v_mfma_f32_16x16x32_bf16 v[48:51], v[128:131], v[176:179], v[48:51]
	v_mfma_f32_16x16x32_bf16 v[48:51], v[124:127], v[172:175], v[48:51]
	v_mfma_f32_16x16x32_bf16 v[32:35], v[124:127], v[180:183], v[32:35]
	v_mfma_f32_16x16x32_bf16 v[32:35], v[128:131], v[184:187], v[32:35]
	v_mfma_f32_16x16x32_bf16 v[16:19], v[128:131], v[214:217], v[16:19]
	v_mfma_f32_16x16x32_bf16 v[16:19], v[124:127], v[188:191], v[16:19]
	v_mfma_f32_16x16x32_bf16 v[12:15], v[132:135], v[188:191], v[12:15]
	v_mfma_f32_16x16x32_bf16 v[12:15], v[144:147], v[214:217], v[12:15]
	v_mfma_f32_16x16x32_bf16 v[28:31], v[144:147], v[184:187], v[28:31]
	v_mfma_f32_16x16x32_bf16 v[28:31], v[132:135], v[180:183], v[28:31]
	v_mfma_f32_16x16x32_bf16 v[44:47], v[132:135], v[172:175], v[44:47]
	v_mfma_f32_16x16x32_bf16 v[44:47], v[144:147], v[176:179], v[44:47]
	v_mfma_f32_16x16x32_bf16 v[60:63], v[144:147], v[168:171], v[60:63]
	v_mfma_f32_16x16x32_bf16 v[60:63], v[132:135], v[164:167], v[60:63]
	v_mfma_f32_16x16x32_bf16 v[56:59], v[148:151], v[164:167], v[56:59]
	v_mfma_f32_16x16x32_bf16 v[56:59], v[152:155], v[168:171], v[56:59]
	v_mfma_f32_16x16x32_bf16 v[40:43], v[152:155], v[176:179], v[40:43]
	v_mfma_f32_16x16x32_bf16 v[40:43], v[148:151], v[172:175], v[40:43]
	v_mfma_f32_16x16x32_bf16 v[24:27], v[148:151], v[180:183], v[24:27]
	v_mfma_f32_16x16x32_bf16 v[24:27], v[152:155], v[184:187], v[24:27]
	v_mfma_f32_16x16x32_bf16 v[8:11], v[152:155], v[214:217], v[8:11]
	v_mfma_f32_16x16x32_bf16 v[8:11], v[148:151], v[188:191], v[8:11]
	v_mfma_f32_16x16x32_bf16 v[4:7], v[156:159], v[188:191], v[4:7]
	v_mfma_f32_16x16x32_bf16 v[4:7], v[160:163], v[214:217], v[4:7]
	v_mfma_f32_16x16x32_bf16 v[20:23], v[160:163], v[184:187], v[20:23]
	v_mfma_f32_16x16x32_bf16 v[20:23], v[156:159], v[180:183], v[20:23]
	v_mfma_f32_16x16x32_bf16 v[36:39], v[156:159], v[172:175], v[36:39]
	v_mfma_f32_16x16x32_bf16 v[36:39], v[160:163], v[176:179], v[36:39]
	v_mfma_f32_16x16x32_bf16 v[52:55], v[160:163], v[168:171], v[52:55]
	v_mfma_f32_16x16x32_bf16 v[52:55], v[156:159], v[164:167], v[52:55]
	s_setprio 0
	s_barrier
	s_add_i32 s55, s55, 2
	s_add_u32 s24, s24, 0x100
	s_addc_u32 s25, s25, 0
	s_add_u32 s53, s53, 0x100
	s_addc_u32 s54, s54, 0
	s_cmp_gt_u32 s55, 61
	s_cbranch_scc0 .LBB0_1456

; #define PG8_STAGE(bufoff, gbase, voff) do { _Pragma("unroll") for (int _i = 0; _i < 2; ++_i) \
;         __builtin_amdgcn_global_load_lds((const unsigned*)((const char*)(gbase) + (voff)[_i]), (PG8_LAS unsigned*)(lds + (bufoff) + ldsw + _i * 8192), 16, 0, 0); } while (0)
; #define PG8_LDA(dst, b, h) do { _Pragma("unroll") for (int m = 0; m < 4; ++m) _Pragma("unroll") for (int k = 0; k < 2; ++k) dst[m][k] = *(const PG8_LAS bf16x8*)(lds + PG8_SA(b, h) + aoff + m * 2048 + k * 1024); } while (0)
; #define PG8_LDB(dst, b, h) do { _Pragma("unroll") for (int n = 0; n < 2; ++n) _Pragma("unroll") for (int k = 0; k < 2; ++k) dst[n][k] = *(const PG8_LAS bf16x8*)(lds + PG8_SB(b, h) + boff + n * 2048 + k * 1024); } while (0)
; #define PG8_WAIT_V(n) asm volatile("s_waitcnt vmcnt(" #n ")" ::: "memory")
; #define PG8_WAIT_L(n) asm volatile("s_waitcnt lgkmcnt(" #n ")" ::: "memory")
; #define PG8_BAR __builtin_amdgcn_s_barrier()
; #define PG8_SCHED __builtin_amdgcn_sched_barrier(0)
; template <class Epi, class Sched, bool ALIGN_EPI = false, bool SP2 = false, bool I8 = false>
; __device__ __forceinline__ void gemm_phase(PG8_LAS unsigned char* lds, const Gemm g, const Sched& S, const Epi& E) {
;     ...
;         const bool has_next = S.next(ui + 1, nxt);
;         const char* nA = has_next ? (const char*)g.A + (size_t)nxt.pm * tstep : cA; const char* nB = has_next ? (const char*)g.Bt + (size_t)nxt.pn * tstep : cB;
;         for (int t = 0; t < nt; t += 2) {
;             const bool last = (t == nt - 2);
;             const char* a1 = cA + (size_t)(t + 1) * kstep;
;             const char* a2 = last ? nA : cA + (size_t)(t + 2) * kstep; const char* b2 = last ? nB : cB + (size_t)(t + 2) * kstep;
;             const char* a3 = a2 + kstep; const char* b3 = b2 + kstep;
;             if (last && has_next) S.a_ready(nxt);
;             if constexpr (SP2) {
;             PG8_LDB(B0, 0, 0); PG8_LDB(B1, 0, 1); PG8_SCHED; PG8_LDA(At, 0, 0); PG8_STAGE(PG8_SA(1, 1), a1 + hstep, voffA);
;             PG8_WAIT_V(8); PG8_WAIT_L(0); PG8_BAR; PG8_MMA(0, 0, At, B0); PG8_MMA(0, 1, At, B1); PG8_BAR; PG8_SCHED;
;             PG8_LDA(At, 0, 1); PG8_STAGE(PG8_SB(0, 0), b2, voffB); PG8_STAGE(PG8_SB(0, 1), b2 + hstep, voffB); PG8_STAGE(PG8_SA(0, 0), a2, voffA);
;             PG8_WAIT_V(8); PG8_WAIT_L(0); PG8_BAR; PG8_MMA(1, 0, At, B0); PG8_MMA(1, 1, At, B1); PG8_BAR; PG8_SCHED;
.LBB0_1590:
	s_ashr_i32 s25, s24, 31
	s_lshl_b64 s[26:27], s[24:25], 20
	s_add_u32 s26, s28, s26
	s_addc_u32 s27, s42, s27
	s_and_b64 s[36:37], s[10:11], exec
	s_cselect_b32 s25, s27, s41
	s_cselect_b32 s57, s26, s40
	s_ashr_i32 s23, s22, 31
	s_lshl_b64 s[36:37], s[22:23], 20
	s_add_u32 s36, s43, s36
	s_addc_u32 s37, s46, s37
	s_and_b64 s[48:49], s[10:11], exec
	s_cselect_b32 s23, s37, s45
	s_cselect_b32 s58, s36, s44
	s_add_u32 s40, s40, 0x80080
	s_addc_u32 s41, s41, 0
	s_add_u32 s59, s44, 0x100
	s_addc_u32 s60, s45, 0
	s_mov_b32 s61, -2
	s_add_u32 s44, s40, 0xfff80080
	s_addc_u32 s45, s41, -1
	s_add_i32 s64, 0, 0x10000
	s_cmp_eq_u32 s61, 28
	s_cselect_b32 s49, s25, s45
	s_cselect_b32 s48, s57, s44
	s_cselect_b32 s45, s23, s60
	s_cselect_b32 s44, s58, s59
	s_add_i32 s67, 0, 0x14000
	v_add_u32_e32 v144, s64, v167
	v_add_u32_e32 v158, s67, v167
	ds_read_b128 v[36:39], v144
	ds_read_b128 v[44:47], v144 offset:1024
	ds_read_b128 v[140:143], v144 offset:2048
	ds_read_b128 v[144:147], v144 offset:3072
	ds_read_b128 v[160:163], v158
	ds_read_b128 v[172:175], v158 offset:1024
	ds_read_b128 v[176:179], v158 offset:2048
	ds_read_b128 v[180:183], v158 offset:3072
	v_lshl_add_u64 v[164:165], s[40:41], 0, v[154:155]
	s_add_i32 m0, s50, 0xc000
	ds_read_b128 v[184:187], v171
	ds_read_b128 v[188:191], v171 offset:1024
	ds_read_b128 v[204:207], v171 offset:2048
	ds_read_b128 v[208:211], v171 offset:3072
	ds_read_b128 v[212:215], v171 offset:4096
	ds_read_b128 v[216:219], v171 offset:5120
	ds_read_b128 v[220:223], v171 offset:6144
	ds_read_b128 v[224:227], v171 offset:7168
	global_load_lds_dwordx4 v[164:165], off
	v_lshl_add_u64 v[164:165], s[40:41], 0, v[156:157]
	s_add_i32 m0, s50, 0xe000
	s_nop 0
	global_load_lds_dwordx4 v[164:165], off
	s_waitcnt vmcnt(8)
	s_waitcnt lgkmcnt(0)
	s_barrier
	s_setprio 1
	s_waitcnt lgkmcnt(0)
	v_mfma_i32_16x16x64_i8 v[136:139], v[36:39], v[184:187], 0
	v_mfma_i32_16x16x64_i8 v[136:139], v[44:47], v[188:191], v[136:139]
	v_mfma_i32_16x16x64_i8 v[120:123], v[44:47], v[208:211], 0
	v_mfma_i32_16x16x64_i8 v[120:123], v[36:39], v[204:207], v[120:123]
	v_mfma_i32_16x16x64_i8 v[104:107], v[36:39], v[212:215], 0
	v_mfma_i32_16x16x64_i8 v[104:107], v[44:47], v[216:219], v[104:107]
	v_mfma_i32_16x16x64_i8 v[88:91], v[44:47], v[224:227], 0
	v_mfma_i32_16x16x64_i8 v[88:91], v[36:39], v[220:223], v[88:91]
	v_mfma_i32_16x16x64_i8 v[80:83], v[140:143], v[220:223], 0
	v_mfma_i32_16x16x64_i8 v[80:83], v[144:147], v[224:227], v[80:83]
	v_mfma_i32_16x16x64_i8 v[96:99], v[144:147], v[216:219], 0
	v_mfma_i32_16x16x64_i8 v[96:99], v[140:143], v[212:215], v[96:99]
	v_mfma_i32_16x16x64_i8 v[112:115], v[140:143], v[204:207], 0
	v_mfma_i32_16x16x64_i8 v[112:115], v[144:147], v[208:211], v[112:115]
	v_mfma_i32_16x16x64_i8 v[128:131], v[144:147], v[188:191], 0
	v_mfma_i32_16x16x64_i8 v[128:131], v[140:143], v[184:187], v[128:131]
	v_mfma_i32_16x16x64_i8 v[132:135], v[160:163], v[184:187], 0
	v_mfma_i32_16x16x64_i8 v[132:135], v[172:175], v[188:191], v[132:135]
	v_mfma_i32_16x16x64_i8 v[116:119], v[172:175], v[208:211], 0
	v_mfma_i32_16x16x64_i8 v[116:119], v[160:163], v[204:207], v[116:119]
	v_mfma_i32_16x16x64_i8 v[100:103], v[160:163], v[212:215], 0
	v_mfma_i32_16x16x64_i8 v[100:103], v[172:175], v[216:219], v[100:103]
	v_mfma_i32_16x16x64_i8 v[84:87], v[172:175], v[224:227], 0
	v_mfma_i32_16x16x64_i8 v[84:87], v[160:163], v[220:223], v[84:87]
	v_mfma_i32_16x16x64_i8 v[76:79], v[176:179], v[220:223], 0
	v_mfma_i32_16x16x64_i8 v[76:79], v[180:183], v[224:227], v[76:79]
	v_mfma_i32_16x16x64_i8 v[92:95], v[180:183], v[216:219], 0
	v_mfma_i32_16x16x64_i8 v[92:95], v[176:179], v[212:215], v[92:95]
	v_mfma_i32_16x16x64_i8 v[108:111], v[176:179], v[204:207], 0
	v_mfma_i32_16x16x64_i8 v[108:111], v[180:183], v[208:211], v[108:111]
	v_mfma_i32_16x16x64_i8 v[124:127], v[180:183], v[188:191], 0
	v_mfma_i32_16x16x64_i8 v[124:127], v[176:179], v[184:187], v[124:127]
	s_setprio 0
	s_barrier
	s_add_i32 s64, s64, s47
	v_lshl_add_u64 v[164:165], s[44:45], 0, v[2:3]
	s_mov_b32 m0, s64
	ds_read_b128 v[184:187], v171 offset:16384
	ds_read_b128 v[188:191], v171 offset:17408
	ds_read_b128 v[204:207], v171 offset:18432
	ds_read_b128 v[208:211], v171 offset:19456
	ds_read_b128 v[212:215], v171 offset:20480
	ds_read_b128 v[216:219], v171 offset:21504
	ds_read_b128 v[220:223], v171 offset:22528
	ds_read_b128 v[224:227], v171 offset:23552
	global_load_lds_dwordx4 v[164:165], off
	s_add_i32 m0, s64, 0x2000
	s_add_u32 s64, s44, 0x80000
	v_lshl_add_u64 v[228:229], s[44:45], 0, v[148:149]
	s_addc_u32 s65, s45, 0
	s_add_i32 s67, s67, s47
	global_load_lds_dwordx4 v[228:229], off
	v_lshl_add_u64 v[240:241], s[64:65], 0, v[2:3]
	s_mov_b32 m0, s67
	v_lshl_add_u64 v[242:243], s[48:49], 0, v[150:151]
	global_load_lds_dwordx4 v[240:241], off
	v_lshl_add_u64 v[240:241], s[64:65], 0, v[148:149]
	s_add_i32 m0, s67, 0x2000
	s_nop 0
	global_load_lds_dwordx4 v[240:241], off
	v_lshl_add_u64 v[240:241], s[48:49], 0, v[152:153]
	s_waitcnt vmcnt(6)
	s_waitcnt lgkmcnt(0)
	s_barrier
; #define PG8_STAGE(bufoff, gbase, voff) do { _Pragma("unroll") for (int _i = 0; _i < 2; ++_i) \
;         __builtin_amdgcn_global_load_lds((const unsigned*)((const char*)(gbase) + (voff)[_i]), (PG8_LAS unsigned*)(lds + (bufoff) + ldsw + _i * 8192), 16, 0, 0); } while (0)
; #define PG8_LDA(dst, b, h) do { _Pragma("unroll") for (int m = 0; m < 4; ++m) _Pragma("unroll") for (int k = 0; k < 2; ++k) dst[m][k] = *(const PG8_LAS bf16x8*)(lds + PG8_SA(b, h) + aoff + m * 2048 + k * 1024); } while (0)
; #define PG8_LDB(dst, b, h) do { _Pragma("unroll") for (int n = 0; n < 2; ++n) _Pragma("unroll") for (int k = 0; k < 2; ++k) dst[n][k] = *(const PG8_LAS bf16x8*)(lds + PG8_SB(b, h) + boff + n * 2048 + k * 1024); } while (0)
; #define PG8_WAIT_V(n) asm volatile("s_waitcnt vmcnt(" #n ")" ::: "memory")
; #define PG8_WAIT_L(n) asm volatile("s_waitcnt lgkmcnt(" #n ")" ::: "memory")
; #define PG8_BAR __builtin_amdgcn_s_barrier()
; #define PG8_SCHED __builtin_amdgcn_sched_barrier(0)
; template <class Epi, class Sched, bool ALIGN_EPI = false, bool SP2 = false, bool I8 = false>
; __device__ __forceinline__ void gemm_phase(PG8_LAS unsigned char* lds, const Gemm g, const Sched& S, const Epi& E) {
;     ...
;             PG8_WAIT_V(8); PG8_WAIT_L(0); PG8_BAR; PG8_MMA(1, 0, At, B0); PG8_MMA(1, 1, At, B1); PG8_BAR; PG8_SCHED;
;             PG8_LDB(B0, 1, 0); PG8_LDB(B1, 1, 1); PG8_SCHED; PG8_LDA(At, 1, 0); PG8_STAGE(PG8_SA(0, 1), a2 + hstep, voffA);
;             PG8_WAIT_V(8); PG8_WAIT_L(0); PG8_BAR; PG8_MMA(0, 0, At, B0); PG8_MMA(0, 1, At, B1); PG8_BAR; PG8_SCHED;
;             PG8_LDA(At, 1, 1); PG8_STAGE(PG8_SB(1, 0), b3, voffB); PG8_STAGE(PG8_SB(1, 1), b3 + hstep, voffB); PG8_STAGE(PG8_SA(1, 0), a3, voffA);
;             PG8_WAIT_V(8); PG8_WAIT_L(0); PG8_BAR; PG8_MMA(1, 0, At, B0); PG8_MMA(1, 1, At, B1); PG8_BAR; PG8_SCHED;
	s_setprio 1
	s_waitcnt lgkmcnt(0)
	v_mfma_i32_16x16x64_i8 v[72:75], v[36:39], v[184:187], 0
	v_mfma_i32_16x16x64_i8 v[72:75], v[44:47], v[188:191], v[72:75]
	v_mfma_i32_16x16x64_i8 v[56:59], v[44:47], v[208:211], 0
	v_mfma_i32_16x16x64_i8 v[56:59], v[36:39], v[204:207], v[56:59]
	v_mfma_i32_16x16x64_i8 v[32:35], v[36:39], v[212:215], 0
	v_mfma_i32_16x16x64_i8 v[32:35], v[44:47], v[216:219], v[32:35]
	v_mfma_i32_16x16x64_i8 v[16:19], v[44:47], v[224:227], 0
	v_mfma_i32_16x16x64_i8 v[16:19], v[36:39], v[220:223], v[16:19]
	v_mfma_i32_16x16x64_i8 v[8:11], v[140:143], v[220:223], 0
	v_mfma_i32_16x16x64_i8 v[8:11], v[144:147], v[224:227], v[8:11]
	v_mfma_i32_16x16x64_i8 v[24:27], v[144:147], v[216:219], 0
	v_mfma_i32_16x16x64_i8 v[24:27], v[140:143], v[212:215], v[24:27]
	v_mfma_i32_16x16x64_i8 v[48:51], v[140:143], v[204:207], 0
	v_mfma_i32_16x16x64_i8 v[48:51], v[144:147], v[208:211], v[48:51]
	v_mfma_i32_16x16x64_i8 v[64:67], v[144:147], v[188:191], 0
	v_mfma_i32_16x16x64_i8 v[64:67], v[140:143], v[184:187], v[64:67]
	v_mfma_i32_16x16x64_i8 v[36:39], v[160:163], v[184:187], 0
	v_mfma_i32_16x16x64_i8 v[36:39], v[172:175], v[188:191], v[36:39]
	v_mfma_i32_16x16x64_i8 v[52:55], v[172:175], v[208:211], 0
	v_mfma_i32_16x16x64_i8 v[52:55], v[160:163], v[204:207], v[52:55]
	v_mfma_i32_16x16x64_i8 v[28:31], v[160:163], v[212:215], 0
	v_mfma_i32_16x16x64_i8 v[28:31], v[172:175], v[216:219], v[28:31]
	v_mfma_i32_16x16x64_i8 v[12:15], v[172:175], v[224:227], 0
	v_mfma_i32_16x16x64_i8 v[12:15], v[160:163], v[220:223], v[12:15]
	v_mfma_i32_16x16x64_i8 v[4:7], v[176:179], v[220:223], 0
	v_mfma_i32_16x16x64_i8 v[4:7], v[180:183], v[224:227], v[4:7]
	v_mfma_i32_16x16x64_i8 v[20:23], v[180:183], v[216:219], 0
	v_mfma_i32_16x16x64_i8 v[20:23], v[176:179], v[212:215], v[20:23]
	v_mfma_i32_16x16x64_i8 v[40:43], v[176:179], v[204:207], 0
	v_mfma_i32_16x16x64_i8 v[40:43], v[180:183], v[208:211], v[40:43]
	v_mfma_i32_16x16x64_i8 v[44:47], v[180:183], v[188:191], 0
	v_mfma_i32_16x16x64_i8 v[44:47], v[176:179], v[184:187], v[44:47]
	s_setprio 0
	s_barrier
	s_mov_b32 m0, s50
	s_nop 0
	global_load_lds_dwordx4 v[240:241], off
	s_mov_b32 m0, s51
	s_nop 0
	global_load_lds_dwordx4 v[242:243], off
	s_add_i32 s64, 0, 0x18000
	s_add_i32 s65, 0, 0x1c000
	v_add_u32_e32 v144, s64, v167
	v_add_u32_e32 v158, s65, v167
	ds_read_b128 v[60:63], v144
	ds_read_b128 v[68:71], v144 offset:1024
	ds_read_b128 v[140:143], v144 offset:2048
	ds_read_b128 v[144:147], v144 offset:3072
	ds_read_b128 v[160:163], v158
	ds_read_b128 v[172:175], v158 offset:1024
	ds_read_b128 v[176:179], v158 offset:2048
	ds_read_b128 v[180:183], v158 offset:3072
	s_add_u32 s48, s48, 0x80000
	s_addc_u32 s49, s49, 0
	s_mov_b32 m0, s52
	v_lshl_add_u64 v[244:245], s[48:49], 0, v[152:153]
	ds_read_b128 v[184:187], v171 offset:32768
	ds_read_b128 v[188:191], v171 offset:33792
	ds_read_b128 v[204:207], v171 offset:34816
	ds_read_b128 v[208:211], v171 offset:35840
	ds_read_b128 v[212:215], v171 offset:36864
	ds_read_b128 v[216:219], v171 offset:37888
	ds_read_b128 v[220:223], v171 offset:38912
	ds_read_b128 v[224:227], v171 offset:39936
	global_load_lds_dwordx4 v[244:245], off
	v_lshl_add_u64 v[244:245], s[48:49], 0, v[150:151]
	s_mov_b32 m0, s53
	s_nop 0
	global_load_lds_dwordx4 v[244:245], off
	s_waitcnt vmcnt(8)
	s_waitcnt lgkmcnt(0)
	s_barrier
	s_setprio 1
	s_waitcnt lgkmcnt(0)
	v_mfma_i32_16x16x64_i8 v[136:139], v[60:63], v[184:187], v[136:139]
	v_mfma_i32_16x16x64_i8 v[136:139], v[68:71], v[188:191], v[136:139]
	v_mfma_i32_16x16x64_i8 v[120:123], v[68:71], v[208:211], v[120:123]
	v_mfma_i32_16x16x64_i8 v[120:123], v[60:63], v[204:207], v[120:123]
	v_mfma_i32_16x16x64_i8 v[104:107], v[60:63], v[212:215], v[104:107]
	v_mfma_i32_16x16x64_i8 v[104:107], v[68:71], v[216:219], v[104:107]
	v_mfma_i32_16x16x64_i8 v[88:91], v[68:71], v[224:227], v[88:91]
	v_mfma_i32_16x16x64_i8 v[88:91], v[60:63], v[220:223], v[88:91]
	v_mfma_i32_16x16x64_i8 v[80:83], v[140:143], v[220:223], v[80:83]
	v_mfma_i32_16x16x64_i8 v[80:83], v[144:147], v[224:227], v[80:83]
	v_mfma_i32_16x16x64_i8 v[96:99], v[144:147], v[216:219], v[96:99]
	v_mfma_i32_16x16x64_i8 v[96:99], v[140:143], v[212:215], v[96:99]
	v_mfma_i32_16x16x64_i8 v[112:115], v[140:143], v[204:207], v[112:115]
	v_mfma_i32_16x16x64_i8 v[112:115], v[144:147], v[208:211], v[112:115]
	v_mfma_i32_16x16x64_i8 v[128:131], v[144:147], v[188:191], v[128:131]
	v_mfma_i32_16x16x64_i8 v[128:131], v[140:143], v[184:187], v[128:131]
	v_mfma_i32_16x16x64_i8 v[132:135], v[160:163], v[184:187], v[132:135]
	v_mfma_i32_16x16x64_i8 v[132:135], v[172:175], v[188:191], v[132:135]
	v_mfma_i32_16x16x64_i8 v[116:119], v[172:175], v[208:211], v[116:119]
	v_mfma_i32_16x16x64_i8 v[116:119], v[160:163], v[204:207], v[116:119]
	v_mfma_i32_16x16x64_i8 v[100:103], v[160:163], v[212:215], v[100:103]
	v_mfma_i32_16x16x64_i8 v[100:103], v[172:175], v[216:219], v[100:103]
	v_mfma_i32_16x16x64_i8 v[84:87], v[172:175], v[224:227], v[84:87]
	v_mfma_i32_16x16x64_i8 v[84:87], v[160:163], v[220:223], v[84:87]
	v_mfma_i32_16x16x64_i8 v[76:79], v[176:179], v[220:223], v[76:79]
	v_mfma_i32_16x16x64_i8 v[76:79], v[180:183], v[224:227], v[76:79]
	v_mfma_i32_16x16x64_i8 v[92:95], v[180:183], v[216:219], v[92:95]
	v_mfma_i32_16x16x64_i8 v[92:95], v[176:179], v[212:215], v[92:95]
	v_mfma_i32_16x16x64_i8 v[108:111], v[176:179], v[204:207], v[108:111]
	v_mfma_i32_16x16x64_i8 v[108:111], v[180:183], v[208:211], v[108:111]
	v_mfma_i32_16x16x64_i8 v[124:127], v[180:183], v[188:191], v[124:127]
	v_mfma_i32_16x16x64_i8 v[124:127], v[176:179], v[184:187], v[124:127]
	s_setprio 0
	s_barrier
	s_add_i32 s48, s64, s47
	v_lshl_add_u64 v[164:165], v[164:165], 0, s[84:85]
	s_mov_b32 m0, s48
	ds_read_b128 v[184:187], v171 offset:49152
	ds_read_b128 v[188:191], v171 offset:50176
	ds_read_b128 v[204:207], v171 offset:51200
	ds_read_b128 v[208:211], v171 offset:52224
	ds_read_b128 v[212:215], v171 offset:53248
	ds_read_b128 v[216:219], v171 offset:54272
	ds_read_b128 v[220:223], v171 offset:55296
	ds_read_b128 v[224:227], v171 offset:56320
	global_load_lds_dwordx4 v[164:165], off
	s_add_i32 m0, s48, 0x2000
	s_add_u32 s44, s44, 0x80080
	v_lshl_add_u64 v[164:165], v[228:229], 0, s[84:85]
	s_addc_u32 s45, s45, 0
	s_add_i32 s48, s65, s47
	global_load_lds_dwordx4 v[164:165], off
	v_lshl_add_u64 v[164:165], s[44:45], 0, v[2:3]
	s_mov_b32 m0, s48
	s_nop 0
	global_load_lds_dwordx4 v[164:165], off
	v_lshl_add_u64 v[164:165], s[44:45], 0, v[148:149]
	s_add_i32 m0, s48, 0x2000
	s_nop 0
	global_load_lds_dwordx4 v[164:165], off
	s_cmp_eq_u32 s61, 28
	s_cbranch_scc0 .Ldefer_1591_peel
	v_lshl_add_u64 v[164:165], v[240:241], 0, s[84:85]
	s_mov_b32 m0, s54
	s_nop 0
	global_load_lds_dwordx4 v[164:165], off
	v_lshl_add_u64 v[164:165], v[242:243], 0, s[84:85]
	s_mov_b32 m0, s55
	s_nop 0
	global_load_lds_dwordx4 v[164:165], off
; #define PG8_STAGE(bufoff, gbase, voff) do { _Pragma("unroll") for (int _i = 0; _i < 2; ++_i) \
;         __builtin_amdgcn_global_load_lds((const unsigned*)((const char*)(gbase) + (voff)[_i]), (PG8_LAS unsigned*)(lds + (bufoff) + ldsw + _i * 8192), 16, 0, 0); } while (0)
; #define PG8_LDA(dst, b, h) do { _Pragma("unroll") for (int m = 0; m < 4; ++m) _Pragma("unroll") for (int k = 0; k < 2; ++k) dst[m][k] = *(const PG8_LAS bf16x8*)(lds + PG8_SA(b, h) + aoff + m * 2048 + k * 1024); } while (0)
; #define PG8_WAIT_V(n) asm volatile("s_waitcnt vmcnt(" #n ")" ::: "memory")
; #define PG8_WAIT_L(n) asm volatile("s_waitcnt lgkmcnt(" #n ")" ::: "memory")
; #define PG8_BAR __builtin_amdgcn_s_barrier()
; template <class Epi, class Sched, bool ALIGN_EPI = false, bool SP2 = false, bool I8 = false>
; __device__ __forceinline__ void gemm_phase(PG8_LAS unsigned char* lds, const Gemm g, const Sched& S, const Epi& E) {
;     ...
;         for (int t = 0; t < nt; t += 2) {
;             const bool last = (t == nt - 2);
;             const char* a1 = cA + (size_t)(t + 1) * kstep;
;             const char* a2 = last ? nA : cA + (size_t)(t + 2) * kstep; const char* b2 = last ? nB : cB + (size_t)(t + 2) * kstep;
;             const char* a3 = a2 + kstep; const char* b3 = b2 + kstep;
;             if (last && has_next) S.a_ready(nxt);
;             if constexpr (SP2) {
;             PG8_LDB(B0, 0, 0); PG8_LDB(B1, 0, 1); PG8_SCHED; PG8_LDA(At, 0, 0); PG8_STAGE(PG8_SA(1, 1), a1 + hstep, voffA);
;             PG8_WAIT_V(8); PG8_WAIT_L(0); PG8_BAR; PG8_MMA(0, 0, At, B0); PG8_MMA(0, 1, At, B1); PG8_BAR; PG8_SCHED;
;             PG8_LDA(At, 0, 1); PG8_STAGE(PG8_SB(0, 0), b2, voffB); PG8_STAGE(PG8_SB(0, 1), b2 + hstep, voffB); PG8_STAGE(PG8_SA(0, 0), a2, voffA);
;             PG8_WAIT_V(8); PG8_WAIT_L(0); PG8_BAR; PG8_MMA(1, 0, At, B0); PG8_MMA(1, 1, At, B1); PG8_BAR; PG8_SCHED;
;             PG8_LDB(B0, 1, 0); PG8_LDB(B1, 1, 1); PG8_SCHED; PG8_LDA(At, 1, 0); PG8_STAGE(PG8_SA(0, 1), a2 + hstep, voffA);
;             PG8_WAIT_V(8); PG8_WAIT_L(0); PG8_BAR; PG8_MMA(0, 0, At, B0); PG8_MMA(0, 1, At, B1); PG8_BAR; PG8_SCHED;
;             PG8_LDA(At, 1, 1); PG8_STAGE(PG8_SB(1, 0), b3, voffB); PG8_STAGE(PG8_SB(1, 1), b3 + hstep, voffB); PG8_STAGE(PG8_SA(1, 0), a3, voffA);
;             PG8_WAIT_V(8); PG8_WAIT_L(0); PG8_BAR; PG8_MMA(1, 0, At, B0); PG8_MMA(1, 1, At, B1); PG8_BAR; PG8_SCHED;
.Ldefer_1591_peel:
	s_waitcnt vmcnt(6)
	s_waitcnt lgkmcnt(0)
	s_barrier
	s_setprio 1
	s_waitcnt lgkmcnt(0)
	v_mfma_i32_16x16x64_i8 v[72:75], v[60:63], v[184:187], v[72:75]
	v_mfma_i32_16x16x64_i8 v[72:75], v[68:71], v[188:191], v[72:75]
	v_mfma_i32_16x16x64_i8 v[56:59], v[68:71], v[208:211], v[56:59]
	v_mfma_i32_16x16x64_i8 v[56:59], v[60:63], v[204:207], v[56:59]
	v_mfma_i32_16x16x64_i8 v[32:35], v[60:63], v[212:215], v[32:35]
	v_mfma_i32_16x16x64_i8 v[32:35], v[68:71], v[216:219], v[32:35]
	v_mfma_i32_16x16x64_i8 v[16:19], v[68:71], v[224:227], v[16:19]
	v_mfma_i32_16x16x64_i8 v[16:19], v[60:63], v[220:223], v[16:19]
	v_mfma_i32_16x16x64_i8 v[8:11], v[140:143], v[220:223], v[8:11]
	v_mfma_i32_16x16x64_i8 v[8:11], v[144:147], v[224:227], v[8:11]
	v_mfma_i32_16x16x64_i8 v[24:27], v[144:147], v[216:219], v[24:27]
	v_mfma_i32_16x16x64_i8 v[24:27], v[140:143], v[212:215], v[24:27]
	v_mfma_i32_16x16x64_i8 v[48:51], v[140:143], v[204:207], v[48:51]
	v_mfma_i32_16x16x64_i8 v[48:51], v[144:147], v[208:211], v[48:51]
	v_mfma_i32_16x16x64_i8 v[64:67], v[144:147], v[188:191], v[64:67]
	v_mfma_i32_16x16x64_i8 v[64:67], v[140:143], v[184:187], v[64:67]
	v_mfma_i32_16x16x64_i8 v[36:39], v[160:163], v[184:187], v[36:39]
	v_mfma_i32_16x16x64_i8 v[68:71], v[172:175], v[188:191], v[36:39]
	v_mfma_i32_16x16x64_i8 v[36:39], v[172:175], v[208:211], v[52:55]
	v_mfma_i32_16x16x64_i8 v[52:55], v[160:163], v[204:207], v[36:39]
	v_mfma_i32_16x16x64_i8 v[28:31], v[160:163], v[212:215], v[28:31]
	v_mfma_i32_16x16x64_i8 v[28:31], v[172:175], v[216:219], v[28:31]
	v_mfma_i32_16x16x64_i8 v[12:15], v[172:175], v[224:227], v[12:15]
	v_mfma_i32_16x16x64_i8 v[12:15], v[160:163], v[220:223], v[12:15]
	v_mfma_i32_16x16x64_i8 v[4:7], v[176:179], v[220:223], v[4:7]
	v_mfma_i32_16x16x64_i8 v[4:7], v[180:183], v[224:227], v[4:7]
	v_mfma_i32_16x16x64_i8 v[20:23], v[180:183], v[216:219], v[20:23]
	v_mfma_i32_16x16x64_i8 v[20:23], v[176:179], v[212:215], v[20:23]
	v_mfma_i32_16x16x64_i8 v[36:39], v[176:179], v[204:207], v[40:43]
	v_mfma_i32_16x16x64_i8 v[40:43], v[180:183], v[208:211], v[36:39]
	v_mfma_i32_16x16x64_i8 v[36:39], v[180:183], v[188:191], v[44:47]
	v_mfma_i32_16x16x64_i8 v[60:63], v[176:179], v[184:187], v[36:39]
	s_setprio 0
	s_barrier
	s_add_i32 s61, s61, 2
	s_add_u32 s40, s40, 0x100
	s_addc_u32 s41, s41, 0
	s_add_u32 s59, s59, 0x100
	s_addc_u32 s60, s60, 0
	s_cmp_gt_u32 s61, 29
	s_cbranch_scc1 .Lkloop_exit_3
.LBB0_1591:
	s_add_u32 s44, s40, 0xfff80080
	s_addc_u32 s45, s41, -1
	s_add_i32 s64, 0, 0x10000
	s_cmp_eq_u32 s61, 28
	s_cselect_b32 s49, s25, s45
	s_cselect_b32 s48, s57, s44
	s_cselect_b32 s45, s23, s60
	s_cselect_b32 s44, s58, s59
	s_add_i32 s67, 0, 0x14000
	v_add_u32_e32 v144, s64, v167
	v_add_u32_e32 v158, s67, v167
	ds_read_b128 v[36:39], v144
	ds_read_b128 v[44:47], v144 offset:1024
	ds_read_b128 v[140:143], v144 offset:2048
	ds_read_b128 v[144:147], v144 offset:3072
	ds_read_b128 v[160:163], v158
	ds_read_b128 v[172:175], v158 offset:1024
	ds_read_b128 v[176:179], v158 offset:2048
	ds_read_b128 v[180:183], v158 offset:3072
	v_lshl_add_u64 v[164:165], v[240:241], 0, s[84:85]
	s_mov_b32 m0, s54
	s_nop 0
	global_load_lds_dwordx4 v[164:165], off
	v_lshl_add_u64 v[164:165], v[242:243], 0, s[84:85]
	s_mov_b32 m0, s55
	s_nop 0
	global_load_lds_dwordx4 v[164:165], off
	v_lshl_add_u64 v[164:165], s[40:41], 0, v[154:155]
	s_add_i32 m0, s50, 0xc000
	ds_read_b128 v[184:187], v171
	ds_read_b128 v[188:191], v171 offset:1024
	ds_read_b128 v[204:207], v171 offset:2048
	ds_read_b128 v[208:211], v171 offset:3072
	ds_read_b128 v[212:215], v171 offset:4096
	ds_read_b128 v[216:219], v171 offset:5120
	ds_read_b128 v[220:223], v171 offset:6144
	ds_read_b128 v[224:227], v171 offset:7168
	global_load_lds_dwordx4 v[164:165], off
	v_lshl_add_u64 v[164:165], s[40:41], 0, v[156:157]
	s_add_i32 m0, s50, 0xe000
	s_nop 0
	global_load_lds_dwordx4 v[164:165], off
	s_waitcnt vmcnt(8)
	s_waitcnt lgkmcnt(0)
	s_barrier
	s_setprio 1
	s_waitcnt lgkmcnt(0)
	v_mfma_i32_16x16x64_i8 v[136:139], v[36:39], v[184:187], v[136:139]
	v_mfma_i32_16x16x64_i8 v[136:139], v[44:47], v[188:191], v[136:139]
	v_mfma_i32_16x16x64_i8 v[120:123], v[44:47], v[208:211], v[120:123]
	v_mfma_i32_16x16x64_i8 v[120:123], v[36:39], v[204:207], v[120:123]
	v_mfma_i32_16x16x64_i8 v[104:107], v[36:39], v[212:215], v[104:107]
	v_mfma_i32_16x16x64_i8 v[104:107], v[44:47], v[216:219], v[104:107]
	v_mfma_i32_16x16x64_i8 v[88:91], v[44:47], v[224:227], v[88:91]
	v_mfma_i32_16x16x64_i8 v[88:91], v[36:39], v[220:223], v[88:91]
	v_mfma_i32_16x16x64_i8 v[80:83], v[140:143], v[220:223], v[80:83]
	v_mfma_i32_16x16x64_i8 v[80:83], v[144:147], v[224:227], v[80:83]
	v_mfma_i32_16x16x64_i8 v[96:99], v[144:147], v[216:219], v[96:99]
	v_mfma_i32_16x16x64_i8 v[96:99], v[140:143], v[212:215], v[96:99]
	v_mfma_i32_16x16x64_i8 v[112:115], v[140:143], v[204:207], v[112:115]
	v_mfma_i32_16x16x64_i8 v[112:115], v[144:147], v[208:211], v[112:115]
	v_mfma_i32_16x16x64_i8 v[128:131], v[144:147], v[188:191], v[128:131]
	v_mfma_i32_16x16x64_i8 v[128:131], v[140:143], v[184:187], v[128:131]
	v_mfma_i32_16x16x64_i8 v[132:135], v[160:163], v[184:187], v[132:135]
	v_mfma_i32_16x16x64_i8 v[132:135], v[172:175], v[188:191], v[132:135]
	v_mfma_i32_16x16x64_i8 v[116:119], v[172:175], v[208:211], v[116:119]
	v_mfma_i32_16x16x64_i8 v[116:119], v[160:163], v[204:207], v[116:119]
	v_mfma_i32_16x16x64_i8 v[100:103], v[160:163], v[212:215], v[100:103]
	v_mfma_i32_16x16x64_i8 v[100:103], v[172:175], v[216:219], v[100:103]
	v_mfma_i32_16x16x64_i8 v[84:87], v[172:175], v[224:227], v[84:87]
	v_mfma_i32_16x16x64_i8 v[84:87], v[160:163], v[220:223], v[84:87]
	v_mfma_i32_16x16x64_i8 v[76:79], v[176:179], v[220:223], v[76:79]
	v_mfma_i32_16x16x64_i8 v[76:79], v[180:183], v[224:227], v[76:79]
	v_mfma_i32_16x16x64_i8 v[92:95], v[180:183], v[216:219], v[92:95]
	v_mfma_i32_16x16x64_i8 v[92:95], v[176:179], v[212:215], v[92:95]
	v_mfma_i32_16x16x64_i8 v[108:111], v[176:179], v[204:207], v[108:111]
	v_mfma_i32_16x16x64_i8 v[108:111], v[180:183], v[208:211], v[108:111]
	v_mfma_i32_16x16x64_i8 v[124:127], v[180:183], v[188:191], v[124:127]
	v_mfma_i32_16x16x64_i8 v[124:127], v[176:179], v[184:187], v[124:127]
	s_setprio 0
	s_barrier
; #define PG8_STAGE(bufoff, gbase, voff) do { _Pragma("unroll") for (int _i = 0; _i < 2; ++_i) \
;         __builtin_amdgcn_global_load_lds((const unsigned*)((const char*)(gbase) + (voff)[_i]), (PG8_LAS unsigned*)(lds + (bufoff) + ldsw + _i * 8192), 16, 0, 0); } while (0)
; #define PG8_LDA(dst, b, h) do { _Pragma("unroll") for (int m = 0; m < 4; ++m) _Pragma("unroll") for (int k = 0; k < 2; ++k) dst[m][k] = *(const PG8_LAS bf16x8*)(lds + PG8_SA(b, h) + aoff + m * 2048 + k * 1024); } while (0)
; #define PG8_LDB(dst, b, h) do { _Pragma("unroll") for (int n = 0; n < 2; ++n) _Pragma("unroll") for (int k = 0; k < 2; ++k) dst[n][k] = *(const PG8_LAS bf16x8*)(lds + PG8_SB(b, h) + boff + n * 2048 + k * 1024); } while (0)
; #define PG8_WAIT_V(n) asm volatile("s_waitcnt vmcnt(" #n ")" ::: "memory")
; #define PG8_WAIT_L(n) asm volatile("s_waitcnt lgkmcnt(" #n ")" ::: "memory")
; #define PG8_BAR __builtin_amdgcn_s_barrier()
; #define PG8_SCHED __builtin_amdgcn_sched_barrier(0)
; template <class Epi, class Sched, bool ALIGN_EPI = false, bool SP2 = false, bool I8 = false>
; __device__ __forceinline__ void gemm_phase(PG8_LAS unsigned char* lds, const Gemm g, const Sched& S, const Epi& E) {
;     ...
;             PG8_LDA(At, 0, 1); PG8_STAGE(PG8_SB(0, 0), b2, voffB); PG8_STAGE(PG8_SB(0, 1), b2 + hstep, voffB); PG8_STAGE(PG8_SA(0, 0), a2, voffA);
;             PG8_WAIT_V(8); PG8_WAIT_L(0); PG8_BAR; PG8_MMA(1, 0, At, B0); PG8_MMA(1, 1, At, B1); PG8_BAR; PG8_SCHED;
;             PG8_LDB(B0, 1, 0); PG8_LDB(B1, 1, 1); PG8_SCHED; PG8_LDA(At, 1, 0); PG8_STAGE(PG8_SA(0, 1), a2 + hstep, voffA);
;             PG8_WAIT_V(8); PG8_WAIT_L(0); PG8_BAR; PG8_MMA(0, 0, At, B0); PG8_MMA(0, 1, At, B1); PG8_BAR; PG8_SCHED;
	s_add_i32 s64, s64, s47
	v_lshl_add_u64 v[164:165], s[44:45], 0, v[2:3]
	s_mov_b32 m0, s64
	ds_read_b128 v[184:187], v171 offset:16384
	ds_read_b128 v[188:191], v171 offset:17408
	ds_read_b128 v[204:207], v171 offset:18432
	ds_read_b128 v[208:211], v171 offset:19456
	ds_read_b128 v[212:215], v171 offset:20480
	ds_read_b128 v[216:219], v171 offset:21504
	ds_read_b128 v[220:223], v171 offset:22528
	ds_read_b128 v[224:227], v171 offset:23552
	global_load_lds_dwordx4 v[164:165], off
	s_add_i32 m0, s64, 0x2000
	s_add_u32 s64, s44, 0x80000
	v_lshl_add_u64 v[228:229], s[44:45], 0, v[148:149]
	s_addc_u32 s65, s45, 0
	s_add_i32 s67, s67, s47
	global_load_lds_dwordx4 v[228:229], off
	v_lshl_add_u64 v[240:241], s[64:65], 0, v[2:3]
	s_mov_b32 m0, s67
	v_lshl_add_u64 v[242:243], s[48:49], 0, v[150:151]
	global_load_lds_dwordx4 v[240:241], off
	v_lshl_add_u64 v[240:241], s[64:65], 0, v[148:149]
	s_add_i32 m0, s67, 0x2000
	s_nop 0
	global_load_lds_dwordx4 v[240:241], off
	v_lshl_add_u64 v[240:241], s[48:49], 0, v[152:153]
	s_waitcnt vmcnt(6)
	s_waitcnt lgkmcnt(0)
	s_barrier
	s_setprio 1
	s_waitcnt lgkmcnt(0)
	v_mfma_i32_16x16x64_i8 v[72:75], v[36:39], v[184:187], v[72:75]
	v_mfma_i32_16x16x64_i8 v[72:75], v[44:47], v[188:191], v[72:75]
	v_mfma_i32_16x16x64_i8 v[56:59], v[44:47], v[208:211], v[56:59]
	v_mfma_i32_16x16x64_i8 v[56:59], v[36:39], v[204:207], v[56:59]
	v_mfma_i32_16x16x64_i8 v[32:35], v[36:39], v[212:215], v[32:35]
	v_mfma_i32_16x16x64_i8 v[32:35], v[44:47], v[216:219], v[32:35]
	v_mfma_i32_16x16x64_i8 v[16:19], v[44:47], v[224:227], v[16:19]
	v_mfma_i32_16x16x64_i8 v[16:19], v[36:39], v[220:223], v[16:19]
	v_mfma_i32_16x16x64_i8 v[8:11], v[140:143], v[220:223], v[8:11]
	v_mfma_i32_16x16x64_i8 v[8:11], v[144:147], v[224:227], v[8:11]
	v_mfma_i32_16x16x64_i8 v[24:27], v[144:147], v[216:219], v[24:27]
	v_mfma_i32_16x16x64_i8 v[24:27], v[140:143], v[212:215], v[24:27]
	v_mfma_i32_16x16x64_i8 v[48:51], v[140:143], v[204:207], v[48:51]
	v_mfma_i32_16x16x64_i8 v[48:51], v[144:147], v[208:211], v[48:51]
	v_mfma_i32_16x16x64_i8 v[64:67], v[144:147], v[188:191], v[64:67]
	v_mfma_i32_16x16x64_i8 v[64:67], v[140:143], v[184:187], v[64:67]
	v_mfma_i32_16x16x64_i8 v[36:39], v[160:163], v[184:187], v[68:71]
	v_mfma_i32_16x16x64_i8 v[36:39], v[172:175], v[188:191], v[36:39]
	v_mfma_i32_16x16x64_i8 v[52:55], v[172:175], v[208:211], v[52:55]
	v_mfma_i32_16x16x64_i8 v[52:55], v[160:163], v[204:207], v[52:55]
	v_mfma_i32_16x16x64_i8 v[28:31], v[160:163], v[212:215], v[28:31]
	v_mfma_i32_16x16x64_i8 v[28:31], v[172:175], v[216:219], v[28:31]
	v_mfma_i32_16x16x64_i8 v[12:15], v[172:175], v[224:227], v[12:15]
	v_mfma_i32_16x16x64_i8 v[12:15], v[160:163], v[220:223], v[12:15]
	v_mfma_i32_16x16x64_i8 v[4:7], v[176:179], v[220:223], v[4:7]
	v_mfma_i32_16x16x64_i8 v[4:7], v[180:183], v[224:227], v[4:7]
	v_mfma_i32_16x16x64_i8 v[20:23], v[180:183], v[216:219], v[20:23]
	v_mfma_i32_16x16x64_i8 v[20:23], v[176:179], v[212:215], v[20:23]
	v_mfma_i32_16x16x64_i8 v[40:43], v[176:179], v[204:207], v[40:43]
	v_mfma_i32_16x16x64_i8 v[40:43], v[180:183], v[208:211], v[40:43]
	v_mfma_i32_16x16x64_i8 v[44:47], v[180:183], v[188:191], v[60:63]
	v_mfma_i32_16x16x64_i8 v[44:47], v[176:179], v[184:187], v[44:47]
	s_setprio 0
	s_barrier
	s_mov_b32 m0, s50
	s_nop 0
	global_load_lds_dwordx4 v[240:241], off
	s_mov_b32 m0, s51
	s_nop 0
	global_load_lds_dwordx4 v[242:243], off
	s_add_i32 s64, 0, 0x18000
	s_add_i32 s65, 0, 0x1c000
	v_add_u32_e32 v144, s64, v167
	v_add_u32_e32 v158, s65, v167
	ds_read_b128 v[60:63], v144
	ds_read_b128 v[68:71], v144 offset:1024
	ds_read_b128 v[140:143], v144 offset:2048
	ds_read_b128 v[144:147], v144 offset:3072
	ds_read_b128 v[160:163], v158
	ds_read_b128 v[172:175], v158 offset:1024
	ds_read_b128 v[176:179], v158 offset:2048
	ds_read_b128 v[180:183], v158 offset:3072
	s_add_u32 s48, s48, 0x80000
	s_addc_u32 s49, s49, 0
	s_mov_b32 m0, s52
	v_lshl_add_u64 v[244:245], s[48:49], 0, v[152:153]
	ds_read_b128 v[184:187], v171 offset:32768
	ds_read_b128 v[188:191], v171 offset:33792
	ds_read_b128 v[204:207], v171 offset:34816
	ds_read_b128 v[208:211], v171 offset:35840
	ds_read_b128 v[212:215], v171 offset:36864
	ds_read_b128 v[216:219], v171 offset:37888
	ds_read_b128 v[220:223], v171 offset:38912
	ds_read_b128 v[224:227], v171 offset:39936
	global_load_lds_dwordx4 v[244:245], off
	v_lshl_add_u64 v[244:245], s[48:49], 0, v[150:151]
	s_mov_b32 m0, s53
	s_nop 0
	global_load_lds_dwordx4 v[244:245], off
	s_waitcnt vmcnt(8)
	s_waitcnt lgkmcnt(0)
	s_barrier
; #define PG8_STAGE(bufoff, gbase, voff) do { _Pragma("unroll") for (int _i = 0; _i < 2; ++_i) \
;         __builtin_amdgcn_global_load_lds((const unsigned*)((const char*)(gbase) + (voff)[_i]), (PG8_LAS unsigned*)(lds + (bufoff) + ldsw + _i * 8192), 16, 0, 0); } while (0)
; #define PG8_LDA(dst, b, h) do { _Pragma("unroll") for (int m = 0; m < 4; ++m) _Pragma("unroll") for (int k = 0; k < 2; ++k) dst[m][k] = *(const PG8_LAS bf16x8*)(lds + PG8_SA(b, h) + aoff + m * 2048 + k * 1024); } while (0)
; #define PG8_WAIT_V(n) asm volatile("s_waitcnt vmcnt(" #n ")" ::: "memory")
; #define PG8_WAIT_L(n) asm volatile("s_waitcnt lgkmcnt(" #n ")" ::: "memory")
; #define PG8_BAR __builtin_amdgcn_s_barrier()
; #define PG8_SCHED __builtin_amdgcn_sched_barrier(0)
; template <class Epi, class Sched, bool ALIGN_EPI = false, bool SP2 = false, bool I8 = false>
; __device__ __forceinline__ void gemm_phase(PG8_LAS unsigned char* lds, const Gemm g, const Sched& S, const Epi& E) {
;     ...
;             PG8_WAIT_V(8); PG8_WAIT_L(0); PG8_BAR; PG8_MMA(0, 0, At, B0); PG8_MMA(0, 1, At, B1); PG8_BAR; PG8_SCHED;
;             PG8_LDA(At, 1, 1); PG8_STAGE(PG8_SB(1, 0), b3, voffB); PG8_STAGE(PG8_SB(1, 1), b3 + hstep, voffB); PG8_STAGE(PG8_SA(1, 0), a3, voffA);
;             PG8_WAIT_V(8); PG8_WAIT_L(0); PG8_BAR; PG8_MMA(1, 0, At, B0); PG8_MMA(1, 1, At, B1); PG8_BAR; PG8_SCHED;
	s_setprio 1
	s_waitcnt lgkmcnt(0)
	v_mfma_i32_16x16x64_i8 v[136:139], v[60:63], v[184:187], v[136:139]
	v_mfma_i32_16x16x64_i8 v[136:139], v[68:71], v[188:191], v[136:139]
	v_mfma_i32_16x16x64_i8 v[120:123], v[68:71], v[208:211], v[120:123]
	v_mfma_i32_16x16x64_i8 v[120:123], v[60:63], v[204:207], v[120:123]
	v_mfma_i32_16x16x64_i8 v[104:107], v[60:63], v[212:215], v[104:107]
	v_mfma_i32_16x16x64_i8 v[104:107], v[68:71], v[216:219], v[104:107]
	v_mfma_i32_16x16x64_i8 v[88:91], v[68:71], v[224:227], v[88:91]
	v_mfma_i32_16x16x64_i8 v[88:91], v[60:63], v[220:223], v[88:91]
	v_mfma_i32_16x16x64_i8 v[80:83], v[140:143], v[220:223], v[80:83]
	v_mfma_i32_16x16x64_i8 v[80:83], v[144:147], v[224:227], v[80:83]
	v_mfma_i32_16x16x64_i8 v[96:99], v[144:147], v[216:219], v[96:99]
	v_mfma_i32_16x16x64_i8 v[96:99], v[140:143], v[212:215], v[96:99]
	v_mfma_i32_16x16x64_i8 v[112:115], v[140:143], v[204:207], v[112:115]
	v_mfma_i32_16x16x64_i8 v[112:115], v[144:147], v[208:211], v[112:115]
	v_mfma_i32_16x16x64_i8 v[128:131], v[144:147], v[188:191], v[128:131]
	v_mfma_i32_16x16x64_i8 v[128:131], v[140:143], v[184:187], v[128:131]
	v_mfma_i32_16x16x64_i8 v[132:135], v[160:163], v[184:187], v[132:135]
	v_mfma_i32_16x16x64_i8 v[132:135], v[172:175], v[188:191], v[132:135]
	v_mfma_i32_16x16x64_i8 v[116:119], v[172:175], v[208:211], v[116:119]
	v_mfma_i32_16x16x64_i8 v[116:119], v[160:163], v[204:207], v[116:119]
	v_mfma_i32_16x16x64_i8 v[100:103], v[160:163], v[212:215], v[100:103]
	v_mfma_i32_16x16x64_i8 v[100:103], v[172:175], v[216:219], v[100:103]
	v_mfma_i32_16x16x64_i8 v[84:87], v[172:175], v[224:227], v[84:87]
	v_mfma_i32_16x16x64_i8 v[84:87], v[160:163], v[220:223], v[84:87]
	v_mfma_i32_16x16x64_i8 v[76:79], v[176:179], v[220:223], v[76:79]
	v_mfma_i32_16x16x64_i8 v[76:79], v[180:183], v[224:227], v[76:79]
	v_mfma_i32_16x16x64_i8 v[92:95], v[180:183], v[216:219], v[92:95]
	v_mfma_i32_16x16x64_i8 v[92:95], v[176:179], v[212:215], v[92:95]
	v_mfma_i32_16x16x64_i8 v[108:111], v[176:179], v[204:207], v[108:111]
	v_mfma_i32_16x16x64_i8 v[108:111], v[180:183], v[208:211], v[108:111]
	v_mfma_i32_16x16x64_i8 v[124:127], v[180:183], v[188:191], v[124:127]
	v_mfma_i32_16x16x64_i8 v[124:127], v[176:179], v[184:187], v[124:127]
	s_setprio 0
	s_barrier
	s_add_i32 s48, s64, s47
	v_lshl_add_u64 v[164:165], v[164:165], 0, s[84:85]
	s_mov_b32 m0, s48
	ds_read_b128 v[184:187], v171 offset:49152
	ds_read_b128 v[188:191], v171 offset:50176
	ds_read_b128 v[204:207], v171 offset:51200
	ds_read_b128 v[208:211], v171 offset:52224
	ds_read_b128 v[212:215], v171 offset:53248
	ds_read_b128 v[216:219], v171 offset:54272
	ds_read_b128 v[220:223], v171 offset:55296
	ds_read_b128 v[224:227], v171 offset:56320
	global_load_lds_dwordx4 v[164:165], off
	s_add_i32 m0, s48, 0x2000
	s_add_u32 s44, s44, 0x80080
	v_lshl_add_u64 v[164:165], v[228:229], 0, s[84:85]
	s_addc_u32 s45, s45, 0
	s_add_i32 s48, s65, s47
	global_load_lds_dwordx4 v[164:165], off
	v_lshl_add_u64 v[164:165], s[44:45], 0, v[2:3]
	s_mov_b32 m0, s48
	s_nop 0
	global_load_lds_dwordx4 v[164:165], off
	v_lshl_add_u64 v[164:165], s[44:45], 0, v[148:149]
	s_add_i32 m0, s48, 0x2000
	s_nop 0
	global_load_lds_dwordx4 v[164:165], off
	s_cmp_eq_u32 s61, 28
	s_cbranch_scc0 .Ldefer_1591_body
	v_lshl_add_u64 v[164:165], v[240:241], 0, s[84:85]
	s_mov_b32 m0, s54
	s_nop 0
	global_load_lds_dwordx4 v[164:165], off
	v_lshl_add_u64 v[164:165], v[242:243], 0, s[84:85]
	s_mov_b32 m0, s55
	s_nop 0
	global_load_lds_dwordx4 v[164:165], off
.Ldefer_1591_body:
	s_waitcnt vmcnt(6)
	s_waitcnt lgkmcnt(0)
	s_barrier
	s_setprio 1
	s_waitcnt lgkmcnt(0)
	v_mfma_i32_16x16x64_i8 v[72:75], v[60:63], v[184:187], v[72:75]
	v_mfma_i32_16x16x64_i8 v[72:75], v[68:71], v[188:191], v[72:75]
	v_mfma_i32_16x16x64_i8 v[56:59], v[68:71], v[208:211], v[56:59]
	v_mfma_i32_16x16x64_i8 v[56:59], v[60:63], v[204:207], v[56:59]
	v_mfma_i32_16x16x64_i8 v[32:35], v[60:63], v[212:215], v[32:35]
	v_mfma_i32_16x16x64_i8 v[32:35], v[68:71], v[216:219], v[32:35]
	v_mfma_i32_16x16x64_i8 v[16:19], v[68:71], v[224:227], v[16:19]
	v_mfma_i32_16x16x64_i8 v[16:19], v[60:63], v[220:223], v[16:19]
	v_mfma_i32_16x16x64_i8 v[8:11], v[140:143], v[220:223], v[8:11]
	v_mfma_i32_16x16x64_i8 v[8:11], v[144:147], v[224:227], v[8:11]
	v_mfma_i32_16x16x64_i8 v[24:27], v[144:147], v[216:219], v[24:27]
	v_mfma_i32_16x16x64_i8 v[24:27], v[140:143], v[212:215], v[24:27]
	v_mfma_i32_16x16x64_i8 v[48:51], v[140:143], v[204:207], v[48:51]
	v_mfma_i32_16x16x64_i8 v[48:51], v[144:147], v[208:211], v[48:51]
	v_mfma_i32_16x16x64_i8 v[64:67], v[144:147], v[188:191], v[64:67]
	v_mfma_i32_16x16x64_i8 v[64:67], v[140:143], v[184:187], v[64:67]
	v_mfma_i32_16x16x64_i8 v[36:39], v[160:163], v[184:187], v[36:39]
	v_mfma_i32_16x16x64_i8 v[68:71], v[172:175], v[188:191], v[36:39]
	v_mfma_i32_16x16x64_i8 v[36:39], v[172:175], v[208:211], v[52:55]
	v_mfma_i32_16x16x64_i8 v[52:55], v[160:163], v[204:207], v[36:39]
	v_mfma_i32_16x16x64_i8 v[28:31], v[160:163], v[212:215], v[28:31]
	v_mfma_i32_16x16x64_i8 v[28:31], v[172:175], v[216:219], v[28:31]
	v_mfma_i32_16x16x64_i8 v[12:15], v[172:175], v[224:227], v[12:15]
	v_mfma_i32_16x16x64_i8 v[12:15], v[160:163], v[220:223], v[12:15]
	v_mfma_i32_16x16x64_i8 v[4:7], v[176:179], v[220:223], v[4:7]
	v_mfma_i32_16x16x64_i8 v[4:7], v[180:183], v[224:227], v[4:7]
	v_mfma_i32_16x16x64_i8 v[20:23], v[180:183], v[216:219], v[20:23]
	v_mfma_i32_16x16x64_i8 v[20:23], v[176:179], v[212:215], v[20:23]
	v_mfma_i32_16x16x64_i8 v[36:39], v[176:179], v[204:207], v[40:43]
	v_mfma_i32_16x16x64_i8 v[40:43], v[180:183], v[208:211], v[36:39]
	v_mfma_i32_16x16x64_i8 v[36:39], v[180:183], v[188:191], v[44:47]
	v_mfma_i32_16x16x64_i8 v[60:63], v[176:179], v[184:187], v[36:39]
	s_setprio 0
	s_barrier
	s_add_i32 s61, s61, 2
	s_add_u32 s40, s40, 0x100
	s_addc_u32 s41, s41, 0
	s_add_u32 s59, s59, 0x100
	s_addc_u32 s60, s60, 0
	s_cmp_gt_u32 s61, 29
	s_cbranch_scc0 .LBB0_1591

; #define PG8_STAGE(bufoff, gbase, voff) do { _Pragma("unroll") for (int _i = 0; _i < 2; ++_i) \
;         __builtin_amdgcn_global_load_lds((const unsigned*)((const char*)(gbase) + (voff)[_i]), (PG8_LAS unsigned*)(lds + (bufoff) + ldsw + _i * 8192), 16, 0, 0); } while (0)
; #define PG8_LDA(dst, b, h) do { _Pragma("unroll") for (int m = 0; m < 4; ++m) _Pragma("unroll") for (int k = 0; k < 2; ++k) dst[m][k] = *(const PG8_LAS bf16x8*)(lds + PG8_SA(b, h) + aoff + m * 2048 + k * 1024); } while (0)
; #define PG8_LDB(dst, b, h) do { _Pragma("unroll") for (int n = 0; n < 2; ++n) _Pragma("unroll") for (int k = 0; k < 2; ++k) dst[n][k] = *(const PG8_LAS bf16x8*)(lds + PG8_SB(b, h) + boff + n * 2048 + k * 1024); } while (0)
; #define PG8_WAIT_V(n) asm volatile("s_waitcnt vmcnt(" #n ")" ::: "memory")
; #define PG8_WAIT_L(n) asm volatile("s_waitcnt lgkmcnt(" #n ")" ::: "memory")
; #define PG8_BAR __builtin_amdgcn_s_barrier()
; #define PG8_SCHED __builtin_amdgcn_sched_barrier(0)
; template <class Epi, class Sched, bool ALIGN_EPI = false, bool SP2 = false, bool I8 = false>
; __device__ __forceinline__ void gemm_phase(PG8_LAS unsigned char* lds, const Gemm g, const Sched& S, const Epi& E) {
;     ...
;         const bool has_next = S.next(ui + 1, nxt);
;         const char* nA = has_next ? (const char*)g.A + (size_t)nxt.pm * tstep : cA; const char* nB = has_next ? (const char*)g.Bt + (size_t)nxt.pn * tstep : cB;
;         for (int t = 0; t < nt; t += 2) {
;             const bool last = (t == nt - 2);
;             const char* a1 = cA + (size_t)(t + 1) * kstep;
;             const char* a2 = last ? nA : cA + (size_t)(t + 2) * kstep; const char* b2 = last ? nB : cB + (size_t)(t + 2) * kstep;
;             const char* a3 = a2 + kstep; const char* b3 = b2 + kstep;
;             if (last && has_next) S.a_ready(nxt);
;             if constexpr (SP2) {
;             PG8_LDB(B0, 0, 0); PG8_LDB(B1, 0, 1); PG8_SCHED; PG8_LDA(At, 0, 0); PG8_STAGE(PG8_SA(1, 1), a1 + hstep, voffA);
;             PG8_WAIT_V(8); PG8_WAIT_L(0); PG8_BAR; PG8_MMA(0, 0, At, B0); PG8_MMA(0, 1, At, B1); PG8_BAR; PG8_SCHED;
;             PG8_LDA(At, 0, 1); PG8_STAGE(PG8_SB(0, 0), b2, voffB); PG8_STAGE(PG8_SB(0, 1), b2 + hstep, voffB); PG8_STAGE(PG8_SA(0, 0), a2, voffA);
;             PG8_WAIT_V(8); PG8_WAIT_L(0); PG8_BAR; PG8_MMA(1, 0, At, B0); PG8_MMA(1, 1, At, B1); PG8_BAR; PG8_SCHED;
.LBB0_1699:
	s_add_u32 s53, s24, 0x100
	s_addc_u32 s54, s25, 0
	s_mov_b32 s55, -2
	s_add_u32 s24, s22, 0x100
	s_addc_u32 s25, s23, 0
	s_add_i32 s56, 0, 0x10000
	s_cmpk_eq_i32 s55, 0xa8
	s_cselect_b32 s37, s13, s25
	s_cselect_b32 s36, s12, s24
	s_cselect_b32 s27, s21, s54
	s_cselect_b32 s26, s20, s53
	s_add_i32 s57, 0, 0x14000
	v_add_u32_e32 v144, s56, v240
	v_add_u32_e32 v160, s57, v240
	ds_read_b128 v[124:127], v144
	ds_read_b128 v[128:131], v144 offset:1024
	ds_read_b128 v[132:135], v144 offset:2048
	ds_read_b128 v[144:147], v144 offset:3072
	ds_read_b128 v[148:151], v160
	ds_read_b128 v[152:155], v160 offset:1024
	ds_read_b128 v[156:159], v160 offset:2048
	ds_read_b128 v[160:163], v160 offset:3072
	v_lshl_add_u64 v[218:219], s[22:23], 0, v[210:211]
	s_add_i32 m0, s42, 0xc000
	ds_read_b128 v[164:167], v242
	ds_read_b128 v[168:171], v242 offset:1024
	ds_read_b128 v[172:175], v242 offset:2048
	ds_read_b128 v[176:179], v242 offset:3072
	ds_read_b128 v[180:183], v242 offset:4096
	ds_read_b128 v[184:187], v242 offset:5120
	ds_read_b128 v[188:191], v242 offset:6144
	ds_read_b128 v[214:217], v242 offset:7168
	global_load_lds_dwordx4 v[218:219], off
	v_lshl_add_u64 v[218:219], s[22:23], 0, v[212:213]
	s_add_i32 m0, s42, 0xe000
	s_nop 0
	global_load_lds_dwordx4 v[218:219], off
	s_waitcnt vmcnt(8)
	s_waitcnt lgkmcnt(0)
	s_barrier
	s_setprio 1
	s_waitcnt lgkmcnt(0)
	v_mfma_f32_16x16x32_bf16 v[140:143], v[124:127], v[164:167], 0
	v_mfma_f32_16x16x32_bf16 v[140:143], v[128:131], v[168:171], v[140:143]
	v_mfma_f32_16x16x32_bf16 v[112:115], v[128:131], v[176:179], 0
	v_mfma_f32_16x16x32_bf16 v[112:115], v[124:127], v[172:175], v[112:115]
	v_mfma_f32_16x16x32_bf16 v[96:99], v[124:127], v[180:183], 0
	v_mfma_f32_16x16x32_bf16 v[96:99], v[128:131], v[184:187], v[96:99]
	v_mfma_f32_16x16x32_bf16 v[80:83], v[128:131], v[214:217], 0
	v_mfma_f32_16x16x32_bf16 v[80:83], v[124:127], v[188:191], v[80:83]
	v_mfma_f32_16x16x32_bf16 v[76:79], v[132:135], v[188:191], 0
	v_mfma_f32_16x16x32_bf16 v[76:79], v[144:147], v[214:217], v[76:79]
	v_mfma_f32_16x16x32_bf16 v[92:95], v[144:147], v[184:187], 0
	v_mfma_f32_16x16x32_bf16 v[92:95], v[132:135], v[180:183], v[92:95]
	v_mfma_f32_16x16x32_bf16 v[108:111], v[132:135], v[172:175], 0
	v_mfma_f32_16x16x32_bf16 v[108:111], v[144:147], v[176:179], v[108:111]
	v_mfma_f32_16x16x32_bf16 v[136:139], v[144:147], v[168:171], 0
	v_mfma_f32_16x16x32_bf16 v[136:139], v[132:135], v[164:167], v[136:139]
	v_mfma_f32_16x16x32_bf16 v[120:123], v[148:151], v[164:167], 0
	v_mfma_f32_16x16x32_bf16 v[120:123], v[152:155], v[168:171], v[120:123]
	v_mfma_f32_16x16x32_bf16 v[104:107], v[152:155], v[176:179], 0
	v_mfma_f32_16x16x32_bf16 v[104:107], v[148:151], v[172:175], v[104:107]
	v_mfma_f32_16x16x32_bf16 v[88:91], v[148:151], v[180:183], 0
	v_mfma_f32_16x16x32_bf16 v[88:91], v[152:155], v[184:187], v[88:91]
	v_mfma_f32_16x16x32_bf16 v[72:75], v[152:155], v[214:217], 0
	v_mfma_f32_16x16x32_bf16 v[72:75], v[148:151], v[188:191], v[72:75]
	v_mfma_f32_16x16x32_bf16 v[68:71], v[156:159], v[188:191], 0
	v_mfma_f32_16x16x32_bf16 v[68:71], v[160:163], v[214:217], v[68:71]
	v_mfma_f32_16x16x32_bf16 v[84:87], v[160:163], v[184:187], 0
	v_mfma_f32_16x16x32_bf16 v[84:87], v[156:159], v[180:183], v[84:87]
	v_mfma_f32_16x16x32_bf16 v[100:103], v[156:159], v[172:175], 0
	v_mfma_f32_16x16x32_bf16 v[100:103], v[160:163], v[176:179], v[100:103]
	v_mfma_f32_16x16x32_bf16 v[116:119], v[160:163], v[168:171], 0
	v_mfma_f32_16x16x32_bf16 v[116:119], v[156:159], v[164:167], v[116:119]
	s_setprio 0
	s_barrier
	s_add_i32 s22, s56, s41
	v_lshl_add_u64 v[218:219], s[26:27], 0, v[2:3]
	s_mov_b32 m0, s22
	ds_read_b128 v[164:167], v242 offset:16384
	ds_read_b128 v[168:171], v242 offset:17408
	ds_read_b128 v[172:175], v242 offset:18432
	ds_read_b128 v[176:179], v242 offset:19456
	ds_read_b128 v[180:183], v242 offset:20480
	ds_read_b128 v[184:187], v242 offset:21504
	ds_read_b128 v[188:191], v242 offset:22528
	ds_read_b128 v[214:217], v242 offset:23552
	global_load_lds_dwordx4 v[218:219], off
	s_add_i32 m0, s22, 0x2000
	s_add_u32 s22, s26, 0x2b0000
	v_lshl_add_u64 v[220:221], s[26:27], 0, v[204:205]
	s_addc_u32 s23, s27, 0
	s_add_i32 s56, s57, s41
	global_load_lds_dwordx4 v[220:221], off
	v_lshl_add_u64 v[222:223], s[22:23], 0, v[2:3]
	s_mov_b32 m0, s56
	v_lshl_add_u64 v[224:225], s[36:37], 0, v[206:207]
	global_load_lds_dwordx4 v[222:223], off
	v_lshl_add_u64 v[222:223], s[22:23], 0, v[204:205]
	s_add_i32 m0, s56, 0x2000
	s_nop 0
	global_load_lds_dwordx4 v[222:223], off
	v_lshl_add_u64 v[222:223], s[36:37], 0, v[208:209]
	s_waitcnt vmcnt(6)
	s_waitcnt lgkmcnt(0)
	s_barrier
; #define PG8_STAGE(bufoff, gbase, voff) do { _Pragma("unroll") for (int _i = 0; _i < 2; ++_i) \
;         __builtin_amdgcn_global_load_lds((const unsigned*)((const char*)(gbase) + (voff)[_i]), (PG8_LAS unsigned*)(lds + (bufoff) + ldsw + _i * 8192), 16, 0, 0); } while (0)
; #define PG8_LDA(dst, b, h) do { _Pragma("unroll") for (int m = 0; m < 4; ++m) _Pragma("unroll") for (int k = 0; k < 2; ++k) dst[m][k] = *(const PG8_LAS bf16x8*)(lds + PG8_SA(b, h) + aoff + m * 2048 + k * 1024); } while (0)
; #define PG8_LDB(dst, b, h) do { _Pragma("unroll") for (int n = 0; n < 2; ++n) _Pragma("unroll") for (int k = 0; k < 2; ++k) dst[n][k] = *(const PG8_LAS bf16x8*)(lds + PG8_SB(b, h) + boff + n * 2048 + k * 1024); } while (0)
; #define PG8_WAIT_V(n) asm volatile("s_waitcnt vmcnt(" #n ")" ::: "memory")
; #define PG8_WAIT_L(n) asm volatile("s_waitcnt lgkmcnt(" #n ")" ::: "memory")
; #define PG8_BAR __builtin_amdgcn_s_barrier()
; #define PG8_SCHED __builtin_amdgcn_sched_barrier(0)
; template <class Epi, class Sched, bool ALIGN_EPI = false, bool SP2 = false, bool I8 = false>
; __device__ __forceinline__ void gemm_phase(PG8_LAS unsigned char* lds, const Gemm g, const Sched& S, const Epi& E) {
;     ...
;             PG8_WAIT_V(8); PG8_WAIT_L(0); PG8_BAR; PG8_MMA(0, 0, At, B0); PG8_MMA(0, 1, At, B1); PG8_BAR; PG8_SCHED;
;             PG8_LDA(At, 0, 1); PG8_STAGE(PG8_SB(0, 0), b2, voffB); PG8_STAGE(PG8_SB(0, 1), b2 + hstep, voffB); PG8_STAGE(PG8_SA(0, 0), a2, voffA);
;             PG8_WAIT_V(8); PG8_WAIT_L(0); PG8_BAR; PG8_MMA(1, 0, At, B0); PG8_MMA(1, 1, At, B1); PG8_BAR; PG8_SCHED;
;             PG8_LDB(B0, 1, 0); PG8_LDB(B1, 1, 1); PG8_SCHED; PG8_LDA(At, 1, 0); PG8_STAGE(PG8_SA(0, 1), a2 + hstep, voffA);
;             PG8_WAIT_V(8); PG8_WAIT_L(0); PG8_BAR; PG8_MMA(0, 0, At, B0); PG8_MMA(0, 1, At, B1); PG8_BAR; PG8_SCHED;
;             PG8_LDA(At, 1, 1); PG8_STAGE(PG8_SB(1, 0), b3, voffB); PG8_STAGE(PG8_SB(1, 1), b3 + hstep, voffB); PG8_STAGE(PG8_SA(1, 0), a3, voffA);
;             PG8_WAIT_V(8); PG8_WAIT_L(0); PG8_BAR; PG8_MMA(1, 0, At, B0); PG8_MMA(1, 1, At, B1); PG8_BAR; PG8_SCHED;
	s_setprio 1
	s_waitcnt lgkmcnt(0)
	v_mfma_f32_16x16x32_bf16 v[64:67], v[124:127], v[164:167], 0
	v_mfma_f32_16x16x32_bf16 v[64:67], v[128:131], v[168:171], v[64:67]
	v_mfma_f32_16x16x32_bf16 v[48:51], v[128:131], v[176:179], 0
	v_mfma_f32_16x16x32_bf16 v[48:51], v[124:127], v[172:175], v[48:51]
	v_mfma_f32_16x16x32_bf16 v[32:35], v[124:127], v[180:183], 0
	v_mfma_f32_16x16x32_bf16 v[32:35], v[128:131], v[184:187], v[32:35]
	v_mfma_f32_16x16x32_bf16 v[16:19], v[128:131], v[214:217], 0
	v_mfma_f32_16x16x32_bf16 v[16:19], v[124:127], v[188:191], v[16:19]
	v_mfma_f32_16x16x32_bf16 v[12:15], v[132:135], v[188:191], 0
	v_mfma_f32_16x16x32_bf16 v[12:15], v[144:147], v[214:217], v[12:15]
	v_mfma_f32_16x16x32_bf16 v[28:31], v[144:147], v[184:187], 0
	v_mfma_f32_16x16x32_bf16 v[28:31], v[132:135], v[180:183], v[28:31]
	v_mfma_f32_16x16x32_bf16 v[44:47], v[132:135], v[172:175], 0
	v_mfma_f32_16x16x32_bf16 v[44:47], v[144:147], v[176:179], v[44:47]
	v_mfma_f32_16x16x32_bf16 v[60:63], v[144:147], v[168:171], 0
	v_mfma_f32_16x16x32_bf16 v[60:63], v[132:135], v[164:167], v[60:63]
	v_mfma_f32_16x16x32_bf16 v[56:59], v[148:151], v[164:167], 0
	v_mfma_f32_16x16x32_bf16 v[56:59], v[152:155], v[168:171], v[56:59]
	v_mfma_f32_16x16x32_bf16 v[40:43], v[152:155], v[176:179], 0
	v_mfma_f32_16x16x32_bf16 v[40:43], v[148:151], v[172:175], v[40:43]
	v_mfma_f32_16x16x32_bf16 v[24:27], v[148:151], v[180:183], 0
	v_mfma_f32_16x16x32_bf16 v[24:27], v[152:155], v[184:187], v[24:27]
	v_mfma_f32_16x16x32_bf16 v[8:11], v[152:155], v[214:217], 0
	v_mfma_f32_16x16x32_bf16 v[8:11], v[148:151], v[188:191], v[8:11]
	v_mfma_f32_16x16x32_bf16 v[4:7], v[156:159], v[188:191], 0
	v_mfma_f32_16x16x32_bf16 v[4:7], v[160:163], v[214:217], v[4:7]
	v_mfma_f32_16x16x32_bf16 v[20:23], v[160:163], v[184:187], 0
	v_mfma_f32_16x16x32_bf16 v[20:23], v[156:159], v[180:183], v[20:23]
	v_mfma_f32_16x16x32_bf16 v[36:39], v[156:159], v[172:175], 0
	v_mfma_f32_16x16x32_bf16 v[36:39], v[160:163], v[176:179], v[36:39]
	v_mfma_f32_16x16x32_bf16 v[52:55], v[160:163], v[168:171], 0
	v_mfma_f32_16x16x32_bf16 v[52:55], v[156:159], v[164:167], v[52:55]
	s_setprio 0
	s_barrier
	s_mov_b32 m0, s42
	s_nop 0
	global_load_lds_dwordx4 v[222:223], off
	s_mov_b32 m0, s43
	s_nop 0
	global_load_lds_dwordx4 v[224:225], off
	s_add_i32 s56, 0, 0x18000
	s_add_i32 s57, 0, 0x1c000
	v_add_u32_e32 v144, s56, v240
	v_add_u32_e32 v160, s57, v240
	ds_read_b128 v[124:127], v144
	ds_read_b128 v[128:131], v144 offset:1024
	ds_read_b128 v[132:135], v144 offset:2048
	ds_read_b128 v[144:147], v144 offset:3072
	ds_read_b128 v[148:151], v160
	ds_read_b128 v[152:155], v160 offset:1024
	ds_read_b128 v[156:159], v160 offset:2048
	ds_read_b128 v[160:163], v160 offset:3072
	s_add_u32 s22, s36, 0x2b0000
	s_addc_u32 s23, s37, 0
	s_mov_b32 m0, s44
	v_lshl_add_u64 v[226:227], s[22:23], 0, v[208:209]
	ds_read_b128 v[164:167], v242 offset:32768
	ds_read_b128 v[168:171], v242 offset:33792
	ds_read_b128 v[172:175], v242 offset:34816
	ds_read_b128 v[176:179], v242 offset:35840
	ds_read_b128 v[180:183], v242 offset:36864
	ds_read_b128 v[184:187], v242 offset:37888
	ds_read_b128 v[188:191], v242 offset:38912
	ds_read_b128 v[214:217], v242 offset:39936
	global_load_lds_dwordx4 v[226:227], off
	v_lshl_add_u64 v[226:227], s[22:23], 0, v[206:207]
	s_mov_b32 m0, s45
	s_nop 0
	global_load_lds_dwordx4 v[226:227], off
	s_waitcnt vmcnt(8)
	s_waitcnt lgkmcnt(0)
	s_barrier
	s_setprio 1
	s_waitcnt lgkmcnt(0)
	v_mfma_f32_16x16x32_bf16 v[140:143], v[124:127], v[164:167], v[140:143]
	v_mfma_f32_16x16x32_bf16 v[140:143], v[128:131], v[168:171], v[140:143]
	v_mfma_f32_16x16x32_bf16 v[112:115], v[128:131], v[176:179], v[112:115]
	v_mfma_f32_16x16x32_bf16 v[112:115], v[124:127], v[172:175], v[112:115]
	v_mfma_f32_16x16x32_bf16 v[96:99], v[124:127], v[180:183], v[96:99]
	v_mfma_f32_16x16x32_bf16 v[96:99], v[128:131], v[184:187], v[96:99]
	v_mfma_f32_16x16x32_bf16 v[80:83], v[128:131], v[214:217], v[80:83]
	v_mfma_f32_16x16x32_bf16 v[80:83], v[124:127], v[188:191], v[80:83]
	v_mfma_f32_16x16x32_bf16 v[76:79], v[132:135], v[188:191], v[76:79]
	v_mfma_f32_16x16x32_bf16 v[76:79], v[144:147], v[214:217], v[76:79]
	v_mfma_f32_16x16x32_bf16 v[92:95], v[144:147], v[184:187], v[92:95]
	v_mfma_f32_16x16x32_bf16 v[92:95], v[132:135], v[180:183], v[92:95]
	v_mfma_f32_16x16x32_bf16 v[108:111], v[132:135], v[172:175], v[108:111]
	v_mfma_f32_16x16x32_bf16 v[108:111], v[144:147], v[176:179], v[108:111]
	v_mfma_f32_16x16x32_bf16 v[136:139], v[144:147], v[168:171], v[136:139]
	v_mfma_f32_16x16x32_bf16 v[136:139], v[132:135], v[164:167], v[136:139]
	v_mfma_f32_16x16x32_bf16 v[120:123], v[148:151], v[164:167], v[120:123]
	v_mfma_f32_16x16x32_bf16 v[120:123], v[152:155], v[168:171], v[120:123]
	v_mfma_f32_16x16x32_bf16 v[104:107], v[152:155], v[176:179], v[104:107]
	v_mfma_f32_16x16x32_bf16 v[104:107], v[148:151], v[172:175], v[104:107]
	v_mfma_f32_16x16x32_bf16 v[88:91], v[148:151], v[180:183], v[88:91]
	v_mfma_f32_16x16x32_bf16 v[88:91], v[152:155], v[184:187], v[88:91]
	v_mfma_f32_16x16x32_bf16 v[72:75], v[152:155], v[214:217], v[72:75]
	v_mfma_f32_16x16x32_bf16 v[72:75], v[148:151], v[188:191], v[72:75]
	v_mfma_f32_16x16x32_bf16 v[68:71], v[156:159], v[188:191], v[68:71]
	v_mfma_f32_16x16x32_bf16 v[68:71], v[160:163], v[214:217], v[68:71]
	v_mfma_f32_16x16x32_bf16 v[84:87], v[160:163], v[184:187], v[84:87]
	v_mfma_f32_16x16x32_bf16 v[84:87], v[156:159], v[180:183], v[84:87]
	v_mfma_f32_16x16x32_bf16 v[100:103], v[156:159], v[172:175], v[100:103]
	v_mfma_f32_16x16x32_bf16 v[100:103], v[160:163], v[176:179], v[100:103]
	v_mfma_f32_16x16x32_bf16 v[116:119], v[160:163], v[168:171], v[116:119]
	v_mfma_f32_16x16x32_bf16 v[116:119], v[156:159], v[164:167], v[116:119]
	s_setprio 0
	s_barrier
	s_add_i32 s22, s56, s41
	v_lshl_add_u64 v[218:219], v[218:219], 0, s[84:85]
	s_mov_b32 m0, s22
	ds_read_b128 v[164:167], v242 offset:49152
	ds_read_b128 v[168:171], v242 offset:50176
	ds_read_b128 v[172:175], v242 offset:51200
	ds_read_b128 v[176:179], v242 offset:52224
	ds_read_b128 v[180:183], v242 offset:53248
	ds_read_b128 v[184:187], v242 offset:54272
	ds_read_b128 v[188:191], v242 offset:55296
	ds_read_b128 v[214:217], v242 offset:56320
	global_load_lds_dwordx4 v[218:219], off
	s_add_i32 m0, s22, 0x2000
	s_add_u32 s22, s26, 0x2b0080
	v_lshl_add_u64 v[218:219], v[220:221], 0, s[84:85]
	s_addc_u32 s23, s27, 0
	s_add_i32 s26, s57, s41
	global_load_lds_dwordx4 v[218:219], off
	v_lshl_add_u64 v[218:219], s[22:23], 0, v[2:3]
	s_mov_b32 m0, s26
	s_nop 0
	global_load_lds_dwordx4 v[218:219], off
	v_lshl_add_u64 v[218:219], s[22:23], 0, v[204:205]
	s_add_i32 m0, s26, 0x2000
	s_nop 0
	global_load_lds_dwordx4 v[218:219], off
	s_cmpk_eq_i32 s55, 0xa8
	s_cbranch_scc0 .Ldefer_1700_peel
	v_lshl_add_u64 v[218:219], v[222:223], 0, s[84:85]
	s_mov_b32 m0, s46
	s_nop 0
	global_load_lds_dwordx4 v[218:219], off
	v_lshl_add_u64 v[218:219], v[224:225], 0, s[84:85]
	s_mov_b32 m0, s47
	s_nop 0
	global_load_lds_dwordx4 v[218:219], off
; #define PG8_STAGE(bufoff, gbase, voff) do { _Pragma("unroll") for (int _i = 0; _i < 2; ++_i) \
;         __builtin_amdgcn_global_load_lds((const unsigned*)((const char*)(gbase) + (voff)[_i]), (PG8_LAS unsigned*)(lds + (bufoff) + ldsw + _i * 8192), 16, 0, 0); } while (0)
; #define PG8_LDA(dst, b, h) do { _Pragma("unroll") for (int m = 0; m < 4; ++m) _Pragma("unroll") for (int k = 0; k < 2; ++k) dst[m][k] = *(const PG8_LAS bf16x8*)(lds + PG8_SA(b, h) + aoff + m * 2048 + k * 1024); } while (0)
; #define PG8_LDB(dst, b, h) do { _Pragma("unroll") for (int n = 0; n < 2; ++n) _Pragma("unroll") for (int k = 0; k < 2; ++k) dst[n][k] = *(const PG8_LAS bf16x8*)(lds + PG8_SB(b, h) + boff + n * 2048 + k * 1024); } while (0)
; #define PG8_WAIT_V(n) asm volatile("s_waitcnt vmcnt(" #n ")" ::: "memory")
; #define PG8_WAIT_L(n) asm volatile("s_waitcnt lgkmcnt(" #n ")" ::: "memory")
; #define PG8_BAR __builtin_amdgcn_s_barrier()
; #define PG8_SCHED __builtin_amdgcn_sched_barrier(0)
; template <class Epi, class Sched, bool ALIGN_EPI = false, bool SP2 = false, bool I8 = false>
; __device__ __forceinline__ void gemm_phase(PG8_LAS unsigned char* lds, const Gemm g, const Sched& S, const Epi& E) {
;     ...
;             if constexpr (SP2) {
;             PG8_LDB(B0, 0, 0); PG8_LDB(B1, 0, 1); PG8_SCHED; PG8_LDA(At, 0, 0); PG8_STAGE(PG8_SA(1, 1), a1 + hstep, voffA);
;             PG8_WAIT_V(8); PG8_WAIT_L(0); PG8_BAR; PG8_MMA(0, 0, At, B0); PG8_MMA(0, 1, At, B1); PG8_BAR; PG8_SCHED;
;             PG8_LDA(At, 0, 1); PG8_STAGE(PG8_SB(0, 0), b2, voffB); PG8_STAGE(PG8_SB(0, 1), b2 + hstep, voffB); PG8_STAGE(PG8_SA(0, 0), a2, voffA);
;             PG8_WAIT_V(8); PG8_WAIT_L(0); PG8_BAR; PG8_MMA(1, 0, At, B0); PG8_MMA(1, 1, At, B1); PG8_BAR; PG8_SCHED;
;             PG8_LDB(B0, 1, 0); PG8_LDB(B1, 1, 1); PG8_SCHED; PG8_LDA(At, 1, 0); PG8_STAGE(PG8_SA(0, 1), a2 + hstep, voffA);
;             PG8_WAIT_V(8); PG8_WAIT_L(0); PG8_BAR; PG8_MMA(0, 0, At, B0); PG8_MMA(0, 1, At, B1); PG8_BAR; PG8_SCHED;
;             PG8_LDA(At, 1, 1); PG8_STAGE(PG8_SB(1, 0), b3, voffB); PG8_STAGE(PG8_SB(1, 1), b3 + hstep, voffB); PG8_STAGE(PG8_SA(1, 0), a3, voffA);
;             PG8_WAIT_V(8); PG8_WAIT_L(0); PG8_BAR; PG8_MMA(1, 0, At, B0); PG8_MMA(1, 1, At, B1); PG8_BAR; PG8_SCHED;
.Ldefer_1700_peel:
	s_waitcnt vmcnt(6)
	s_waitcnt lgkmcnt(0)
	s_barrier
	s_setprio 1
	s_waitcnt lgkmcnt(0)
	v_mfma_f32_16x16x32_bf16 v[64:67], v[124:127], v[164:167], v[64:67]
	v_mfma_f32_16x16x32_bf16 v[64:67], v[128:131], v[168:171], v[64:67]
	v_mfma_f32_16x16x32_bf16 v[48:51], v[128:131], v[176:179], v[48:51]
	v_mfma_f32_16x16x32_bf16 v[48:51], v[124:127], v[172:175], v[48:51]
	v_mfma_f32_16x16x32_bf16 v[32:35], v[124:127], v[180:183], v[32:35]
	v_mfma_f32_16x16x32_bf16 v[32:35], v[128:131], v[184:187], v[32:35]
	v_mfma_f32_16x16x32_bf16 v[16:19], v[128:131], v[214:217], v[16:19]
	v_mfma_f32_16x16x32_bf16 v[16:19], v[124:127], v[188:191], v[16:19]
	v_mfma_f32_16x16x32_bf16 v[12:15], v[132:135], v[188:191], v[12:15]
	v_mfma_f32_16x16x32_bf16 v[12:15], v[144:147], v[214:217], v[12:15]
	v_mfma_f32_16x16x32_bf16 v[28:31], v[144:147], v[184:187], v[28:31]
	v_mfma_f32_16x16x32_bf16 v[28:31], v[132:135], v[180:183], v[28:31]
	v_mfma_f32_16x16x32_bf16 v[44:47], v[132:135], v[172:175], v[44:47]
	v_mfma_f32_16x16x32_bf16 v[44:47], v[144:147], v[176:179], v[44:47]
	v_mfma_f32_16x16x32_bf16 v[60:63], v[144:147], v[168:171], v[60:63]
	v_mfma_f32_16x16x32_bf16 v[60:63], v[132:135], v[164:167], v[60:63]
	v_mfma_f32_16x16x32_bf16 v[56:59], v[148:151], v[164:167], v[56:59]
	v_mfma_f32_16x16x32_bf16 v[56:59], v[152:155], v[168:171], v[56:59]
	v_mfma_f32_16x16x32_bf16 v[40:43], v[152:155], v[176:179], v[40:43]
	v_mfma_f32_16x16x32_bf16 v[40:43], v[148:151], v[172:175], v[40:43]
	v_mfma_f32_16x16x32_bf16 v[24:27], v[148:151], v[180:183], v[24:27]
	v_mfma_f32_16x16x32_bf16 v[24:27], v[152:155], v[184:187], v[24:27]
	v_mfma_f32_16x16x32_bf16 v[8:11], v[152:155], v[214:217], v[8:11]
	v_mfma_f32_16x16x32_bf16 v[8:11], v[148:151], v[188:191], v[8:11]
	v_mfma_f32_16x16x32_bf16 v[4:7], v[156:159], v[188:191], v[4:7]
	v_mfma_f32_16x16x32_bf16 v[4:7], v[160:163], v[214:217], v[4:7]
	v_mfma_f32_16x16x32_bf16 v[20:23], v[160:163], v[184:187], v[20:23]
	v_mfma_f32_16x16x32_bf16 v[20:23], v[156:159], v[180:183], v[20:23]
	v_mfma_f32_16x16x32_bf16 v[36:39], v[156:159], v[172:175], v[36:39]
	v_mfma_f32_16x16x32_bf16 v[36:39], v[160:163], v[176:179], v[36:39]
	v_mfma_f32_16x16x32_bf16 v[52:55], v[160:163], v[168:171], v[52:55]
	v_mfma_f32_16x16x32_bf16 v[52:55], v[156:159], v[164:167], v[52:55]
	s_setprio 0
	s_barrier
	s_add_i32 s55, s55, 2
	s_add_u32 s53, s53, 0x100
	s_addc_u32 s54, s54, 0
	s_cmpk_gt_u32 s55, 0xa9
	s_mov_b64 s[22:23], s[24:25]
	s_cbranch_scc1 .Lkloop_exit_5
.LBB0_1700:
	s_add_u32 s24, s22, 0x100
	s_addc_u32 s25, s23, 0
	s_add_i32 s56, 0, 0x10000
	s_cmpk_eq_i32 s55, 0xa8
	s_cselect_b32 s37, s13, s25
	s_cselect_b32 s36, s12, s24
	s_cselect_b32 s27, s21, s54
	s_cselect_b32 s26, s20, s53
	s_add_i32 s57, 0, 0x14000
	v_add_u32_e32 v144, s56, v240
	v_add_u32_e32 v160, s57, v240
	ds_read_b128 v[124:127], v144
	ds_read_b128 v[128:131], v144 offset:1024
	ds_read_b128 v[132:135], v144 offset:2048
	ds_read_b128 v[144:147], v144 offset:3072
	ds_read_b128 v[148:151], v160
	ds_read_b128 v[152:155], v160 offset:1024
	ds_read_b128 v[156:159], v160 offset:2048
	ds_read_b128 v[160:163], v160 offset:3072
	v_lshl_add_u64 v[218:219], v[222:223], 0, s[84:85]
	s_mov_b32 m0, s46
	s_nop 0
	global_load_lds_dwordx4 v[218:219], off
	v_lshl_add_u64 v[218:219], v[224:225], 0, s[84:85]
	s_mov_b32 m0, s47
	s_nop 0
	global_load_lds_dwordx4 v[218:219], off
	v_lshl_add_u64 v[218:219], s[22:23], 0, v[210:211]
	s_add_i32 m0, s42, 0xc000
	ds_read_b128 v[164:167], v242
	ds_read_b128 v[168:171], v242 offset:1024
	ds_read_b128 v[172:175], v242 offset:2048
	ds_read_b128 v[176:179], v242 offset:3072
	ds_read_b128 v[180:183], v242 offset:4096
	ds_read_b128 v[184:187], v242 offset:5120
	ds_read_b128 v[188:191], v242 offset:6144
	ds_read_b128 v[214:217], v242 offset:7168
	global_load_lds_dwordx4 v[218:219], off
	v_lshl_add_u64 v[218:219], s[22:23], 0, v[212:213]
	s_add_i32 m0, s42, 0xe000
	s_nop 0
	global_load_lds_dwordx4 v[218:219], off
	s_waitcnt vmcnt(8)
	s_waitcnt lgkmcnt(0)
	s_barrier
	s_setprio 1
	s_waitcnt lgkmcnt(0)
	v_mfma_f32_16x16x32_bf16 v[140:143], v[124:127], v[164:167], v[140:143]
	v_mfma_f32_16x16x32_bf16 v[140:143], v[128:131], v[168:171], v[140:143]
	v_mfma_f32_16x16x32_bf16 v[112:115], v[128:131], v[176:179], v[112:115]
	v_mfma_f32_16x16x32_bf16 v[112:115], v[124:127], v[172:175], v[112:115]
	v_mfma_f32_16x16x32_bf16 v[96:99], v[124:127], v[180:183], v[96:99]
	v_mfma_f32_16x16x32_bf16 v[96:99], v[128:131], v[184:187], v[96:99]
	v_mfma_f32_16x16x32_bf16 v[80:83], v[128:131], v[214:217], v[80:83]
	v_mfma_f32_16x16x32_bf16 v[80:83], v[124:127], v[188:191], v[80:83]
	v_mfma_f32_16x16x32_bf16 v[76:79], v[132:135], v[188:191], v[76:79]
	v_mfma_f32_16x16x32_bf16 v[76:79], v[144:147], v[214:217], v[76:79]
	v_mfma_f32_16x16x32_bf16 v[92:95], v[144:147], v[184:187], v[92:95]
	v_mfma_f32_16x16x32_bf16 v[92:95], v[132:135], v[180:183], v[92:95]
	v_mfma_f32_16x16x32_bf16 v[108:111], v[132:135], v[172:175], v[108:111]
	v_mfma_f32_16x16x32_bf16 v[108:111], v[144:147], v[176:179], v[108:111]
	v_mfma_f32_16x16x32_bf16 v[136:139], v[144:147], v[168:171], v[136:139]
	v_mfma_f32_16x16x32_bf16 v[136:139], v[132:135], v[164:167], v[136:139]
	v_mfma_f32_16x16x32_bf16 v[120:123], v[148:151], v[164:167], v[120:123]
	v_mfma_f32_16x16x32_bf16 v[120:123], v[152:155], v[168:171], v[120:123]
	v_mfma_f32_16x16x32_bf16 v[104:107], v[152:155], v[176:179], v[104:107]
	v_mfma_f32_16x16x32_bf16 v[104:107], v[148:151], v[172:175], v[104:107]
	v_mfma_f32_16x16x32_bf16 v[88:91], v[148:151], v[180:183], v[88:91]
	v_mfma_f32_16x16x32_bf16 v[88:91], v[152:155], v[184:187], v[88:91]
	v_mfma_f32_16x16x32_bf16 v[72:75], v[152:155], v[214:217], v[72:75]
	v_mfma_f32_16x16x32_bf16 v[72:75], v[148:151], v[188:191], v[72:75]
	v_mfma_f32_16x16x32_bf16 v[68:71], v[156:159], v[188:191], v[68:71]
	v_mfma_f32_16x16x32_bf16 v[68:71], v[160:163], v[214:217], v[68:71]
	v_mfma_f32_16x16x32_bf16 v[84:87], v[160:163], v[184:187], v[84:87]
	v_mfma_f32_16x16x32_bf16 v[84:87], v[156:159], v[180:183], v[84:87]
	v_mfma_f32_16x16x32_bf16 v[100:103], v[156:159], v[172:175], v[100:103]
	v_mfma_f32_16x16x32_bf16 v[100:103], v[160:163], v[176:179], v[100:103]
	v_mfma_f32_16x16x32_bf16 v[116:119], v[160:163], v[168:171], v[116:119]
	v_mfma_f32_16x16x32_bf16 v[116:119], v[156:159], v[164:167], v[116:119]
	s_setprio 0
	s_barrier
; #define PG8_STAGE(bufoff, gbase, voff) do { _Pragma("unroll") for (int _i = 0; _i < 2; ++_i) \
;         __builtin_amdgcn_global_load_lds((const unsigned*)((const char*)(gbase) + (voff)[_i]), (PG8_LAS unsigned*)(lds + (bufoff) + ldsw + _i * 8192), 16, 0, 0); } while (0)
; #define PG8_LDA(dst, b, h) do { _Pragma("unroll") for (int m = 0; m < 4; ++m) _Pragma("unroll") for (int k = 0; k < 2; ++k) dst[m][k] = *(const PG8_LAS bf16x8*)(lds + PG8_SA(b, h) + aoff + m * 2048 + k * 1024); } while (0)
; #define PG8_LDB(dst, b, h) do { _Pragma("unroll") for (int n = 0; n < 2; ++n) _Pragma("unroll") for (int k = 0; k < 2; ++k) dst[n][k] = *(const PG8_LAS bf16x8*)(lds + PG8_SB(b, h) + boff + n * 2048 + k * 1024); } while (0)
; #define PG8_WAIT_V(n) asm volatile("s_waitcnt vmcnt(" #n ")" ::: "memory")
; #define PG8_WAIT_L(n) asm volatile("s_waitcnt lgkmcnt(" #n ")" ::: "memory")
; #define PG8_BAR __builtin_amdgcn_s_barrier()
; #define PG8_SCHED __builtin_amdgcn_sched_barrier(0)
; template <class Epi, class Sched, bool ALIGN_EPI = false, bool SP2 = false, bool I8 = false>
; __device__ __forceinline__ void gemm_phase(PG8_LAS unsigned char* lds, const Gemm g, const Sched& S, const Epi& E) {
;     ...
;             PG8_WAIT_V(8); PG8_WAIT_L(0); PG8_BAR; PG8_MMA(0, 0, At, B0); PG8_MMA(0, 1, At, B1); PG8_BAR; PG8_SCHED;
;             PG8_LDA(At, 0, 1); PG8_STAGE(PG8_SB(0, 0), b2, voffB); PG8_STAGE(PG8_SB(0, 1), b2 + hstep, voffB); PG8_STAGE(PG8_SA(0, 0), a2, voffA);
;             PG8_WAIT_V(8); PG8_WAIT_L(0); PG8_BAR; PG8_MMA(1, 0, At, B0); PG8_MMA(1, 1, At, B1); PG8_BAR; PG8_SCHED;
;             PG8_LDB(B0, 1, 0); PG8_LDB(B1, 1, 1); PG8_SCHED; PG8_LDA(At, 1, 0); PG8_STAGE(PG8_SA(0, 1), a2 + hstep, voffA);
;             PG8_WAIT_V(8); PG8_WAIT_L(0); PG8_BAR; PG8_MMA(0, 0, At, B0); PG8_MMA(0, 1, At, B1); PG8_BAR; PG8_SCHED;
	s_add_i32 s22, s56, s41
	v_lshl_add_u64 v[218:219], s[26:27], 0, v[2:3]
	s_mov_b32 m0, s22
	ds_read_b128 v[164:167], v242 offset:16384
	ds_read_b128 v[168:171], v242 offset:17408
	ds_read_b128 v[172:175], v242 offset:18432
	ds_read_b128 v[176:179], v242 offset:19456
	ds_read_b128 v[180:183], v242 offset:20480
	ds_read_b128 v[184:187], v242 offset:21504
	ds_read_b128 v[188:191], v242 offset:22528
	ds_read_b128 v[214:217], v242 offset:23552
	global_load_lds_dwordx4 v[218:219], off
	s_add_i32 m0, s22, 0x2000
	s_add_u32 s22, s26, 0x2b0000
	v_lshl_add_u64 v[220:221], s[26:27], 0, v[204:205]
	s_addc_u32 s23, s27, 0
	s_add_i32 s56, s57, s41
	global_load_lds_dwordx4 v[220:221], off
	v_lshl_add_u64 v[222:223], s[22:23], 0, v[2:3]
	s_mov_b32 m0, s56
	v_lshl_add_u64 v[224:225], s[36:37], 0, v[206:207]
	global_load_lds_dwordx4 v[222:223], off
	v_lshl_add_u64 v[222:223], s[22:23], 0, v[204:205]
	s_add_i32 m0, s56, 0x2000
	s_nop 0
	global_load_lds_dwordx4 v[222:223], off
	v_lshl_add_u64 v[222:223], s[36:37], 0, v[208:209]
	s_waitcnt vmcnt(6)
	s_waitcnt lgkmcnt(0)
	s_barrier
	s_setprio 1
	s_waitcnt lgkmcnt(0)
	v_mfma_f32_16x16x32_bf16 v[64:67], v[124:127], v[164:167], v[64:67]
	v_mfma_f32_16x16x32_bf16 v[64:67], v[128:131], v[168:171], v[64:67]
	v_mfma_f32_16x16x32_bf16 v[48:51], v[128:131], v[176:179], v[48:51]
	v_mfma_f32_16x16x32_bf16 v[48:51], v[124:127], v[172:175], v[48:51]
	v_mfma_f32_16x16x32_bf16 v[32:35], v[124:127], v[180:183], v[32:35]
	v_mfma_f32_16x16x32_bf16 v[32:35], v[128:131], v[184:187], v[32:35]
	v_mfma_f32_16x16x32_bf16 v[16:19], v[128:131], v[214:217], v[16:19]
	v_mfma_f32_16x16x32_bf16 v[16:19], v[124:127], v[188:191], v[16:19]
	v_mfma_f32_16x16x32_bf16 v[12:15], v[132:135], v[188:191], v[12:15]
	v_mfma_f32_16x16x32_bf16 v[12:15], v[144:147], v[214:217], v[12:15]
	v_mfma_f32_16x16x32_bf16 v[28:31], v[144:147], v[184:187], v[28:31]
	v_mfma_f32_16x16x32_bf16 v[28:31], v[132:135], v[180:183], v[28:31]
	v_mfma_f32_16x16x32_bf16 v[44:47], v[132:135], v[172:175], v[44:47]
	v_mfma_f32_16x16x32_bf16 v[44:47], v[144:147], v[176:179], v[44:47]
	v_mfma_f32_16x16x32_bf16 v[60:63], v[144:147], v[168:171], v[60:63]
	v_mfma_f32_16x16x32_bf16 v[60:63], v[132:135], v[164:167], v[60:63]
	v_mfma_f32_16x16x32_bf16 v[56:59], v[148:151], v[164:167], v[56:59]
	v_mfma_f32_16x16x32_bf16 v[56:59], v[152:155], v[168:171], v[56:59]
	v_mfma_f32_16x16x32_bf16 v[40:43], v[152:155], v[176:179], v[40:43]
	v_mfma_f32_16x16x32_bf16 v[40:43], v[148:151], v[172:175], v[40:43]
	v_mfma_f32_16x16x32_bf16 v[24:27], v[148:151], v[180:183], v[24:27]
	v_mfma_f32_16x16x32_bf16 v[24:27], v[152:155], v[184:187], v[24:27]
	v_mfma_f32_16x16x32_bf16 v[8:11], v[152:155], v[214:217], v[8:11]
	v_mfma_f32_16x16x32_bf16 v[8:11], v[148:151], v[188:191], v[8:11]
	v_mfma_f32_16x16x32_bf16 v[4:7], v[156:159], v[188:191], v[4:7]
	v_mfma_f32_16x16x32_bf16 v[4:7], v[160:163], v[214:217], v[4:7]
	v_mfma_f32_16x16x32_bf16 v[20:23], v[160:163], v[184:187], v[20:23]
	v_mfma_f32_16x16x32_bf16 v[20:23], v[156:159], v[180:183], v[20:23]
	v_mfma_f32_16x16x32_bf16 v[36:39], v[156:159], v[172:175], v[36:39]
	v_mfma_f32_16x16x32_bf16 v[36:39], v[160:163], v[176:179], v[36:39]
	v_mfma_f32_16x16x32_bf16 v[52:55], v[160:163], v[168:171], v[52:55]
	v_mfma_f32_16x16x32_bf16 v[52:55], v[156:159], v[164:167], v[52:55]
	s_setprio 0
	s_barrier
	s_mov_b32 m0, s42
	s_nop 0
	global_load_lds_dwordx4 v[222:223], off
	s_mov_b32 m0, s43
	s_nop 0
	global_load_lds_dwordx4 v[224:225], off
	s_add_i32 s56, 0, 0x18000
	s_add_i32 s57, 0, 0x1c000
	v_add_u32_e32 v144, s56, v240
	v_add_u32_e32 v160, s57, v240
	ds_read_b128 v[124:127], v144
	ds_read_b128 v[128:131], v144 offset:1024
	ds_read_b128 v[132:135], v144 offset:2048
	ds_read_b128 v[144:147], v144 offset:3072
	ds_read_b128 v[148:151], v160
	ds_read_b128 v[152:155], v160 offset:1024
	ds_read_b128 v[156:159], v160 offset:2048
	ds_read_b128 v[160:163], v160 offset:3072
	s_add_u32 s22, s36, 0x2b0000
	s_addc_u32 s23, s37, 0
	s_mov_b32 m0, s44
	v_lshl_add_u64 v[226:227], s[22:23], 0, v[208:209]
	ds_read_b128 v[164:167], v242 offset:32768
	ds_read_b128 v[168:171], v242 offset:33792
	ds_read_b128 v[172:175], v242 offset:34816
	ds_read_b128 v[176:179], v242 offset:35840
	ds_read_b128 v[180:183], v242 offset:36864
	ds_read_b128 v[184:187], v242 offset:37888
	ds_read_b128 v[188:191], v242 offset:38912
	ds_read_b128 v[214:217], v242 offset:39936
	global_load_lds_dwordx4 v[226:227], off
	v_lshl_add_u64 v[226:227], s[22:23], 0, v[206:207]
	s_mov_b32 m0, s45
	s_nop 0
	global_load_lds_dwordx4 v[226:227], off
	s_waitcnt vmcnt(8)
	s_waitcnt lgkmcnt(0)
	s_barrier
; #define PG8_STAGE(bufoff, gbase, voff) do { _Pragma("unroll") for (int _i = 0; _i < 2; ++_i) \
;         __builtin_amdgcn_global_load_lds((const unsigned*)((const char*)(gbase) + (voff)[_i]), (PG8_LAS unsigned*)(lds + (bufoff) + ldsw + _i * 8192), 16, 0, 0); } while (0)
; #define PG8_LDA(dst, b, h) do { _Pragma("unroll") for (int m = 0; m < 4; ++m) _Pragma("unroll") for (int k = 0; k < 2; ++k) dst[m][k] = *(const PG8_LAS bf16x8*)(lds + PG8_SA(b, h) + aoff + m * 2048 + k * 1024); } while (0)
; #define PG8_WAIT_V(n) asm volatile("s_waitcnt vmcnt(" #n ")" ::: "memory")
; #define PG8_WAIT_L(n) asm volatile("s_waitcnt lgkmcnt(" #n ")" ::: "memory")
; #define PG8_BAR __builtin_amdgcn_s_barrier()
; #define PG8_SCHED __builtin_amdgcn_sched_barrier(0)
; template <class Epi, class Sched, bool ALIGN_EPI = false, bool SP2 = false, bool I8 = false>
; __device__ __forceinline__ void gemm_phase(PG8_LAS unsigned char* lds, const Gemm g, const Sched& S, const Epi& E) {
;     ...
;             PG8_WAIT_V(8); PG8_WAIT_L(0); PG8_BAR; PG8_MMA(0, 0, At, B0); PG8_MMA(0, 1, At, B1); PG8_BAR; PG8_SCHED;
;             PG8_LDA(At, 1, 1); PG8_STAGE(PG8_SB(1, 0), b3, voffB); PG8_STAGE(PG8_SB(1, 1), b3 + hstep, voffB); PG8_STAGE(PG8_SA(1, 0), a3, voffA);
;             PG8_WAIT_V(8); PG8_WAIT_L(0); PG8_BAR; PG8_MMA(1, 0, At, B0); PG8_MMA(1, 1, At, B1); PG8_BAR; PG8_SCHED;
	s_setprio 1
	s_waitcnt lgkmcnt(0)
	v_mfma_f32_16x16x32_bf16 v[140:143], v[124:127], v[164:167], v[140:143]
	v_mfma_f32_16x16x32_bf16 v[140:143], v[128:131], v[168:171], v[140:143]
	v_mfma_f32_16x16x32_bf16 v[112:115], v[128:131], v[176:179], v[112:115]
	v_mfma_f32_16x16x32_bf16 v[112:115], v[124:127], v[172:175], v[112:115]
	v_mfma_f32_16x16x32_bf16 v[96:99], v[124:127], v[180:183], v[96:99]
	v_mfma_f32_16x16x32_bf16 v[96:99], v[128:131], v[184:187], v[96:99]
	v_mfma_f32_16x16x32_bf16 v[80:83], v[128:131], v[214:217], v[80:83]
	v_mfma_f32_16x16x32_bf16 v[80:83], v[124:127], v[188:191], v[80:83]
	v_mfma_f32_16x16x32_bf16 v[76:79], v[132:135], v[188:191], v[76:79]
	v_mfma_f32_16x16x32_bf16 v[76:79], v[144:147], v[214:217], v[76:79]
	v_mfma_f32_16x16x32_bf16 v[92:95], v[144:147], v[184:187], v[92:95]
	v_mfma_f32_16x16x32_bf16 v[92:95], v[132:135], v[180:183], v[92:95]
	v_mfma_f32_16x16x32_bf16 v[108:111], v[132:135], v[172:175], v[108:111]
	v_mfma_f32_16x16x32_bf16 v[108:111], v[144:147], v[176:179], v[108:111]
	v_mfma_f32_16x16x32_bf16 v[136:139], v[144:147], v[168:171], v[136:139]
	v_mfma_f32_16x16x32_bf16 v[136:139], v[132:135], v[164:167], v[136:139]
	v_mfma_f32_16x16x32_bf16 v[120:123], v[148:151], v[164:167], v[120:123]
	v_mfma_f32_16x16x32_bf16 v[120:123], v[152:155], v[168:171], v[120:123]
	v_mfma_f32_16x16x32_bf16 v[104:107], v[152:155], v[176:179], v[104:107]
	v_mfma_f32_16x16x32_bf16 v[104:107], v[148:151], v[172:175], v[104:107]
	v_mfma_f32_16x16x32_bf16 v[88:91], v[148:151], v[180:183], v[88:91]
	v_mfma_f32_16x16x32_bf16 v[88:91], v[152:155], v[184:187], v[88:91]
	v_mfma_f32_16x16x32_bf16 v[72:75], v[152:155], v[214:217], v[72:75]
	v_mfma_f32_16x16x32_bf16 v[72:75], v[148:151], v[188:191], v[72:75]
	v_mfma_f32_16x16x32_bf16 v[68:71], v[156:159], v[188:191], v[68:71]
	v_mfma_f32_16x16x32_bf16 v[68:71], v[160:163], v[214:217], v[68:71]
	v_mfma_f32_16x16x32_bf16 v[84:87], v[160:163], v[184:187], v[84:87]
	v_mfma_f32_16x16x32_bf16 v[84:87], v[156:159], v[180:183], v[84:87]
	v_mfma_f32_16x16x32_bf16 v[100:103], v[156:159], v[172:175], v[100:103]
	v_mfma_f32_16x16x32_bf16 v[100:103], v[160:163], v[176:179], v[100:103]
	v_mfma_f32_16x16x32_bf16 v[116:119], v[160:163], v[168:171], v[116:119]
	v_mfma_f32_16x16x32_bf16 v[116:119], v[156:159], v[164:167], v[116:119]
	s_setprio 0
	s_barrier
	s_add_i32 s22, s56, s41
	v_lshl_add_u64 v[218:219], v[218:219], 0, s[84:85]
	s_mov_b32 m0, s22
	ds_read_b128 v[164:167], v242 offset:49152
	ds_read_b128 v[168:171], v242 offset:50176
	ds_read_b128 v[172:175], v242 offset:51200
	ds_read_b128 v[176:179], v242 offset:52224
	ds_read_b128 v[180:183], v242 offset:53248
	ds_read_b128 v[184:187], v242 offset:54272
	ds_read_b128 v[188:191], v242 offset:55296
	ds_read_b128 v[214:217], v242 offset:56320
	global_load_lds_dwordx4 v[218:219], off
	s_add_i32 m0, s22, 0x2000
	s_add_u32 s22, s26, 0x2b0080
	v_lshl_add_u64 v[218:219], v[220:221], 0, s[84:85]
	s_addc_u32 s23, s27, 0
	s_add_i32 s26, s57, s41
	global_load_lds_dwordx4 v[218:219], off
	v_lshl_add_u64 v[218:219], s[22:23], 0, v[2:3]
	s_mov_b32 m0, s26
	s_nop 0
	global_load_lds_dwordx4 v[218:219], off
	v_lshl_add_u64 v[218:219], s[22:23], 0, v[204:205]
	s_add_i32 m0, s26, 0x2000
	s_nop 0
	global_load_lds_dwordx4 v[218:219], off
	s_cmpk_eq_i32 s55, 0xa8
	s_cbranch_scc0 .Ldefer_1700_body
	v_lshl_add_u64 v[218:219], v[222:223], 0, s[84:85]
	s_mov_b32 m0, s46
	s_nop 0
	global_load_lds_dwordx4 v[218:219], off
	v_lshl_add_u64 v[218:219], v[224:225], 0, s[84:85]
	s_mov_b32 m0, s47
	s_nop 0
	global_load_lds_dwordx4 v[218:219], off
.Ldefer_1700_body:
	s_waitcnt vmcnt(6)
	s_waitcnt lgkmcnt(0)
	s_barrier
	s_setprio 1
	s_waitcnt lgkmcnt(0)
	v_mfma_f32_16x16x32_bf16 v[64:67], v[124:127], v[164:167], v[64:67]
	v_mfma_f32_16x16x32_bf16 v[64:67], v[128:131], v[168:171], v[64:67]
	v_mfma_f32_16x16x32_bf16 v[48:51], v[128:131], v[176:179], v[48:51]
	v_mfma_f32_16x16x32_bf16 v[48:51], v[124:127], v[172:175], v[48:51]
	v_mfma_f32_16x16x32_bf16 v[32:35], v[124:127], v[180:183], v[32:35]
	v_mfma_f32_16x16x32_bf16 v[32:35], v[128:131], v[184:187], v[32:35]
	v_mfma_f32_16x16x32_bf16 v[16:19], v[128:131], v[214:217], v[16:19]
	v_mfma_f32_16x16x32_bf16 v[16:19], v[124:127], v[188:191], v[16:19]
	v_mfma_f32_16x16x32_bf16 v[12:15], v[132:135], v[188:191], v[12:15]
	v_mfma_f32_16x16x32_bf16 v[12:15], v[144:147], v[214:217], v[12:15]
	v_mfma_f32_16x16x32_bf16 v[28:31], v[144:147], v[184:187], v[28:31]
	v_mfma_f32_16x16x32_bf16 v[28:31], v[132:135], v[180:183], v[28:31]
	v_mfma_f32_16x16x32_bf16 v[44:47], v[132:135], v[172:175], v[44:47]
	v_mfma_f32_16x16x32_bf16 v[44:47], v[144:147], v[176:179], v[44:47]
	v_mfma_f32_16x16x32_bf16 v[60:63], v[144:147], v[168:171], v[60:63]
	v_mfma_f32_16x16x32_bf16 v[60:63], v[132:135], v[164:167], v[60:63]
	v_mfma_f32_16x16x32_bf16 v[56:59], v[148:151], v[164:167], v[56:59]
	v_mfma_f32_16x16x32_bf16 v[56:59], v[152:155], v[168:171], v[56:59]
	v_mfma_f32_16x16x32_bf16 v[40:43], v[152:155], v[176:179], v[40:43]
	v_mfma_f32_16x16x32_bf16 v[40:43], v[148:151], v[172:175], v[40:43]
	v_mfma_f32_16x16x32_bf16 v[24:27], v[148:151], v[180:183], v[24:27]
	v_mfma_f32_16x16x32_bf16 v[24:27], v[152:155], v[184:187], v[24:27]
	v_mfma_f32_16x16x32_bf16 v[8:11], v[152:155], v[214:217], v[8:11]
	v_mfma_f32_16x16x32_bf16 v[8:11], v[148:151], v[188:191], v[8:11]
	v_mfma_f32_16x16x32_bf16 v[4:7], v[156:159], v[188:191], v[4:7]
	v_mfma_f32_16x16x32_bf16 v[4:7], v[160:163], v[214:217], v[4:7]
	v_mfma_f32_16x16x32_bf16 v[20:23], v[160:163], v[184:187], v[20:23]
	v_mfma_f32_16x16x32_bf16 v[20:23], v[156:159], v[180:183], v[20:23]
	v_mfma_f32_16x16x32_bf16 v[36:39], v[156:159], v[172:175], v[36:39]
	v_mfma_f32_16x16x32_bf16 v[36:39], v[160:163], v[176:179], v[36:39]
	v_mfma_f32_16x16x32_bf16 v[52:55], v[160:163], v[168:171], v[52:55]
	v_mfma_f32_16x16x32_bf16 v[52:55], v[156:159], v[164:167], v[52:55]
	s_setprio 0
	s_barrier
	s_add_i32 s55, s55, 2
	s_add_u32 s53, s53, 0x100
	s_addc_u32 s54, s54, 0
	s_cmpk_gt_u32 s55, 0xa9
	s_mov_b64 s[22:23], s[24:25]
	s_cbranch_scc0 .LBB0_1700

; #define PG8_STAGE(bufoff, gbase, voff) do { _Pragma("unroll") for (int _i = 0; _i < 2; ++_i) \
;         __builtin_amdgcn_global_load_lds((const unsigned*)((const char*)(gbase) + (voff)[_i]), (PG8_LAS unsigned*)(lds + (bufoff) + ldsw + _i * 8192), 16, 0, 0); } while (0)
; #define PG8_LDA(dst, b, h) do { _Pragma("unroll") for (int m = 0; m < 4; ++m) _Pragma("unroll") for (int k = 0; k < 2; ++k) dst[m][k] = *(const PG8_LAS bf16x8*)(lds + PG8_SA(b, h) + aoff + m * 2048 + k * 1024); } while (0)
; #define PG8_LDB(dst, b, h) do { _Pragma("unroll") for (int n = 0; n < 2; ++n) _Pragma("unroll") for (int k = 0; k < 2; ++k) dst[n][k] = *(const PG8_LAS bf16x8*)(lds + PG8_SB(b, h) + boff + n * 2048 + k * 1024); } while (0)
; #define PG8_WAIT_V(n) asm volatile("s_waitcnt vmcnt(" #n ")" ::: "memory")
; #define PG8_WAIT_L(n) asm volatile("s_waitcnt lgkmcnt(" #n ")" ::: "memory")
; #define PG8_BAR __builtin_amdgcn_s_barrier()
; #define PG8_SCHED __builtin_amdgcn_sched_barrier(0)
; template <class Epi, class Sched, bool ALIGN_EPI = false, bool SP2 = false, bool I8 = false>
; __device__ __forceinline__ void gemm_phase(PG8_LAS unsigned char* lds, const Gemm g, const Sched& S, const Epi& E) {
;     ...
;         const bool has_next = S.next(ui + 1, nxt);
;         const char* nA = has_next ? (const char*)g.A + (size_t)nxt.pm * tstep : cA; const char* nB = has_next ? (const char*)g.Bt + (size_t)nxt.pn * tstep : cB;
;         for (int t = 0; t < nt; t += 2) {
;             const bool last = (t == nt - 2);
;             const char* a1 = cA + (size_t)(t + 1) * kstep;
;             const char* a2 = last ? nA : cA + (size_t)(t + 2) * kstep; const char* b2 = last ? nB : cB + (size_t)(t + 2) * kstep;
;             const char* a3 = a2 + kstep; const char* b3 = b2 + kstep;
;             if (last && has_next) S.a_ready(nxt);
;             if constexpr (SP2) {
;             PG8_LDB(B0, 0, 0); PG8_LDB(B1, 0, 1); PG8_SCHED; PG8_LDA(At, 0, 0); PG8_STAGE(PG8_SA(1, 1), a1 + hstep, voffA);
;             PG8_WAIT_V(8); PG8_WAIT_L(0); PG8_BAR; PG8_MMA(0, 0, At, B0); PG8_MMA(0, 1, At, B1); PG8_BAR; PG8_SCHED;
;             PG8_LDA(At, 0, 1); PG8_STAGE(PG8_SB(0, 0), b2, voffB); PG8_STAGE(PG8_SB(0, 1), b2 + hstep, voffB); PG8_STAGE(PG8_SA(0, 0), a2, voffA);
;             PG8_WAIT_V(8); PG8_WAIT_L(0); PG8_BAR; PG8_MMA(1, 0, At, B0); PG8_MMA(1, 1, At, B1); PG8_BAR; PG8_SCHED;
.LBB0_1842:
	s_ashr_i32 s45, s44, 31
	s_lshl_b64 s[34:35], s[44:45], 20
	s_add_u32 s50, s47, s34
	s_addc_u32 s51, s52, s35
	s_and_b64 s[34:35], s[8:9], exec
	s_cselect_b32 s11, s51, s55
	s_cselect_b32 s13, s50, s54
	s_ashr_i32 s49, s48, 31
	s_lshl_b64 s[34:35], s[48:49], 20
	s_add_u32 s56, s53, s34
	s_addc_u32 s57, s64, s35
	s_and_b64 s[34:35], s[8:9], exec
	s_cselect_b32 s34, s57, s59
	s_cselect_b32 s35, s56, s58
	s_add_u32 s54, s54, 0x80080
	s_addc_u32 s55, s55, 0
	s_add_u32 s45, s58, 0x100
	s_addc_u32 s49, s59, 0
	s_mov_b32 s86, -2
	s_waitcnt lgkmcnt(0)
	s_add_u32 s58, s54, 0xfff80080
	s_addc_u32 s59, s55, -1
	s_add_i32 s87, 0, 0x10000
	s_cmp_eq_u32 s86, 28
	s_cselect_b32 s61, s11, s59
	s_cselect_b32 s60, s13, s58
	s_cselect_b32 s59, s34, s49
	s_cselect_b32 s58, s35, s45
	s_add_i32 vcc_lo, 0, 0x14000
	v_add_u32_e32 v40, s87, v217
	v_add_u32_e32 v160, vcc_lo, v217
	ds_read_b128 v[28:31], v40
	ds_read_b128 v[32:35], v40 offset:1024
	ds_read_b128 v[36:39], v40 offset:2048
	ds_read_b128 v[40:43], v40 offset:3072
	ds_read_b128 v[140:143], v160
	ds_read_b128 v[144:147], v160 offset:1024
	ds_read_b128 v[156:159], v160 offset:2048
	ds_read_b128 v[160:163], v160 offset:3072
	v_lshl_add_u64 v[190:191], s[54:55], 0, v[186:187]
	s_add_i32 m0, s65, 0xc000
	ds_read_b128 v[164:167], v219
	ds_read_b128 v[168:171], v219 offset:1024
	ds_read_b128 v[172:175], v219 offset:2048
	ds_read_b128 v[176:179], v219 offset:3072
	ds_read_b128 v[204:207], v219 offset:4096
	ds_read_b128 v[208:211], v219 offset:5120
	ds_read_b128 v[212:215], v219 offset:6144
	ds_read_b128 v[220:223], v219 offset:7168
	global_load_lds_dwordx4 v[190:191], off
	v_lshl_add_u64 v[190:191], s[54:55], 0, v[188:189]
	s_add_i32 m0, s65, 0xe000
	s_nop 0
	global_load_lds_dwordx4 v[190:191], off
	s_waitcnt vmcnt(8)
	s_waitcnt lgkmcnt(0)
	s_barrier
	s_setprio 1
	s_waitcnt lgkmcnt(0)
	v_mfma_i32_16x16x64_i8 v[152:155], v[28:31], v[164:167], 0
	v_mfma_i32_16x16x64_i8 v[152:155], v[32:35], v[168:171], v[152:155]
	v_mfma_i32_16x16x64_i8 v[128:131], v[32:35], v[176:179], 0
	v_mfma_i32_16x16x64_i8 v[128:131], v[28:31], v[172:175], v[128:131]
	v_mfma_i32_16x16x64_i8 v[112:115], v[28:31], v[204:207], 0
	v_mfma_i32_16x16x64_i8 v[112:115], v[32:35], v[208:211], v[112:115]
	v_mfma_i32_16x16x64_i8 v[96:99], v[32:35], v[220:223], 0
	v_mfma_i32_16x16x64_i8 v[96:99], v[28:31], v[212:215], v[96:99]
	v_mfma_i32_16x16x64_i8 v[92:95], v[36:39], v[212:215], 0
	v_mfma_i32_16x16x64_i8 v[92:95], v[40:43], v[220:223], v[92:95]
	v_mfma_i32_16x16x64_i8 v[108:111], v[40:43], v[208:211], 0
	v_mfma_i32_16x16x64_i8 v[108:111], v[36:39], v[204:207], v[108:111]
	v_mfma_i32_16x16x64_i8 v[124:127], v[36:39], v[172:175], 0
	v_mfma_i32_16x16x64_i8 v[124:127], v[40:43], v[176:179], v[124:127]
	v_mfma_i32_16x16x64_i8 v[148:151], v[40:43], v[168:171], 0
	v_mfma_i32_16x16x64_i8 v[148:151], v[36:39], v[164:167], v[148:151]
	v_mfma_i32_16x16x64_i8 v[136:139], v[140:143], v[164:167], 0
	v_mfma_i32_16x16x64_i8 v[136:139], v[144:147], v[168:171], v[136:139]
	v_mfma_i32_16x16x64_i8 v[120:123], v[144:147], v[176:179], 0
	v_mfma_i32_16x16x64_i8 v[120:123], v[140:143], v[172:175], v[120:123]
	v_mfma_i32_16x16x64_i8 v[104:107], v[140:143], v[204:207], 0
	v_mfma_i32_16x16x64_i8 v[104:107], v[144:147], v[208:211], v[104:107]
	v_mfma_i32_16x16x64_i8 v[88:91], v[144:147], v[220:223], 0
	v_mfma_i32_16x16x64_i8 v[88:91], v[140:143], v[212:215], v[88:91]
	v_mfma_i32_16x16x64_i8 v[84:87], v[156:159], v[212:215], 0
	v_mfma_i32_16x16x64_i8 v[84:87], v[160:163], v[220:223], v[84:87]
	v_mfma_i32_16x16x64_i8 v[100:103], v[160:163], v[208:211], 0
	v_mfma_i32_16x16x64_i8 v[100:103], v[156:159], v[204:207], v[100:103]
	v_mfma_i32_16x16x64_i8 v[116:119], v[156:159], v[172:175], 0
	v_mfma_i32_16x16x64_i8 v[116:119], v[160:163], v[176:179], v[116:119]
	v_mfma_i32_16x16x64_i8 v[132:135], v[160:163], v[168:171], 0
	v_mfma_i32_16x16x64_i8 v[132:135], v[156:159], v[164:167], v[132:135]
	s_setprio 0
	s_barrier
	s_add_i32 s87, s87, s46
	v_lshl_add_u64 v[190:191], s[58:59], 0, v[2:3]
	s_mov_b32 m0, s87
	ds_read_b128 v[164:167], v219 offset:16384
	ds_read_b128 v[168:171], v219 offset:17408
	ds_read_b128 v[172:175], v219 offset:18432
	ds_read_b128 v[176:179], v219 offset:19456
	ds_read_b128 v[204:207], v219 offset:20480
	ds_read_b128 v[208:211], v219 offset:21504
	ds_read_b128 v[212:215], v219 offset:22528
	ds_read_b128 v[220:223], v219 offset:23552
	global_load_lds_dwordx4 v[190:191], off
	s_add_i32 m0, s87, 0x2000
	s_add_u32 s96, s58, 0x80000
	v_lshl_add_u64 v[224:225], s[58:59], 0, v[184:185]
	s_addc_u32 s97, s59, 0
	s_add_i32 s87, vcc_lo, s46
	global_load_lds_dwordx4 v[224:225], off
	v_lshl_add_u64 v[226:227], s[96:97], 0, v[2:3]
	s_mov_b32 m0, s87
	v_lshl_add_u64 v[228:229], s[60:61], 0, v[182:183]
	global_load_lds_dwordx4 v[226:227], off
	v_lshl_add_u64 v[226:227], s[96:97], 0, v[184:185]
	s_add_i32 m0, s87, 0x2000
	s_nop 0
	global_load_lds_dwordx4 v[226:227], off
	v_lshl_add_u64 v[226:227], s[60:61], 0, v[180:181]
	s_waitcnt vmcnt(6)
	s_waitcnt lgkmcnt(0)
	s_barrier
; #define PG8_STAGE(bufoff, gbase, voff) do { _Pragma("unroll") for (int _i = 0; _i < 2; ++_i) \
;         __builtin_amdgcn_global_load_lds((const unsigned*)((const char*)(gbase) + (voff)[_i]), (PG8_LAS unsigned*)(lds + (bufoff) + ldsw + _i * 8192), 16, 0, 0); } while (0)
; #define PG8_LDA(dst, b, h) do { _Pragma("unroll") for (int m = 0; m < 4; ++m) _Pragma("unroll") for (int k = 0; k < 2; ++k) dst[m][k] = *(const PG8_LAS bf16x8*)(lds + PG8_SA(b, h) + aoff + m * 2048 + k * 1024); } while (0)
; #define PG8_LDB(dst, b, h) do { _Pragma("unroll") for (int n = 0; n < 2; ++n) _Pragma("unroll") for (int k = 0; k < 2; ++k) dst[n][k] = *(const PG8_LAS bf16x8*)(lds + PG8_SB(b, h) + boff + n * 2048 + k * 1024); } while (0)
; #define PG8_WAIT_V(n) asm volatile("s_waitcnt vmcnt(" #n ")" ::: "memory")
; #define PG8_WAIT_L(n) asm volatile("s_waitcnt lgkmcnt(" #n ")" ::: "memory")
; #define PG8_BAR __builtin_amdgcn_s_barrier()
; #define PG8_SCHED __builtin_amdgcn_sched_barrier(0)
; template <class Epi, class Sched, bool ALIGN_EPI = false, bool SP2 = false, bool I8 = false>
; __device__ __forceinline__ void gemm_phase(PG8_LAS unsigned char* lds, const Gemm g, const Sched& S, const Epi& E) {
;     ...
;             PG8_WAIT_V(8); PG8_WAIT_L(0); PG8_BAR; PG8_MMA(0, 0, At, B0); PG8_MMA(0, 1, At, B1); PG8_BAR; PG8_SCHED;
;             PG8_LDA(At, 0, 1); PG8_STAGE(PG8_SB(0, 0), b2, voffB); PG8_STAGE(PG8_SB(0, 1), b2 + hstep, voffB); PG8_STAGE(PG8_SA(0, 0), a2, voffA);
;             PG8_WAIT_V(8); PG8_WAIT_L(0); PG8_BAR; PG8_MMA(1, 0, At, B0); PG8_MMA(1, 1, At, B1); PG8_BAR; PG8_SCHED;
;             PG8_LDB(B0, 1, 0); PG8_LDB(B1, 1, 1); PG8_SCHED; PG8_LDA(At, 1, 0); PG8_STAGE(PG8_SA(0, 1), a2 + hstep, voffA);
;             PG8_WAIT_V(8); PG8_WAIT_L(0); PG8_BAR; PG8_MMA(0, 0, At, B0); PG8_MMA(0, 1, At, B1); PG8_BAR; PG8_SCHED;
;             PG8_LDA(At, 1, 1); PG8_STAGE(PG8_SB(1, 0), b3, voffB); PG8_STAGE(PG8_SB(1, 1), b3 + hstep, voffB); PG8_STAGE(PG8_SA(1, 0), a3, voffA);
;             PG8_WAIT_V(8); PG8_WAIT_L(0); PG8_BAR; PG8_MMA(1, 0, At, B0); PG8_MMA(1, 1, At, B1); PG8_BAR; PG8_SCHED;
	s_setprio 1
	s_waitcnt lgkmcnt(0)
	v_mfma_i32_16x16x64_i8 v[80:83], v[28:31], v[164:167], 0
	v_mfma_i32_16x16x64_i8 v[80:83], v[32:35], v[168:171], v[80:83]
	v_mfma_i32_16x16x64_i8 v[64:67], v[32:35], v[176:179], 0
	v_mfma_i32_16x16x64_i8 v[64:67], v[28:31], v[172:175], v[64:67]
	v_mfma_i32_16x16x64_i8 v[48:51], v[28:31], v[204:207], 0
	v_mfma_i32_16x16x64_i8 v[48:51], v[32:35], v[208:211], v[48:51]
	v_mfma_i32_16x16x64_i8 v[16:19], v[32:35], v[220:223], 0
	v_mfma_i32_16x16x64_i8 v[16:19], v[28:31], v[212:215], v[16:19]
	v_mfma_i32_16x16x64_i8 v[12:15], v[36:39], v[212:215], 0
	v_mfma_i32_16x16x64_i8 v[12:15], v[40:43], v[220:223], v[12:15]
	v_mfma_i32_16x16x64_i8 v[44:47], v[40:43], v[208:211], 0
	v_mfma_i32_16x16x64_i8 v[44:47], v[36:39], v[204:207], v[44:47]
	v_mfma_i32_16x16x64_i8 v[60:63], v[36:39], v[172:175], 0
	v_mfma_i32_16x16x64_i8 v[60:63], v[40:43], v[176:179], v[60:63]
	v_mfma_i32_16x16x64_i8 v[76:79], v[40:43], v[168:171], 0
	v_mfma_i32_16x16x64_i8 v[76:79], v[36:39], v[164:167], v[76:79]
	v_mfma_i32_16x16x64_i8 v[28:31], v[140:143], v[164:167], 0
	v_mfma_i32_16x16x64_i8 v[28:31], v[144:147], v[168:171], v[28:31]
	v_mfma_i32_16x16x64_i8 v[36:39], v[144:147], v[176:179], 0
	v_mfma_i32_16x16x64_i8 v[36:39], v[140:143], v[172:175], v[36:39]
	v_mfma_i32_16x16x64_i8 v[24:27], v[140:143], v[204:207], 0
	v_mfma_i32_16x16x64_i8 v[24:27], v[144:147], v[208:211], v[24:27]
	v_mfma_i32_16x16x64_i8 v[8:11], v[144:147], v[220:223], 0
	v_mfma_i32_16x16x64_i8 v[8:11], v[140:143], v[212:215], v[8:11]
	v_mfma_i32_16x16x64_i8 v[4:7], v[156:159], v[212:215], 0
	v_mfma_i32_16x16x64_i8 v[4:7], v[160:163], v[220:223], v[4:7]
	v_mfma_i32_16x16x64_i8 v[20:23], v[160:163], v[208:211], 0
	v_mfma_i32_16x16x64_i8 v[20:23], v[156:159], v[204:207], v[20:23]
	v_mfma_i32_16x16x64_i8 v[40:43], v[156:159], v[172:175], 0
	v_mfma_i32_16x16x64_i8 v[40:43], v[160:163], v[176:179], v[40:43]
	v_mfma_i32_16x16x64_i8 v[32:35], v[160:163], v[168:171], 0
	v_mfma_i32_16x16x64_i8 v[32:35], v[156:159], v[164:167], v[32:35]
	s_setprio 0
	s_barrier
	s_mov_b32 m0, s65
	s_nop 0
	global_load_lds_dwordx4 v[226:227], off
	s_mov_b32 m0, s67
	s_nop 0
	global_load_lds_dwordx4 v[228:229], off
	s_add_i32 s87, 0, 0x18000
	s_add_i32 s96, 0, 0x1c000
	v_add_u32_e32 v72, s87, v217
	v_add_u32_e32 v160, s96, v217
	ds_read_b128 v[52:55], v72
	ds_read_b128 v[56:59], v72 offset:1024
	ds_read_b128 v[68:71], v72 offset:2048
	ds_read_b128 v[72:75], v72 offset:3072
	ds_read_b128 v[140:143], v160
	ds_read_b128 v[144:147], v160 offset:1024
	ds_read_b128 v[156:159], v160 offset:2048
	ds_read_b128 v[160:163], v160 offset:3072
	s_add_u32 s60, s60, 0x80000
	s_addc_u32 s61, s61, 0
	s_mov_b32 m0, s72
	v_lshl_add_u64 v[240:241], s[60:61], 0, v[180:181]
	ds_read_b128 v[164:167], v219 offset:32768
	ds_read_b128 v[168:171], v219 offset:33792
	ds_read_b128 v[172:175], v219 offset:34816
	ds_read_b128 v[176:179], v219 offset:35840
	ds_read_b128 v[204:207], v219 offset:36864
	ds_read_b128 v[208:211], v219 offset:37888
	ds_read_b128 v[212:215], v219 offset:38912
	ds_read_b128 v[220:223], v219 offset:39936
	global_load_lds_dwordx4 v[240:241], off
	v_lshl_add_u64 v[240:241], s[60:61], 0, v[182:183]
	s_mov_b32 m0, s73
	s_nop 0
	global_load_lds_dwordx4 v[240:241], off
	s_waitcnt vmcnt(8)
	s_waitcnt lgkmcnt(0)
	s_barrier
	s_setprio 1
	s_waitcnt lgkmcnt(0)
	v_mfma_i32_16x16x64_i8 v[152:155], v[52:55], v[164:167], v[152:155]
	v_mfma_i32_16x16x64_i8 v[152:155], v[56:59], v[168:171], v[152:155]
	v_mfma_i32_16x16x64_i8 v[128:131], v[56:59], v[176:179], v[128:131]
	v_mfma_i32_16x16x64_i8 v[128:131], v[52:55], v[172:175], v[128:131]
	v_mfma_i32_16x16x64_i8 v[112:115], v[52:55], v[204:207], v[112:115]
	v_mfma_i32_16x16x64_i8 v[112:115], v[56:59], v[208:211], v[112:115]
	v_mfma_i32_16x16x64_i8 v[96:99], v[56:59], v[220:223], v[96:99]
	v_mfma_i32_16x16x64_i8 v[96:99], v[52:55], v[212:215], v[96:99]
	v_mfma_i32_16x16x64_i8 v[92:95], v[68:71], v[212:215], v[92:95]
	v_mfma_i32_16x16x64_i8 v[92:95], v[72:75], v[220:223], v[92:95]
	v_mfma_i32_16x16x64_i8 v[108:111], v[72:75], v[208:211], v[108:111]
	v_mfma_i32_16x16x64_i8 v[108:111], v[68:71], v[204:207], v[108:111]
	v_mfma_i32_16x16x64_i8 v[124:127], v[68:71], v[172:175], v[124:127]
	v_mfma_i32_16x16x64_i8 v[124:127], v[72:75], v[176:179], v[124:127]
	v_mfma_i32_16x16x64_i8 v[148:151], v[72:75], v[168:171], v[148:151]
	v_mfma_i32_16x16x64_i8 v[148:151], v[68:71], v[164:167], v[148:151]
	v_mfma_i32_16x16x64_i8 v[136:139], v[140:143], v[164:167], v[136:139]
	v_mfma_i32_16x16x64_i8 v[136:139], v[144:147], v[168:171], v[136:139]
	v_mfma_i32_16x16x64_i8 v[120:123], v[144:147], v[176:179], v[120:123]
	v_mfma_i32_16x16x64_i8 v[120:123], v[140:143], v[172:175], v[120:123]
	v_mfma_i32_16x16x64_i8 v[104:107], v[140:143], v[204:207], v[104:107]
	v_mfma_i32_16x16x64_i8 v[104:107], v[144:147], v[208:211], v[104:107]
	v_mfma_i32_16x16x64_i8 v[88:91], v[144:147], v[220:223], v[88:91]
	v_mfma_i32_16x16x64_i8 v[88:91], v[140:143], v[212:215], v[88:91]
	v_mfma_i32_16x16x64_i8 v[84:87], v[156:159], v[212:215], v[84:87]
	v_mfma_i32_16x16x64_i8 v[84:87], v[160:163], v[220:223], v[84:87]
	v_mfma_i32_16x16x64_i8 v[100:103], v[160:163], v[208:211], v[100:103]
	v_mfma_i32_16x16x64_i8 v[100:103], v[156:159], v[204:207], v[100:103]
	v_mfma_i32_16x16x64_i8 v[116:119], v[156:159], v[172:175], v[116:119]
	v_mfma_i32_16x16x64_i8 v[116:119], v[160:163], v[176:179], v[116:119]
	v_mfma_i32_16x16x64_i8 v[132:135], v[160:163], v[168:171], v[132:135]
	v_mfma_i32_16x16x64_i8 v[132:135], v[156:159], v[164:167], v[132:135]
	s_setprio 0
	s_barrier
	s_add_i32 s60, s87, s46
	v_lshl_add_u64 v[190:191], v[190:191], 0, s[84:85]
	s_mov_b32 m0, s60
	ds_read_b128 v[164:167], v219 offset:49152
	ds_read_b128 v[168:171], v219 offset:50176
	ds_read_b128 v[172:175], v219 offset:51200
	ds_read_b128 v[176:179], v219 offset:52224
	ds_read_b128 v[204:207], v219 offset:53248
	ds_read_b128 v[208:211], v219 offset:54272
	ds_read_b128 v[212:215], v219 offset:55296
	ds_read_b128 v[220:223], v219 offset:56320
	global_load_lds_dwordx4 v[190:191], off
	s_add_i32 m0, s60, 0x2000
	s_add_u32 s58, s58, 0x80080
	v_lshl_add_u64 v[190:191], v[224:225], 0, s[84:85]
	s_addc_u32 s59, s59, 0
	s_add_i32 s60, s96, s46
	global_load_lds_dwordx4 v[190:191], off
	v_lshl_add_u64 v[190:191], s[58:59], 0, v[2:3]
	s_mov_b32 m0, s60
	s_nop 0
	global_load_lds_dwordx4 v[190:191], off
	v_lshl_add_u64 v[190:191], s[58:59], 0, v[184:185]
	s_add_i32 m0, s60, 0x2000
	s_nop 0
	global_load_lds_dwordx4 v[190:191], off
	s_cmp_eq_u32 s86, 28
	s_cbranch_scc0 .Ldefer_1843_peel
	v_lshl_add_u64 v[190:191], v[226:227], 0, s[84:85]
	s_mov_b32 m0, s28
	s_nop 0
	global_load_lds_dwordx4 v[190:191], off
	v_lshl_add_u64 v[190:191], v[228:229], 0, s[84:85]
	s_mov_b32 m0, s77
	s_nop 0
	global_load_lds_dwordx4 v[190:191], off
; #define PG8_STAGE(bufoff, gbase, voff) do { _Pragma("unroll") for (int _i = 0; _i < 2; ++_i) \
;         __builtin_amdgcn_global_load_lds((const unsigned*)((const char*)(gbase) + (voff)[_i]), (PG8_LAS unsigned*)(lds + (bufoff) + ldsw + _i * 8192), 16, 0, 0); } while (0)
; #define PG8_LDA(dst, b, h) do { _Pragma("unroll") for (int m = 0; m < 4; ++m) _Pragma("unroll") for (int k = 0; k < 2; ++k) dst[m][k] = *(const PG8_LAS bf16x8*)(lds + PG8_SA(b, h) + aoff + m * 2048 + k * 1024); } while (0)
; #define PG8_LDB(dst, b, h) do { _Pragma("unroll") for (int n = 0; n < 2; ++n) _Pragma("unroll") for (int k = 0; k < 2; ++k) dst[n][k] = *(const PG8_LAS bf16x8*)(lds + PG8_SB(b, h) + boff + n * 2048 + k * 1024); } while (0)
; #define PG8_WAIT_V(n) asm volatile("s_waitcnt vmcnt(" #n ")" ::: "memory")
; #define PG8_WAIT_L(n) asm volatile("s_waitcnt lgkmcnt(" #n ")" ::: "memory")
; #define PG8_BAR __builtin_amdgcn_s_barrier()
; #define PG8_SCHED __builtin_amdgcn_sched_barrier(0)
; template <class Epi, class Sched, bool ALIGN_EPI = false, bool SP2 = false, bool I8 = false>
; __device__ __forceinline__ void gemm_phase(PG8_LAS unsigned char* lds, const Gemm g, const Sched& S, const Epi& E) {
;     ...
;             if constexpr (SP2) {
;             PG8_LDB(B0, 0, 0); PG8_LDB(B1, 0, 1); PG8_SCHED; PG8_LDA(At, 0, 0); PG8_STAGE(PG8_SA(1, 1), a1 + hstep, voffA);
;             PG8_WAIT_V(8); PG8_WAIT_L(0); PG8_BAR; PG8_MMA(0, 0, At, B0); PG8_MMA(0, 1, At, B1); PG8_BAR; PG8_SCHED;
;             PG8_LDA(At, 0, 1); PG8_STAGE(PG8_SB(0, 0), b2, voffB); PG8_STAGE(PG8_SB(0, 1), b2 + hstep, voffB); PG8_STAGE(PG8_SA(0, 0), a2, voffA);
;             PG8_WAIT_V(8); PG8_WAIT_L(0); PG8_BAR; PG8_MMA(1, 0, At, B0); PG8_MMA(1, 1, At, B1); PG8_BAR; PG8_SCHED;
;             PG8_LDB(B0, 1, 0); PG8_LDB(B1, 1, 1); PG8_SCHED; PG8_LDA(At, 1, 0); PG8_STAGE(PG8_SA(0, 1), a2 + hstep, voffA);
;             PG8_WAIT_V(8); PG8_WAIT_L(0); PG8_BAR; PG8_MMA(0, 0, At, B0); PG8_MMA(0, 1, At, B1); PG8_BAR; PG8_SCHED;
;             PG8_LDA(At, 1, 1); PG8_STAGE(PG8_SB(1, 0), b3, voffB); PG8_STAGE(PG8_SB(1, 1), b3 + hstep, voffB); PG8_STAGE(PG8_SA(1, 0), a3, voffA);
;             PG8_WAIT_V(8); PG8_WAIT_L(0); PG8_BAR; PG8_MMA(1, 0, At, B0); PG8_MMA(1, 1, At, B1); PG8_BAR; PG8_SCHED;
.Ldefer_1843_peel:
	s_waitcnt vmcnt(6)
	s_waitcnt lgkmcnt(0)
	s_barrier
	s_setprio 1
	s_waitcnt lgkmcnt(0)
	v_mfma_i32_16x16x64_i8 v[80:83], v[52:55], v[164:167], v[80:83]
	v_mfma_i32_16x16x64_i8 v[80:83], v[56:59], v[168:171], v[80:83]
	v_mfma_i32_16x16x64_i8 v[64:67], v[56:59], v[176:179], v[64:67]
	v_mfma_i32_16x16x64_i8 v[64:67], v[52:55], v[172:175], v[64:67]
	v_mfma_i32_16x16x64_i8 v[48:51], v[52:55], v[204:207], v[48:51]
	v_mfma_i32_16x16x64_i8 v[48:51], v[56:59], v[208:211], v[48:51]
	v_mfma_i32_16x16x64_i8 v[16:19], v[56:59], v[220:223], v[16:19]
	v_mfma_i32_16x16x64_i8 v[16:19], v[52:55], v[212:215], v[16:19]
	v_mfma_i32_16x16x64_i8 v[12:15], v[68:71], v[212:215], v[12:15]
	v_mfma_i32_16x16x64_i8 v[12:15], v[72:75], v[220:223], v[12:15]
	v_mfma_i32_16x16x64_i8 v[44:47], v[72:75], v[208:211], v[44:47]
	v_mfma_i32_16x16x64_i8 v[44:47], v[68:71], v[204:207], v[44:47]
	v_mfma_i32_16x16x64_i8 v[60:63], v[68:71], v[172:175], v[60:63]
	v_mfma_i32_16x16x64_i8 v[60:63], v[72:75], v[176:179], v[60:63]
	v_mfma_i32_16x16x64_i8 v[76:79], v[72:75], v[168:171], v[76:79]
	v_mfma_i32_16x16x64_i8 v[76:79], v[68:71], v[164:167], v[76:79]
	v_mfma_i32_16x16x64_i8 v[28:31], v[140:143], v[164:167], v[28:31]
	v_mfma_i32_16x16x64_i8 v[72:75], v[144:147], v[168:171], v[28:31]
	v_mfma_i32_16x16x64_i8 v[28:31], v[144:147], v[176:179], v[36:39]
	v_mfma_i32_16x16x64_i8 v[56:59], v[140:143], v[172:175], v[28:31]
	v_mfma_i32_16x16x64_i8 v[24:27], v[140:143], v[204:207], v[24:27]
	v_mfma_i32_16x16x64_i8 v[24:27], v[144:147], v[208:211], v[24:27]
	v_mfma_i32_16x16x64_i8 v[8:11], v[144:147], v[220:223], v[8:11]
	v_mfma_i32_16x16x64_i8 v[8:11], v[140:143], v[212:215], v[8:11]
	v_mfma_i32_16x16x64_i8 v[4:7], v[156:159], v[212:215], v[4:7]
	v_mfma_i32_16x16x64_i8 v[4:7], v[160:163], v[220:223], v[4:7]
	v_mfma_i32_16x16x64_i8 v[20:23], v[160:163], v[208:211], v[20:23]
	v_mfma_i32_16x16x64_i8 v[20:23], v[156:159], v[204:207], v[20:23]
	v_mfma_i32_16x16x64_i8 v[28:31], v[156:159], v[172:175], v[40:43]
	v_mfma_i32_16x16x64_i8 v[52:55], v[160:163], v[176:179], v[28:31]
	v_mfma_i32_16x16x64_i8 v[28:31], v[160:163], v[168:171], v[32:35]
	v_mfma_i32_16x16x64_i8 v[68:71], v[156:159], v[164:167], v[28:31]
	s_setprio 0
	s_barrier
	s_add_i32 s86, s86, 2
	s_add_u32 s54, s54, 0x100
	s_addc_u32 s55, s55, 0
	s_add_u32 s45, s45, 0x100
	s_addc_u32 s49, s49, 0
	s_cmp_gt_u32 s86, 29
	s_cbranch_scc1 .Lkloop_exit_6
.LBB0_1843:
	s_add_u32 s58, s54, 0xfff80080
	s_addc_u32 s59, s55, -1
	s_add_i32 s87, 0, 0x10000
	s_cmp_eq_u32 s86, 28
	s_cselect_b32 s61, s11, s59
	s_cselect_b32 s60, s13, s58
	s_cselect_b32 s59, s34, s49
	s_cselect_b32 s58, s35, s45
	s_add_i32 vcc_lo, 0, 0x14000
	v_add_u32_e32 v40, s87, v217
	v_add_u32_e32 v160, vcc_lo, v217
	ds_read_b128 v[28:31], v40
	ds_read_b128 v[32:35], v40 offset:1024
	ds_read_b128 v[36:39], v40 offset:2048
	ds_read_b128 v[40:43], v40 offset:3072
	ds_read_b128 v[140:143], v160
	ds_read_b128 v[144:147], v160 offset:1024
	ds_read_b128 v[156:159], v160 offset:2048
	ds_read_b128 v[160:163], v160 offset:3072
	v_lshl_add_u64 v[190:191], v[226:227], 0, s[84:85]
	s_mov_b32 m0, s28
	s_nop 0
	global_load_lds_dwordx4 v[190:191], off
	v_lshl_add_u64 v[190:191], v[228:229], 0, s[84:85]
	s_mov_b32 m0, s77
	s_nop 0
	global_load_lds_dwordx4 v[190:191], off
	v_lshl_add_u64 v[190:191], s[54:55], 0, v[186:187]
	s_add_i32 m0, s65, 0xc000
	ds_read_b128 v[164:167], v219
	ds_read_b128 v[168:171], v219 offset:1024
	ds_read_b128 v[172:175], v219 offset:2048
	ds_read_b128 v[176:179], v219 offset:3072
	ds_read_b128 v[204:207], v219 offset:4096
	ds_read_b128 v[208:211], v219 offset:5120
	ds_read_b128 v[212:215], v219 offset:6144
	ds_read_b128 v[220:223], v219 offset:7168
	global_load_lds_dwordx4 v[190:191], off
	v_lshl_add_u64 v[190:191], s[54:55], 0, v[188:189]
	s_add_i32 m0, s65, 0xe000
	s_nop 0
	global_load_lds_dwordx4 v[190:191], off
	s_waitcnt vmcnt(8)
	s_waitcnt lgkmcnt(0)
	s_barrier
	s_setprio 1
	s_waitcnt lgkmcnt(0)
	v_mfma_i32_16x16x64_i8 v[152:155], v[28:31], v[164:167], v[152:155]
	v_mfma_i32_16x16x64_i8 v[152:155], v[32:35], v[168:171], v[152:155]
	v_mfma_i32_16x16x64_i8 v[128:131], v[32:35], v[176:179], v[128:131]
	v_mfma_i32_16x16x64_i8 v[128:131], v[28:31], v[172:175], v[128:131]
	v_mfma_i32_16x16x64_i8 v[112:115], v[28:31], v[204:207], v[112:115]
	v_mfma_i32_16x16x64_i8 v[112:115], v[32:35], v[208:211], v[112:115]
	v_mfma_i32_16x16x64_i8 v[96:99], v[32:35], v[220:223], v[96:99]
	v_mfma_i32_16x16x64_i8 v[96:99], v[28:31], v[212:215], v[96:99]
	v_mfma_i32_16x16x64_i8 v[92:95], v[36:39], v[212:215], v[92:95]
	v_mfma_i32_16x16x64_i8 v[92:95], v[40:43], v[220:223], v[92:95]
	v_mfma_i32_16x16x64_i8 v[108:111], v[40:43], v[208:211], v[108:111]
	v_mfma_i32_16x16x64_i8 v[108:111], v[36:39], v[204:207], v[108:111]
	v_mfma_i32_16x16x64_i8 v[124:127], v[36:39], v[172:175], v[124:127]
	v_mfma_i32_16x16x64_i8 v[124:127], v[40:43], v[176:179], v[124:127]
	v_mfma_i32_16x16x64_i8 v[148:151], v[40:43], v[168:171], v[148:151]
	v_mfma_i32_16x16x64_i8 v[148:151], v[36:39], v[164:167], v[148:151]
	v_mfma_i32_16x16x64_i8 v[136:139], v[140:143], v[164:167], v[136:139]
	v_mfma_i32_16x16x64_i8 v[136:139], v[144:147], v[168:171], v[136:139]
	v_mfma_i32_16x16x64_i8 v[120:123], v[144:147], v[176:179], v[120:123]
	v_mfma_i32_16x16x64_i8 v[120:123], v[140:143], v[172:175], v[120:123]
	v_mfma_i32_16x16x64_i8 v[104:107], v[140:143], v[204:207], v[104:107]
	v_mfma_i32_16x16x64_i8 v[104:107], v[144:147], v[208:211], v[104:107]
	v_mfma_i32_16x16x64_i8 v[88:91], v[144:147], v[220:223], v[88:91]
	v_mfma_i32_16x16x64_i8 v[88:91], v[140:143], v[212:215], v[88:91]
	v_mfma_i32_16x16x64_i8 v[84:87], v[156:159], v[212:215], v[84:87]
	v_mfma_i32_16x16x64_i8 v[84:87], v[160:163], v[220:223], v[84:87]
	v_mfma_i32_16x16x64_i8 v[100:103], v[160:163], v[208:211], v[100:103]
	v_mfma_i32_16x16x64_i8 v[100:103], v[156:159], v[204:207], v[100:103]
	v_mfma_i32_16x16x64_i8 v[116:119], v[156:159], v[172:175], v[116:119]
	v_mfma_i32_16x16x64_i8 v[116:119], v[160:163], v[176:179], v[116:119]
	v_mfma_i32_16x16x64_i8 v[132:135], v[160:163], v[168:171], v[132:135]
	v_mfma_i32_16x16x64_i8 v[132:135], v[156:159], v[164:167], v[132:135]
	s_setprio 0
	s_barrier
; #define PG8_STAGE(bufoff, gbase, voff) do { _Pragma("unroll") for (int _i = 0; _i < 2; ++_i) \
;         __builtin_amdgcn_global_load_lds((const unsigned*)((const char*)(gbase) + (voff)[_i]), (PG8_LAS unsigned*)(lds + (bufoff) + ldsw + _i * 8192), 16, 0, 0); } while (0)
; #define PG8_LDA(dst, b, h) do { _Pragma("unroll") for (int m = 0; m < 4; ++m) _Pragma("unroll") for (int k = 0; k < 2; ++k) dst[m][k] = *(const PG8_LAS bf16x8*)(lds + PG8_SA(b, h) + aoff + m * 2048 + k * 1024); } while (0)
; #define PG8_LDB(dst, b, h) do { _Pragma("unroll") for (int n = 0; n < 2; ++n) _Pragma("unroll") for (int k = 0; k < 2; ++k) dst[n][k] = *(const PG8_LAS bf16x8*)(lds + PG8_SB(b, h) + boff + n * 2048 + k * 1024); } while (0)
; #define PG8_WAIT_V(n) asm volatile("s_waitcnt vmcnt(" #n ")" ::: "memory")
; #define PG8_WAIT_L(n) asm volatile("s_waitcnt lgkmcnt(" #n ")" ::: "memory")
; #define PG8_BAR __builtin_amdgcn_s_barrier()
; #define PG8_SCHED __builtin_amdgcn_sched_barrier(0)
; template <class Epi, class Sched, bool ALIGN_EPI = false, bool SP2 = false, bool I8 = false>
; __device__ __forceinline__ void gemm_phase(PG8_LAS unsigned char* lds, const Gemm g, const Sched& S, const Epi& E) {
;     ...
;             PG8_WAIT_V(8); PG8_WAIT_L(0); PG8_BAR; PG8_MMA(0, 0, At, B0); PG8_MMA(0, 1, At, B1); PG8_BAR; PG8_SCHED;
;             PG8_LDA(At, 0, 1); PG8_STAGE(PG8_SB(0, 0), b2, voffB); PG8_STAGE(PG8_SB(0, 1), b2 + hstep, voffB); PG8_STAGE(PG8_SA(0, 0), a2, voffA);
;             PG8_WAIT_V(8); PG8_WAIT_L(0); PG8_BAR; PG8_MMA(1, 0, At, B0); PG8_MMA(1, 1, At, B1); PG8_BAR; PG8_SCHED;
;             PG8_LDB(B0, 1, 0); PG8_LDB(B1, 1, 1); PG8_SCHED; PG8_LDA(At, 1, 0); PG8_STAGE(PG8_SA(0, 1), a2 + hstep, voffA);
;             PG8_WAIT_V(8); PG8_WAIT_L(0); PG8_BAR; PG8_MMA(0, 0, At, B0); PG8_MMA(0, 1, At, B1); PG8_BAR; PG8_SCHED;
	s_add_i32 s87, s87, s46
	v_lshl_add_u64 v[190:191], s[58:59], 0, v[2:3]
	s_mov_b32 m0, s87
	ds_read_b128 v[164:167], v219 offset:16384
	ds_read_b128 v[168:171], v219 offset:17408
	ds_read_b128 v[172:175], v219 offset:18432
	ds_read_b128 v[176:179], v219 offset:19456
	ds_read_b128 v[204:207], v219 offset:20480
	ds_read_b128 v[208:211], v219 offset:21504
	ds_read_b128 v[212:215], v219 offset:22528
	ds_read_b128 v[220:223], v219 offset:23552
	global_load_lds_dwordx4 v[190:191], off
	s_add_i32 m0, s87, 0x2000
	s_add_u32 s96, s58, 0x80000
	v_lshl_add_u64 v[224:225], s[58:59], 0, v[184:185]
	s_addc_u32 s97, s59, 0
	s_add_i32 s87, vcc_lo, s46
	global_load_lds_dwordx4 v[224:225], off
	v_lshl_add_u64 v[226:227], s[96:97], 0, v[2:3]
	s_mov_b32 m0, s87
	v_lshl_add_u64 v[228:229], s[60:61], 0, v[182:183]
	global_load_lds_dwordx4 v[226:227], off
	v_lshl_add_u64 v[226:227], s[96:97], 0, v[184:185]
	s_add_i32 m0, s87, 0x2000
	s_nop 0
	global_load_lds_dwordx4 v[226:227], off
	v_lshl_add_u64 v[226:227], s[60:61], 0, v[180:181]
	s_waitcnt vmcnt(6)
	s_waitcnt lgkmcnt(0)
	s_barrier
	s_setprio 1
	s_waitcnt lgkmcnt(0)
	v_mfma_i32_16x16x64_i8 v[80:83], v[28:31], v[164:167], v[80:83]
	v_mfma_i32_16x16x64_i8 v[80:83], v[32:35], v[168:171], v[80:83]
	v_mfma_i32_16x16x64_i8 v[64:67], v[32:35], v[176:179], v[64:67]
	v_mfma_i32_16x16x64_i8 v[64:67], v[28:31], v[172:175], v[64:67]
	v_mfma_i32_16x16x64_i8 v[48:51], v[28:31], v[204:207], v[48:51]
	v_mfma_i32_16x16x64_i8 v[48:51], v[32:35], v[208:211], v[48:51]
	v_mfma_i32_16x16x64_i8 v[16:19], v[32:35], v[220:223], v[16:19]
	v_mfma_i32_16x16x64_i8 v[16:19], v[28:31], v[212:215], v[16:19]
	v_mfma_i32_16x16x64_i8 v[12:15], v[36:39], v[212:215], v[12:15]
	v_mfma_i32_16x16x64_i8 v[12:15], v[40:43], v[220:223], v[12:15]
	v_mfma_i32_16x16x64_i8 v[44:47], v[40:43], v[208:211], v[44:47]
	v_mfma_i32_16x16x64_i8 v[44:47], v[36:39], v[204:207], v[44:47]
	v_mfma_i32_16x16x64_i8 v[60:63], v[36:39], v[172:175], v[60:63]
	v_mfma_i32_16x16x64_i8 v[60:63], v[40:43], v[176:179], v[60:63]
	v_mfma_i32_16x16x64_i8 v[76:79], v[40:43], v[168:171], v[76:79]
	v_mfma_i32_16x16x64_i8 v[76:79], v[36:39], v[164:167], v[76:79]
	v_mfma_i32_16x16x64_i8 v[28:31], v[140:143], v[164:167], v[72:75]
	v_mfma_i32_16x16x64_i8 v[28:31], v[144:147], v[168:171], v[28:31]
	v_mfma_i32_16x16x64_i8 v[36:39], v[144:147], v[176:179], v[56:59]
	v_mfma_i32_16x16x64_i8 v[36:39], v[140:143], v[172:175], v[36:39]
	v_mfma_i32_16x16x64_i8 v[24:27], v[140:143], v[204:207], v[24:27]
	v_mfma_i32_16x16x64_i8 v[24:27], v[144:147], v[208:211], v[24:27]
	v_mfma_i32_16x16x64_i8 v[8:11], v[144:147], v[220:223], v[8:11]
	v_mfma_i32_16x16x64_i8 v[8:11], v[140:143], v[212:215], v[8:11]
	v_mfma_i32_16x16x64_i8 v[4:7], v[156:159], v[212:215], v[4:7]
	v_mfma_i32_16x16x64_i8 v[4:7], v[160:163], v[220:223], v[4:7]
	v_mfma_i32_16x16x64_i8 v[20:23], v[160:163], v[208:211], v[20:23]
	v_mfma_i32_16x16x64_i8 v[20:23], v[156:159], v[204:207], v[20:23]
	v_mfma_i32_16x16x64_i8 v[40:43], v[156:159], v[172:175], v[52:55]
	v_mfma_i32_16x16x64_i8 v[40:43], v[160:163], v[176:179], v[40:43]
	v_mfma_i32_16x16x64_i8 v[32:35], v[160:163], v[168:171], v[68:71]
	v_mfma_i32_16x16x64_i8 v[32:35], v[156:159], v[164:167], v[32:35]
	s_setprio 0
	s_barrier
	s_mov_b32 m0, s65
	s_nop 0
	global_load_lds_dwordx4 v[226:227], off
	s_mov_b32 m0, s67
	s_nop 0
	global_load_lds_dwordx4 v[228:229], off
	s_add_i32 s87, 0, 0x18000
	s_add_i32 s96, 0, 0x1c000
	v_add_u32_e32 v72, s87, v217
	v_add_u32_e32 v160, s96, v217
	ds_read_b128 v[52:55], v72
	ds_read_b128 v[56:59], v72 offset:1024
	ds_read_b128 v[68:71], v72 offset:2048
	ds_read_b128 v[72:75], v72 offset:3072
	ds_read_b128 v[140:143], v160
	ds_read_b128 v[144:147], v160 offset:1024
	ds_read_b128 v[156:159], v160 offset:2048
	ds_read_b128 v[160:163], v160 offset:3072
	s_add_u32 s60, s60, 0x80000
	s_addc_u32 s61, s61, 0
	s_mov_b32 m0, s72
	v_lshl_add_u64 v[240:241], s[60:61], 0, v[180:181]
	ds_read_b128 v[164:167], v219 offset:32768
	ds_read_b128 v[168:171], v219 offset:33792
	ds_read_b128 v[172:175], v219 offset:34816
	ds_read_b128 v[176:179], v219 offset:35840
	ds_read_b128 v[204:207], v219 offset:36864
	ds_read_b128 v[208:211], v219 offset:37888
	ds_read_b128 v[212:215], v219 offset:38912
	ds_read_b128 v[220:223], v219 offset:39936
	global_load_lds_dwordx4 v[240:241], off
	v_lshl_add_u64 v[240:241], s[60:61], 0, v[182:183]
	s_mov_b32 m0, s73
	s_nop 0
	global_load_lds_dwordx4 v[240:241], off
	s_waitcnt vmcnt(8)
	s_waitcnt lgkmcnt(0)
	s_barrier
; #define PG8_STAGE(bufoff, gbase, voff) do { _Pragma("unroll") for (int _i = 0; _i < 2; ++_i) \
;         __builtin_amdgcn_global_load_lds((const unsigned*)((const char*)(gbase) + (voff)[_i]), (PG8_LAS unsigned*)(lds + (bufoff) + ldsw + _i * 8192), 16, 0, 0); } while (0)
; #define PG8_LDA(dst, b, h) do { _Pragma("unroll") for (int m = 0; m < 4; ++m) _Pragma("unroll") for (int k = 0; k < 2; ++k) dst[m][k] = *(const PG8_LAS bf16x8*)(lds + PG8_SA(b, h) + aoff + m * 2048 + k * 1024); } while (0)
; #define PG8_WAIT_V(n) asm volatile("s_waitcnt vmcnt(" #n ")" ::: "memory")
; #define PG8_WAIT_L(n) asm volatile("s_waitcnt lgkmcnt(" #n ")" ::: "memory")
; #define PG8_BAR __builtin_amdgcn_s_barrier()
; #define PG8_SCHED __builtin_amdgcn_sched_barrier(0)
; template <class Epi, class Sched, bool ALIGN_EPI = false, bool SP2 = false, bool I8 = false>
; __device__ __forceinline__ void gemm_phase(PG8_LAS unsigned char* lds, const Gemm g, const Sched& S, const Epi& E) {
;     ...
;             PG8_WAIT_V(8); PG8_WAIT_L(0); PG8_BAR; PG8_MMA(0, 0, At, B0); PG8_MMA(0, 1, At, B1); PG8_BAR; PG8_SCHED;
;             PG8_LDA(At, 1, 1); PG8_STAGE(PG8_SB(1, 0), b3, voffB); PG8_STAGE(PG8_SB(1, 1), b3 + hstep, voffB); PG8_STAGE(PG8_SA(1, 0), a3, voffA);
;             PG8_WAIT_V(8); PG8_WAIT_L(0); PG8_BAR; PG8_MMA(1, 0, At, B0); PG8_MMA(1, 1, At, B1); PG8_BAR; PG8_SCHED;
	s_setprio 1
	s_waitcnt lgkmcnt(0)
	v_mfma_i32_16x16x64_i8 v[152:155], v[52:55], v[164:167], v[152:155]
	v_mfma_i32_16x16x64_i8 v[152:155], v[56:59], v[168:171], v[152:155]
	v_mfma_i32_16x16x64_i8 v[128:131], v[56:59], v[176:179], v[128:131]
	v_mfma_i32_16x16x64_i8 v[128:131], v[52:55], v[172:175], v[128:131]
	v_mfma_i32_16x16x64_i8 v[112:115], v[52:55], v[204:207], v[112:115]
	v_mfma_i32_16x16x64_i8 v[112:115], v[56:59], v[208:211], v[112:115]
	v_mfma_i32_16x16x64_i8 v[96:99], v[56:59], v[220:223], v[96:99]
	v_mfma_i32_16x16x64_i8 v[96:99], v[52:55], v[212:215], v[96:99]
	v_mfma_i32_16x16x64_i8 v[92:95], v[68:71], v[212:215], v[92:95]
	v_mfma_i32_16x16x64_i8 v[92:95], v[72:75], v[220:223], v[92:95]
	v_mfma_i32_16x16x64_i8 v[108:111], v[72:75], v[208:211], v[108:111]
	v_mfma_i32_16x16x64_i8 v[108:111], v[68:71], v[204:207], v[108:111]
	v_mfma_i32_16x16x64_i8 v[124:127], v[68:71], v[172:175], v[124:127]
	v_mfma_i32_16x16x64_i8 v[124:127], v[72:75], v[176:179], v[124:127]
	v_mfma_i32_16x16x64_i8 v[148:151], v[72:75], v[168:171], v[148:151]
	v_mfma_i32_16x16x64_i8 v[148:151], v[68:71], v[164:167], v[148:151]
	v_mfma_i32_16x16x64_i8 v[136:139], v[140:143], v[164:167], v[136:139]
	v_mfma_i32_16x16x64_i8 v[136:139], v[144:147], v[168:171], v[136:139]
	v_mfma_i32_16x16x64_i8 v[120:123], v[144:147], v[176:179], v[120:123]
	v_mfma_i32_16x16x64_i8 v[120:123], v[140:143], v[172:175], v[120:123]
	v_mfma_i32_16x16x64_i8 v[104:107], v[140:143], v[204:207], v[104:107]
	v_mfma_i32_16x16x64_i8 v[104:107], v[144:147], v[208:211], v[104:107]
	v_mfma_i32_16x16x64_i8 v[88:91], v[144:147], v[220:223], v[88:91]
	v_mfma_i32_16x16x64_i8 v[88:91], v[140:143], v[212:215], v[88:91]
	v_mfma_i32_16x16x64_i8 v[84:87], v[156:159], v[212:215], v[84:87]
	v_mfma_i32_16x16x64_i8 v[84:87], v[160:163], v[220:223], v[84:87]
	v_mfma_i32_16x16x64_i8 v[100:103], v[160:163], v[208:211], v[100:103]
	v_mfma_i32_16x16x64_i8 v[100:103], v[156:159], v[204:207], v[100:103]
	v_mfma_i32_16x16x64_i8 v[116:119], v[156:159], v[172:175], v[116:119]
	v_mfma_i32_16x16x64_i8 v[116:119], v[160:163], v[176:179], v[116:119]
	v_mfma_i32_16x16x64_i8 v[132:135], v[160:163], v[168:171], v[132:135]
	v_mfma_i32_16x16x64_i8 v[132:135], v[156:159], v[164:167], v[132:135]
	s_setprio 0
	s_barrier
	s_add_i32 s60, s87, s46
	v_lshl_add_u64 v[190:191], v[190:191], 0, s[84:85]
	s_mov_b32 m0, s60
	ds_read_b128 v[164:167], v219 offset:49152
	ds_read_b128 v[168:171], v219 offset:50176
	ds_read_b128 v[172:175], v219 offset:51200
	ds_read_b128 v[176:179], v219 offset:52224
	ds_read_b128 v[204:207], v219 offset:53248
	ds_read_b128 v[208:211], v219 offset:54272
	ds_read_b128 v[212:215], v219 offset:55296
	ds_read_b128 v[220:223], v219 offset:56320
	global_load_lds_dwordx4 v[190:191], off
	s_add_i32 m0, s60, 0x2000
	s_add_u32 s58, s58, 0x80080
	v_lshl_add_u64 v[190:191], v[224:225], 0, s[84:85]
	s_addc_u32 s59, s59, 0
	s_add_i32 s60, s96, s46
	global_load_lds_dwordx4 v[190:191], off
	v_lshl_add_u64 v[190:191], s[58:59], 0, v[2:3]
	s_mov_b32 m0, s60
	s_nop 0
	global_load_lds_dwordx4 v[190:191], off
	v_lshl_add_u64 v[190:191], s[58:59], 0, v[184:185]
	s_add_i32 m0, s60, 0x2000
	s_nop 0
	global_load_lds_dwordx4 v[190:191], off
	s_cmp_eq_u32 s86, 28
	s_cbranch_scc0 .Ldefer_1843_body
	v_lshl_add_u64 v[190:191], v[226:227], 0, s[84:85]
	s_mov_b32 m0, s28
	s_nop 0
	global_load_lds_dwordx4 v[190:191], off
	v_lshl_add_u64 v[190:191], v[228:229], 0, s[84:85]
	s_mov_b32 m0, s77
	s_nop 0
	global_load_lds_dwordx4 v[190:191], off
.Ldefer_1843_body:
	s_waitcnt vmcnt(6)
	s_waitcnt lgkmcnt(0)
	s_barrier
	s_setprio 1
	s_waitcnt lgkmcnt(0)
	v_mfma_i32_16x16x64_i8 v[80:83], v[52:55], v[164:167], v[80:83]
	v_mfma_i32_16x16x64_i8 v[80:83], v[56:59], v[168:171], v[80:83]
	v_mfma_i32_16x16x64_i8 v[64:67], v[56:59], v[176:179], v[64:67]
	v_mfma_i32_16x16x64_i8 v[64:67], v[52:55], v[172:175], v[64:67]
	v_mfma_i32_16x16x64_i8 v[48:51], v[52:55], v[204:207], v[48:51]
	v_mfma_i32_16x16x64_i8 v[48:51], v[56:59], v[208:211], v[48:51]
	v_mfma_i32_16x16x64_i8 v[16:19], v[56:59], v[220:223], v[16:19]
	v_mfma_i32_16x16x64_i8 v[16:19], v[52:55], v[212:215], v[16:19]
	v_mfma_i32_16x16x64_i8 v[12:15], v[68:71], v[212:215], v[12:15]
	v_mfma_i32_16x16x64_i8 v[12:15], v[72:75], v[220:223], v[12:15]
	v_mfma_i32_16x16x64_i8 v[44:47], v[72:75], v[208:211], v[44:47]
	v_mfma_i32_16x16x64_i8 v[44:47], v[68:71], v[204:207], v[44:47]
	v_mfma_i32_16x16x64_i8 v[60:63], v[68:71], v[172:175], v[60:63]
	v_mfma_i32_16x16x64_i8 v[60:63], v[72:75], v[176:179], v[60:63]
	v_mfma_i32_16x16x64_i8 v[76:79], v[72:75], v[168:171], v[76:79]
	v_mfma_i32_16x16x64_i8 v[76:79], v[68:71], v[164:167], v[76:79]
	v_mfma_i32_16x16x64_i8 v[28:31], v[140:143], v[164:167], v[28:31]
	v_mfma_i32_16x16x64_i8 v[72:75], v[144:147], v[168:171], v[28:31]
	v_mfma_i32_16x16x64_i8 v[28:31], v[144:147], v[176:179], v[36:39]
	v_mfma_i32_16x16x64_i8 v[56:59], v[140:143], v[172:175], v[28:31]
	v_mfma_i32_16x16x64_i8 v[24:27], v[140:143], v[204:207], v[24:27]
	v_mfma_i32_16x16x64_i8 v[24:27], v[144:147], v[208:211], v[24:27]
	v_mfma_i32_16x16x64_i8 v[8:11], v[144:147], v[220:223], v[8:11]
	v_mfma_i32_16x16x64_i8 v[8:11], v[140:143], v[212:215], v[8:11]
	v_mfma_i32_16x16x64_i8 v[4:7], v[156:159], v[212:215], v[4:7]
	v_mfma_i32_16x16x64_i8 v[4:7], v[160:163], v[220:223], v[4:7]
	v_mfma_i32_16x16x64_i8 v[20:23], v[160:163], v[208:211], v[20:23]
	v_mfma_i32_16x16x64_i8 v[20:23], v[156:159], v[204:207], v[20:23]
	v_mfma_i32_16x16x64_i8 v[28:31], v[156:159], v[172:175], v[40:43]
	v_mfma_i32_16x16x64_i8 v[52:55], v[160:163], v[176:179], v[28:31]
	v_mfma_i32_16x16x64_i8 v[28:31], v[160:163], v[168:171], v[32:35]
	v_mfma_i32_16x16x64_i8 v[68:71], v[156:159], v[164:167], v[28:31]
	s_setprio 0
	s_barrier
	s_add_i32 s86, s86, 2
	s_add_u32 s54, s54, 0x100
	s_addc_u32 s55, s55, 0
	s_add_u32 s45, s45, 0x100
	s_addc_u32 s49, s49, 0
	s_cmp_gt_u32 s86, 29
	s_cbranch_scc0 .LBB0_1843
